# unit boundary: lead half keeps priority 1 from the join barrier through its epilogue, unit header and first load segment (its header and loads then overlap the trail half's epilogue); priority reset a
# speedup vs baseline: 1.0091x; 1.0011x over previous
; __device__ __forceinline__ unsigned xb_ld(unsigned* p)              { return __hip_atomic_load(p, __ATOMIC_RELAXED, __HIP_MEMORY_SCOPE_AGENT); }
; __device__ __forceinline__ void xcd_barrier_complete(unsigned* bar, unsigned x, unsigned& nloc, unsigned& nx) {
;     const unsigned G = gridDim.x * gridDim.y * gridDim.z;
;     unsigned sum, cnt, mine, sp = 0u;
;     for (;;) {
;         sum = 0u; cnt = 0u; mine = 0u;
; #pragma unroll
;         for (unsigned j = 0; j < 16; ++j) { const unsigned c = xb_ld(&bar[XB_XCNT(j)]); sum += c; cnt += (c > 0u) ? 1u : 0u; mine = (j == x) ? c : mine; }
;         if (sum == G) break;
;         __builtin_amdgcn_s_sleep(1);
;         if ((++sp & 255u) == 0u) { if (xb_ld(&bar[XB_TMO])) break; if (sp > XB_SPIN_CAP) { atomicAdd(&bar[XB_TMO], 1u); break; } }
;     }
;     nloc = mine > 0u ? mine : 1u; nx = cnt > 0u ? cnt : 1u;
; }
; __device__ __forceinline__ void xcd_barrier(const XcdBarrier& b) {
;     asm volatile("s_waitcnt vmcnt(0)" ::: "memory");
;     __syncthreads();
;     if (threadIdx.x == 0) {
;         unsigned* bar = b.bar;
;         __builtin_amdgcn_s_waitcnt(0);
;         unsigned nloc = b.st[0], nx = b.st[1];
;         if (nloc == 0u) { xcd_barrier_complete(bar, b.x, nloc, nx); b.st[0] = nloc; b.st[1] = nx; }
.LBB0_72:
	s_or_b64 exec, exec, s[4:5]
	s_waitcnt vmcnt(0)
	s_setprio 0
	s_barrier
	s_and_saveexec_b64 s[4:5], s[94:95]
	s_xor_b64 s[4:5], exec, s[4:5]
	s_cbranch_execz .LBB0_125
	s_add_i32 s6, 0, 0x20160
	v_mov_b32_e32 v1, s6
	s_waitcnt vmcnt(0) expcnt(0) lgkmcnt(0)
	ds_read_b32 v3, v1
	s_add_i32 s6, 0, 0x20164
	v_mov_b32_e32 v1, s6
	ds_read_b32 v1, v1
	s_waitcnt lgkmcnt(1)
	v_cmp_ne_u32_e32 vcc, 0, v3
	s_cbranch_vccnz .LBB0_88
	v_readlane_b32 s6, v252, 0
	v_readlane_b32 s7, v252, 1
	s_load_dwordx2 s[10:11], s[6:7], 0x4
	s_add_u32 s6, s88, 0x4200
	s_addc_u32 s7, s89, 0
	s_add_u32 s8, s88, 0x4400
	s_addc_u32 s9, s89, 0
	s_waitcnt lgkmcnt(0)
	s_mul_i32 s3, s10, s3
	s_add_u32 s10, s88, 0x4500
	s_mul_i32 s3, s3, s11
	s_addc_u32 s11, s89, 0
	s_add_u32 s12, s88, 0x4600
	s_addc_u32 s13, s89, 0
	s_add_u32 s14, s88, 0x4700
	s_addc_u32 s15, s89, 0
	s_add_u32 s16, s88, 0x4800
	s_addc_u32 s17, s89, 0
	s_add_u32 s18, s88, 0x4900
	s_addc_u32 s19, s89, 0
	s_add_u32 s20, s88, 0x4a00
	s_addc_u32 s21, s89, 0
	s_add_u32 s22, s88, 0x4b00
	s_addc_u32 s23, s89, 0
	s_add_u32 s24, s88, 0x4c00
	s_addc_u32 s25, s89, 0
	s_add_u32 s26, s88, 0x4d00
	s_addc_u32 s27, s89, 0
	s_add_u32 s28, s88, 0x4e00
	s_addc_u32 s29, s89, 0
	s_add_u32 s30, s88, 0x4f00
	s_addc_u32 s31, s89, 0
	s_add_u32 s34, s88, 0x5000
	s_addc_u32 s35, s89, 0
	s_add_u32 s36, s88, 0x5100
	s_addc_u32 s37, s89, 0
	s_add_u32 s38, s88, 0x5200
	s_addc_u32 s39, s89, 0
	s_add_u32 s40, s88, 0x5300
	s_addc_u32 s41, s89, 0
	s_mov_b32 s33, 1
	v_mov_b32_e32 v17, 0
	s_branch .LBB0_76

; __device__ __forceinline__ unsigned xb_ld(unsigned* p)              { return __hip_atomic_load(p, __ATOMIC_RELAXED, __HIP_MEMORY_SCOPE_AGENT); }
; __device__ __forceinline__ void xcd_barrier_complete(unsigned* bar, unsigned x, unsigned& nloc, unsigned& nx) {
;     const unsigned G = gridDim.x * gridDim.y * gridDim.z;
;     unsigned sum, cnt, mine, sp = 0u;
;     for (;;) {
;         sum = 0u; cnt = 0u; mine = 0u;
; #pragma unroll
;         for (unsigned j = 0; j < 16; ++j) { const unsigned c = xb_ld(&bar[XB_XCNT(j)]); sum += c; cnt += (c > 0u) ? 1u : 0u; mine = (j == x) ? c : mine; }
;         if (sum == G) break;
;         __builtin_amdgcn_s_sleep(1);
;         if ((++sp & 255u) == 0u) { if (xb_ld(&bar[XB_TMO])) break; if (sp > XB_SPIN_CAP) { atomicAdd(&bar[XB_TMO], 1u); break; } }
;     }
;     nloc = mine > 0u ? mine : 1u; nx = cnt > 0u ? cnt : 1u;
; }
; __device__ __forceinline__ void xcd_barrier(const XcdBarrier& b) {
;     asm volatile("s_waitcnt vmcnt(0)" ::: "memory");
;     __syncthreads();
;     if (threadIdx.x == 0) {
;         unsigned* bar = b.bar;
;         __builtin_amdgcn_s_waitcnt(0);
;         unsigned nloc = b.st[0], nx = b.st[1];
;         if (nloc == 0u) { xcd_barrier_complete(bar, b.x, nloc, nx); b.st[0] = nloc; b.st[1] = nx; }
.LBB0_155:
	s_waitcnt vmcnt(0)
	s_setprio 0
	s_barrier
	s_and_saveexec_b64 s[2:3], s[94:95]
	v_readlane_b32 s58, v254, 35
	s_xor_b64 s[30:31], exec, s[2:3]
	v_readlane_b32 s59, v254, 36
	s_movk_i32 s57, 0x2b00
	s_mov_b32 s56, 0x100000
	s_mov_b32 s62, 0xff61b1e6
	s_mov_b32 s63, 0x41000000
	s_cbranch_execz .LBB0_208
	v_readlane_b32 s2, v254, 23
	s_waitcnt vmcnt(0) expcnt(0) lgkmcnt(0)
	s_nop 0
	v_mov_b32_e32 v2, s2
	ds_read_b32 v4, v2
	v_readlane_b32 s2, v254, 24
	s_waitcnt lgkmcnt(0)
	v_cmp_ne_u32_e32 vcc, 0, v4
	v_mov_b32_e32 v2, s2
	ds_read_b32 v2, v2
	s_cbranch_vccnz .LBB0_171
	s_load_dwordx2 s[2:3], s[88:89], 0x4
	s_waitcnt lgkmcnt(0)
	s_mul_i32 s1, s2, s1
	s_mul_i32 s1, s1, s3
	s_mov_b32 s2, 1
	s_branch .LBB0_159

; #define PG8_STAGEX(rs, bufoff, soff, voff) do { _Pragma("unroll") for (int _i = 0; _i < 2; ++_i) \
;         __builtin_amdgcn_raw_ptr_buffer_load_lds(rs, (LAS unsigned*)(lds + (bufoff) + ldsw + _i * 8192), 16, (voff)[_i], (soff), 0, 0); } while (0)
; #define PG8_LDA(dst, b, h) do { _Pragma("unroll") for (int m = 0; m < 4; ++m) _Pragma("unroll") for (int k = 0; k < 2; ++k) dst[m][k] = *(const LAS bf16x8*)(lds + PG8_SA(b, h) + aoff + m * 2048 + k * 1024); } while (0)
; #define PG8_LDB(dst, b, h) do { _Pragma("unroll") for (int n = 0; n < 2; ++n) _Pragma("unroll") for (int k = 0; k < 2; ++k) dst[n][k] = *(const LAS bf16x8*)(lds + PG8_SB(b, h) + boff + n * 2048 + k * 1024); } while (0)
; #define PG8_WAIT_V(n) asm volatile("s_waitcnt vmcnt(" #n ")" ::: "memory")
; #define PG8_WAIT_L(n) asm volatile("s_waitcnt lgkmcnt(" #n ")" ::: "memory")
; #define PG8_BAR __builtin_amdgcn_s_barrier()
; #define PG8_SCHED __builtin_amdgcn_sched_barrier(0)
;     ...
;             PG8_LDB(B0, 0, 0); PG8_LDB(B1, 0, 1); PG8_SCHED; PG8_LDA(At, 0, 0); PG8_STAGEX(rsA, PG8_SA(1, 1), a1 + hstepA, voffA);
;             PG8_WAIT_V(8); PG8_WAIT_L(0); PG8_BAR; PG8_MMA(0, 0, At, B0); PG8_MMA(0, 1, At, B1); PG8_BAR; PG8_SCHED;
;             PG8_LDA(At, 0, 1); PG8_STAGEX(rsB, PG8_SB(0, 0), b2, voffB); PG8_STAGEX(rsB, PG8_SB(0, 1), b2 + hstepB, voffB); PG8_STAGEX(rsA, PG8_SA(0, 0), a2, voffA);
;             PG8_WAIT_V(8); PG8_WAIT_L(0); PG8_BAR; PG8_MMA(1, 0, At, B0); PG8_MMA(1, 1, At, B1); PG8_BAR; PG8_SCHED;
.LBB0_223:
	v_add_u32_e32 v102, 0x10000, v172
	v_add_u32_e32 v146, 0x14000, v172
	ds_read_b128 v[82:85], v102
	ds_read_b128 v[86:89], v102 offset:1024
	ds_read_b128 v[98:101], v102 offset:2048
	ds_read_b128 v[102:105], v102 offset:3072
	ds_read_b128 v[150:153], v146
	ds_read_b128 v[154:157], v146 offset:1024
	ds_read_b128 v[182:185], v146 offset:2048
	ds_read_b128 v[186:189], v146 offset:3072
	s_add_i32 s42, s50, 0xfff80080
	s_cmp_eq_u32 s52, 28
	s_cselect_b32 s55, s30, s42
	s_cselect_b32 s54, s31, s51
	s_or_b32 s53, s55, 0x80
	s_mov_b32 m0, s22
	ds_read_b128 v[190:193], v173
	ds_read_b128 v[194:197], v173 offset:1024
	ds_read_b128 v[198:201], v173 offset:2048
	ds_read_b128 v[202:205], v173 offset:3072
	ds_read_b128 v[206:209], v173 offset:4096
	ds_read_b128 v[210:213], v173 offset:5120
	ds_read_b128 v[214:217], v173 offset:6144
	ds_read_b128 v[218:221], v173 offset:7168
	buffer_load_dwordx4 v159, s[76:79], s50 offen lds
	s_mov_b32 m0, s23
	s_nop 0
	buffer_load_dwordx4 v163, s[76:79], s50 offen lds
	s_waitcnt vmcnt(8)
	s_waitcnt lgkmcnt(0)
	s_setprio 1
	s_barrier
	v_mfma_f32_16x16x32_bf16 v[142:145], v[82:85], v[190:193], v[142:145]
	v_mfma_f32_16x16x32_bf16 v[142:145], v[86:89], v[194:197], v[142:145]
	v_mfma_f32_16x16x32_bf16 v[134:137], v[102:105], v[194:197], v[134:137]
	v_mfma_f32_16x16x32_bf16 v[134:137], v[98:101], v[190:193], v[134:137]
	v_mfma_f32_16x16x32_bf16 v[118:121], v[98:101], v[198:201], v[118:121]
	v_mfma_f32_16x16x32_bf16 v[118:121], v[102:105], v[202:205], v[118:121]
	v_mfma_f32_16x16x32_bf16 v[126:129], v[86:89], v[202:205], v[126:129]
	v_mfma_f32_16x16x32_bf16 v[126:129], v[82:85], v[198:201], v[126:129]
	v_mfma_f32_16x16x32_bf16 v[110:113], v[82:85], v[206:209], v[110:113]
	v_mfma_f32_16x16x32_bf16 v[110:113], v[86:89], v[210:213], v[110:113]
	v_mfma_f32_16x16x32_bf16 v[94:97], v[102:105], v[210:213], v[94:97]
	v_mfma_f32_16x16x32_bf16 v[94:97], v[98:101], v[206:209], v[94:97]
	v_mfma_f32_16x16x32_bf16 v[70:73], v[98:101], v[214:217], v[70:73]
	v_mfma_f32_16x16x32_bf16 v[70:73], v[102:105], v[218:221], v[70:73]
	v_mfma_f32_16x16x32_bf16 v[78:81], v[86:89], v[218:221], v[78:81]
	v_mfma_f32_16x16x32_bf16 v[78:81], v[82:85], v[214:217], v[78:81]
	v_mfma_f32_16x16x32_bf16 v[138:141], v[150:153], v[190:193], v[138:141]
	v_mfma_f32_16x16x32_bf16 v[138:141], v[154:157], v[194:197], v[138:141]
	v_mfma_f32_16x16x32_bf16 v[130:133], v[186:189], v[194:197], v[130:133]
	v_mfma_f32_16x16x32_bf16 v[130:133], v[182:185], v[190:193], v[130:133]
	v_mfma_f32_16x16x32_bf16 v[114:117], v[182:185], v[198:201], v[114:117]
	v_mfma_f32_16x16x32_bf16 v[114:117], v[186:189], v[202:205], v[114:117]
	v_mfma_f32_16x16x32_bf16 v[122:125], v[154:157], v[202:205], v[122:125]
	v_mfma_f32_16x16x32_bf16 v[122:125], v[150:153], v[198:201], v[122:125]
	v_mfma_f32_16x16x32_bf16 v[106:109], v[150:153], v[206:209], v[106:109]
	v_mfma_f32_16x16x32_bf16 v[106:109], v[154:157], v[210:213], v[106:109]
	v_mfma_f32_16x16x32_bf16 v[90:93], v[186:189], v[210:213], v[90:93]
	v_mfma_f32_16x16x32_bf16 v[90:93], v[182:185], v[206:209], v[90:93]
	v_mfma_f32_16x16x32_bf16 v[66:69], v[182:185], v[214:217], v[66:69]
	v_mfma_f32_16x16x32_bf16 v[66:69], v[186:189], v[218:221], v[66:69]
	v_mfma_f32_16x16x32_bf16 v[74:77], v[154:157], v[218:221], v[74:77]
	v_mfma_f32_16x16x32_bf16 v[74:77], v[150:153], v[214:217], v[74:77]
	s_barrier
	s_setprio 0
	s_mov_b32 m0, s9
	s_mov_b32 s42, s78
	s_mov_b32 s43, s79
	ds_read_b128 v[190:193], v173 offset:16384
	ds_read_b128 v[194:197], v173 offset:17408
	ds_read_b128 v[198:201], v173 offset:18432
	ds_read_b128 v[202:205], v173 offset:19456
	ds_read_b128 v[206:209], v173 offset:20480
	ds_read_b128 v[210:213], v173 offset:21504
	ds_read_b128 v[214:217], v173 offset:22528
	ds_read_b128 v[218:221], v173 offset:23552
	buffer_load_dwordx4 v161, s[40:43], s54 offen lds
	s_mov_b32 m0, s10
	s_add_i32 s56, s54, 0x80000
	buffer_load_dwordx4 v165, s[40:43], s54 offen lds
	s_mov_b32 m0, s11
	s_nop 0
	buffer_load_dwordx4 v161, s[40:43], s56 offen lds
	s_mov_b32 m0, s12
	s_nop 0
	buffer_load_dwordx4 v165, s[40:43], s56 offen lds
	s_mov_b32 m0, s8
	s_nop 0
	buffer_load_dwordx4 v159, s[76:79], s55 offen lds
	s_mov_b32 m0, s13
	s_nop 0
	buffer_load_dwordx4 v163, s[76:79], s55 offen lds
	s_waitcnt vmcnt(8)
	s_waitcnt lgkmcnt(0)
	s_setprio 1
	s_barrier
	v_mfma_f32_16x16x32_bf16 v[62:65], v[82:85], v[190:193], v[62:65]
	v_mfma_f32_16x16x32_bf16 v[62:65], v[86:89], v[194:197], v[62:65]
	v_mfma_f32_16x16x32_bf16 v[54:57], v[102:105], v[194:197], v[54:57]
	v_mfma_f32_16x16x32_bf16 v[54:57], v[98:101], v[190:193], v[54:57]
	v_mfma_f32_16x16x32_bf16 v[38:41], v[98:101], v[198:201], v[38:41]
	v_mfma_f32_16x16x32_bf16 v[38:41], v[102:105], v[202:205], v[38:41]
	v_mfma_f32_16x16x32_bf16 v[46:49], v[86:89], v[202:205], v[46:49]
	v_mfma_f32_16x16x32_bf16 v[46:49], v[82:85], v[198:201], v[46:49]
	v_mfma_f32_16x16x32_bf16 v[30:33], v[82:85], v[206:209], v[30:33]
	v_mfma_f32_16x16x32_bf16 v[30:33], v[86:89], v[210:213], v[30:33]
	v_mfma_f32_16x16x32_bf16 v[22:25], v[102:105], v[210:213], v[22:25]
	v_mfma_f32_16x16x32_bf16 v[22:25], v[98:101], v[206:209], v[22:25]
	v_mfma_f32_16x16x32_bf16 v[6:9], v[98:101], v[214:217], v[6:9]
	v_mfma_f32_16x16x32_bf16 v[6:9], v[102:105], v[218:221], v[6:9]
	v_mfma_f32_16x16x32_bf16 v[14:17], v[86:89], v[218:221], v[14:17]
	v_mfma_f32_16x16x32_bf16 v[14:17], v[82:85], v[214:217], v[14:17]
	v_mfma_f32_16x16x32_bf16 v[58:61], v[150:153], v[190:193], v[58:61]
	v_mfma_f32_16x16x32_bf16 v[58:61], v[154:157], v[194:197], v[58:61]
	v_mfma_f32_16x16x32_bf16 v[50:53], v[186:189], v[194:197], v[50:53]
	v_mfma_f32_16x16x32_bf16 v[50:53], v[182:185], v[190:193], v[50:53]
	v_mfma_f32_16x16x32_bf16 v[34:37], v[182:185], v[198:201], v[34:37]
	v_mfma_f32_16x16x32_bf16 v[34:37], v[186:189], v[202:205], v[34:37]
	v_mfma_f32_16x16x32_bf16 v[42:45], v[154:157], v[202:205], v[42:45]
	v_mfma_f32_16x16x32_bf16 v[42:45], v[150:153], v[198:201], v[42:45]
	v_mfma_f32_16x16x32_bf16 v[26:29], v[150:153], v[206:209], v[26:29]
	v_mfma_f32_16x16x32_bf16 v[26:29], v[154:157], v[210:213], v[26:29]
	v_mfma_f32_16x16x32_bf16 v[18:21], v[186:189], v[210:213], v[18:21]
	v_mfma_f32_16x16x32_bf16 v[18:21], v[182:185], v[206:209], v[18:21]
	v_mfma_f32_16x16x32_bf16 v[2:5], v[182:185], v[214:217], v[2:5]
	v_mfma_f32_16x16x32_bf16 v[2:5], v[186:189], v[218:221], v[2:5]
	v_mfma_f32_16x16x32_bf16 v[10:13], v[154:157], v[218:221], v[10:13]
	v_mfma_f32_16x16x32_bf16 v[10:13], v[150:153], v[214:217], v[10:13]
	s_barrier
; #define PG8_STAGEX(rs, bufoff, soff, voff) do { _Pragma("unroll") for (int _i = 0; _i < 2; ++_i) \
;         __builtin_amdgcn_raw_ptr_buffer_load_lds(rs, (LAS unsigned*)(lds + (bufoff) + ldsw + _i * 8192), 16, (voff)[_i], (soff), 0, 0); } while (0)
; #define PG8_WAIT_V(n) asm volatile("s_waitcnt vmcnt(" #n ")" ::: "memory")
; #define PG8_WAIT_L(n) asm volatile("s_waitcnt lgkmcnt(" #n ")" ::: "memory")
; #define PG8_BAR __builtin_amdgcn_s_barrier()
;     ...
;             PG8_LDB(B0, 1, 0); PG8_LDB(B1, 1, 1); PG8_SCHED; PG8_LDA(At, 1, 0); PG8_STAGEX(rsA, PG8_SA(0, 1), a2 + hstepA, voffA);
;             PG8_WAIT_V(8); PG8_WAIT_L(0); PG8_BAR; PG8_MMA(0, 0, At, B0); PG8_MMA(0, 1, At, B1); PG8_BAR; PG8_SCHED;
;             PG8_LDA(At, 1, 1); PG8_STAGEX(rsB, PG8_SB(1, 0), b3, voffB); PG8_STAGEX(rsB, PG8_SB(1, 1), b3 + hstepB, voffB); PG8_STAGEX(rsA, PG8_SA(1, 0), a3, voffA);
;             PG8_WAIT_V(8); PG8_WAIT_L(0); PG8_BAR; PG8_MMA(1, 0, At, B0); PG8_MMA(1, 1, At, B1); PG8_BAR; PG8_SCHED;
;         }
;         } else {
;             const bool w0 = (QV == 2) || (wr == 0);
; #pragma nounroll
;             for (int t = 0; t < nt; t += 2) {
;                 const bool last = (t == nt - 2);
;                 const unsigned a1 = cA + (unsigned)(t + 1) * kstep;
;                 const unsigned a2 = last ? nA : cA + (unsigned)(t + 2) * kstep, b2 = last ? nB : cB + (unsigned)(t + 2) * kstep;
;                 const unsigned a3 = a2 + kstep, b3 = b2 + kstep;
;                 if (w0) { PG8_LDB(B0, 0, 0); PG8_LDB(B1, 0, 1); PG8_SCHED; PG8_LDA(At, 0, 0); }
;                 PG8_WAIT_L(0); PG8_BAR; if (w0) { PG8_MMA(0, 0, At, B0); PG8_MMA(0, 1, At, B1); } PG8_BAR; PG8_SCHED;
;                 PG8_STAGEX(rsB, PG8_SB(0, 0), b2, voffB); PG8_STAGEX(rsB, PG8_SB(0, 1), b2 + hstepB, voffB); PG8_STAGEX(rsA, PG8_SA(0, 0), a2, voffA);
;                 PG8_WAIT_V(6); PG8_BAR; PG8_BAR; PG8_SCHED;
;                 if (w0) { PG8_LDB(B0, 1, 0); PG8_LDB(B1, 1, 1); PG8_SCHED; PG8_LDA(At, 1, 0); }
;                 PG8_WAIT_L(0); PG8_BAR; if (w0) { PG8_MMA(0, 0, At, B0); PG8_MMA(0, 1, At, B1); } PG8_BAR; PG8_SCHED;
;                 PG8_STAGEX(rsB, PG8_SB(1, 0), b3, voffB); PG8_STAGEX(rsB, PG8_SB(1, 1), b3 + hstepB, voffB); PG8_STAGEX(rsA, PG8_SA(1, 0), a3, voffA);
;                 PG8_WAIT_V(6); PG8_BAR; PG8_BAR; PG8_SCHED;
;             }
;         }
;         if (wr == 0) PG8_BAR;
	s_setprio 0
	v_add_u32_e32 v102, 0x18000, v172
	v_add_u32_e32 v146, 0x1c000, v172
	ds_read_b128 v[82:85], v102
	ds_read_b128 v[86:89], v102 offset:1024
	ds_read_b128 v[98:101], v102 offset:2048
	ds_read_b128 v[102:105], v102 offset:3072
	ds_read_b128 v[150:153], v146
	ds_read_b128 v[154:157], v146 offset:1024
	ds_read_b128 v[182:185], v146 offset:2048
	ds_read_b128 v[186:189], v146 offset:3072
	s_add_i32 s55, s55, 0x80000
	s_mov_b32 m0, s14
	ds_read_b128 v[190:193], v173 offset:32768
	ds_read_b128 v[194:197], v173 offset:33792
	ds_read_b128 v[198:201], v173 offset:34816
	ds_read_b128 v[202:205], v173 offset:35840
	ds_read_b128 v[206:209], v173 offset:36864
	ds_read_b128 v[210:213], v173 offset:37888
	ds_read_b128 v[214:217], v173 offset:38912
	ds_read_b128 v[218:221], v173 offset:39936
	buffer_load_dwordx4 v159, s[76:79], s55 offen lds
	s_mov_b32 m0, s15
	s_nop 0
	buffer_load_dwordx4 v163, s[76:79], s55 offen lds
	s_waitcnt vmcnt(8)
	s_waitcnt lgkmcnt(0)
	s_setprio 1
	s_barrier
	v_mfma_f32_16x16x32_bf16 v[142:145], v[82:85], v[190:193], v[142:145]
	v_mfma_f32_16x16x32_bf16 v[142:145], v[86:89], v[194:197], v[142:145]
	v_mfma_f32_16x16x32_bf16 v[134:137], v[102:105], v[194:197], v[134:137]
	v_mfma_f32_16x16x32_bf16 v[134:137], v[98:101], v[190:193], v[134:137]
	v_mfma_f32_16x16x32_bf16 v[118:121], v[98:101], v[198:201], v[118:121]
	v_mfma_f32_16x16x32_bf16 v[118:121], v[102:105], v[202:205], v[118:121]
	v_mfma_f32_16x16x32_bf16 v[126:129], v[86:89], v[202:205], v[126:129]
	v_mfma_f32_16x16x32_bf16 v[126:129], v[82:85], v[198:201], v[126:129]
	v_mfma_f32_16x16x32_bf16 v[110:113], v[82:85], v[206:209], v[110:113]
	v_mfma_f32_16x16x32_bf16 v[110:113], v[86:89], v[210:213], v[110:113]
	v_mfma_f32_16x16x32_bf16 v[94:97], v[102:105], v[210:213], v[94:97]
	v_mfma_f32_16x16x32_bf16 v[94:97], v[98:101], v[206:209], v[94:97]
	v_mfma_f32_16x16x32_bf16 v[70:73], v[98:101], v[214:217], v[70:73]
	v_mfma_f32_16x16x32_bf16 v[70:73], v[102:105], v[218:221], v[70:73]
	v_mfma_f32_16x16x32_bf16 v[78:81], v[86:89], v[218:221], v[78:81]
	v_mfma_f32_16x16x32_bf16 v[78:81], v[82:85], v[214:217], v[78:81]
	v_mfma_f32_16x16x32_bf16 v[138:141], v[150:153], v[190:193], v[138:141]
	v_mfma_f32_16x16x32_bf16 v[138:141], v[154:157], v[194:197], v[138:141]
	v_mfma_f32_16x16x32_bf16 v[130:133], v[186:189], v[194:197], v[130:133]
	v_mfma_f32_16x16x32_bf16 v[130:133], v[182:185], v[190:193], v[130:133]
	v_mfma_f32_16x16x32_bf16 v[114:117], v[182:185], v[198:201], v[114:117]
	v_mfma_f32_16x16x32_bf16 v[114:117], v[186:189], v[202:205], v[114:117]
	v_mfma_f32_16x16x32_bf16 v[122:125], v[154:157], v[202:205], v[122:125]
	v_mfma_f32_16x16x32_bf16 v[122:125], v[150:153], v[198:201], v[122:125]
	v_mfma_f32_16x16x32_bf16 v[106:109], v[150:153], v[206:209], v[106:109]
	v_mfma_f32_16x16x32_bf16 v[106:109], v[154:157], v[210:213], v[106:109]
	v_mfma_f32_16x16x32_bf16 v[90:93], v[186:189], v[210:213], v[90:93]
	v_mfma_f32_16x16x32_bf16 v[90:93], v[182:185], v[206:209], v[90:93]
	v_mfma_f32_16x16x32_bf16 v[66:69], v[182:185], v[214:217], v[66:69]
	v_mfma_f32_16x16x32_bf16 v[66:69], v[186:189], v[218:221], v[66:69]
	v_mfma_f32_16x16x32_bf16 v[74:77], v[154:157], v[218:221], v[74:77]
	v_mfma_f32_16x16x32_bf16 v[74:77], v[150:153], v[214:217], v[74:77]
	s_barrier
	s_setprio 0
	s_mov_b32 m0, s16
	s_or_b32 s55, s54, 0x80
	ds_read_b128 v[190:193], v173 offset:49152
	ds_read_b128 v[194:197], v173 offset:50176
	ds_read_b128 v[198:201], v173 offset:51200
	ds_read_b128 v[202:205], v173 offset:52224
	ds_read_b128 v[206:209], v173 offset:53248
	ds_read_b128 v[210:213], v173 offset:54272
	ds_read_b128 v[214:217], v173 offset:55296
	ds_read_b128 v[218:221], v173 offset:56320
	buffer_load_dwordx4 v161, s[40:43], s55 offen lds
	s_mov_b32 m0, s17
	s_add_i32 s54, s54, 0x80080
	buffer_load_dwordx4 v165, s[40:43], s55 offen lds
	s_mov_b32 m0, s20
	s_nop 0
	buffer_load_dwordx4 v161, s[40:43], s54 offen lds
	s_mov_b32 m0, s21
	s_nop 0
	buffer_load_dwordx4 v165, s[40:43], s54 offen lds
	s_mov_b32 m0, s18
	s_nop 0
	buffer_load_dwordx4 v159, s[76:79], s53 offen lds
	s_mov_b32 m0, s19
	s_nop 0
	buffer_load_dwordx4 v163, s[76:79], s53 offen lds
	s_waitcnt vmcnt(8)
	s_waitcnt lgkmcnt(0)
	s_setprio 1
	s_barrier
	v_mfma_f32_16x16x32_bf16 v[62:65], v[82:85], v[190:193], v[62:65]
	v_mfma_f32_16x16x32_bf16 v[62:65], v[86:89], v[194:197], v[62:65]
	v_mfma_f32_16x16x32_bf16 v[54:57], v[102:105], v[194:197], v[54:57]
	v_mfma_f32_16x16x32_bf16 v[54:57], v[98:101], v[190:193], v[54:57]
	v_mfma_f32_16x16x32_bf16 v[38:41], v[98:101], v[198:201], v[38:41]
	v_mfma_f32_16x16x32_bf16 v[38:41], v[102:105], v[202:205], v[38:41]
	v_mfma_f32_16x16x32_bf16 v[46:49], v[86:89], v[202:205], v[46:49]
	v_mfma_f32_16x16x32_bf16 v[46:49], v[82:85], v[198:201], v[46:49]
	v_mfma_f32_16x16x32_bf16 v[30:33], v[82:85], v[206:209], v[30:33]
	v_mfma_f32_16x16x32_bf16 v[30:33], v[86:89], v[210:213], v[30:33]
	v_mfma_f32_16x16x32_bf16 v[22:25], v[102:105], v[210:213], v[22:25]
	v_mfma_f32_16x16x32_bf16 v[22:25], v[98:101], v[206:209], v[22:25]
	v_mfma_f32_16x16x32_bf16 v[6:9], v[98:101], v[214:217], v[6:9]
	v_mfma_f32_16x16x32_bf16 v[6:9], v[102:105], v[218:221], v[6:9]
	v_mfma_f32_16x16x32_bf16 v[14:17], v[86:89], v[218:221], v[14:17]
	v_mfma_f32_16x16x32_bf16 v[14:17], v[82:85], v[214:217], v[14:17]
	v_mfma_f32_16x16x32_bf16 v[58:61], v[150:153], v[190:193], v[58:61]
	v_mfma_f32_16x16x32_bf16 v[58:61], v[154:157], v[194:197], v[58:61]
	v_mfma_f32_16x16x32_bf16 v[50:53], v[186:189], v[194:197], v[50:53]
	v_mfma_f32_16x16x32_bf16 v[50:53], v[182:185], v[190:193], v[50:53]
	v_mfma_f32_16x16x32_bf16 v[34:37], v[182:185], v[198:201], v[34:37]
	v_mfma_f32_16x16x32_bf16 v[34:37], v[186:189], v[202:205], v[34:37]
	v_mfma_f32_16x16x32_bf16 v[42:45], v[154:157], v[202:205], v[42:45]
	v_mfma_f32_16x16x32_bf16 v[42:45], v[150:153], v[198:201], v[42:45]
	v_mfma_f32_16x16x32_bf16 v[26:29], v[150:153], v[206:209], v[26:29]
	v_mfma_f32_16x16x32_bf16 v[26:29], v[154:157], v[210:213], v[26:29]
	v_mfma_f32_16x16x32_bf16 v[18:21], v[186:189], v[210:213], v[18:21]
	v_mfma_f32_16x16x32_bf16 v[18:21], v[182:185], v[206:209], v[18:21]
	v_mfma_f32_16x16x32_bf16 v[2:5], v[182:185], v[214:217], v[2:5]
	v_mfma_f32_16x16x32_bf16 v[2:5], v[186:189], v[218:221], v[2:5]
	v_mfma_f32_16x16x32_bf16 v[10:13], v[154:157], v[218:221], v[10:13]
	v_mfma_f32_16x16x32_bf16 v[10:13], v[150:153], v[214:217], v[10:13]
	s_barrier
	s_setprio 0
	s_add_i32 s52, s52, 2
	s_addk_i32 s50, 0x100
	s_addk_i32 s51, 0x100
	s_cmp_gt_u32 s52, 29
	s_cbranch_scc0 .LBB0_223
	s_and_b64 vcc, exec, s[46:47]
	s_cbranch_vccz .LBB0_226
	s_barrier
	s_setprio 1

; __device__ __forceinline__ unsigned xb_ld(unsigned* p)              { return __hip_atomic_load(p, __ATOMIC_RELAXED, __HIP_MEMORY_SCOPE_AGENT); }
; __device__ __forceinline__ void xcd_barrier_complete(unsigned* bar, unsigned x, unsigned& nloc, unsigned& nx) {
;     const unsigned G = gridDim.x * gridDim.y * gridDim.z;
;     unsigned sum, cnt, mine, sp = 0u;
;     for (;;) {
;         sum = 0u; cnt = 0u; mine = 0u;
; #pragma unroll
;         for (unsigned j = 0; j < 16; ++j) { const unsigned c = xb_ld(&bar[XB_XCNT(j)]); sum += c; cnt += (c > 0u) ? 1u : 0u; mine = (j == x) ? c : mine; }
;         if (sum == G) break;
;         __builtin_amdgcn_s_sleep(1);
;         if ((++sp & 255u) == 0u) { if (xb_ld(&bar[XB_TMO])) break; if (sp > XB_SPIN_CAP) { atomicAdd(&bar[XB_TMO], 1u); break; } }
;     }
;     nloc = mine > 0u ? mine : 1u; nx = cnt > 0u ? cnt : 1u;
; }
; __device__ __forceinline__ void xcd_barrier(const XcdBarrier& b) {
;     asm volatile("s_waitcnt vmcnt(0)" ::: "memory");
;     __syncthreads();
;     if (threadIdx.x == 0) {
;         unsigned* bar = b.bar;
;         __builtin_amdgcn_s_waitcnt(0);
;         unsigned nloc = b.st[0], nx = b.st[1];
;         if (nloc == 0u) { xcd_barrier_complete(bar, b.x, nloc, nx); b.st[0] = nloc; b.st[1] = nx; }
.LBB0_246:
	s_waitcnt vmcnt(0)
	s_setprio 0
	s_barrier
	s_and_saveexec_b64 s[30:31], s[94:95]
	s_cbranch_execz .LBB0_298
	v_readlane_b32 s2, v254, 23
	s_waitcnt vmcnt(0) expcnt(0) lgkmcnt(0)
	s_nop 0
	v_mov_b32_e32 v2, s2
	ds_read_b32 v4, v2
	v_readlane_b32 s2, v254, 24
	s_waitcnt lgkmcnt(0)
	v_cmp_ne_u32_e32 vcc, 0, v4
	v_mov_b32_e32 v2, s2
	ds_read_b32 v2, v2
	s_cbranch_vccnz .LBB0_262
	s_load_dwordx2 s[2:3], s[88:89], 0x4
	s_waitcnt lgkmcnt(0)
	s_mul_i32 s1, s2, s1
	s_mul_i32 s1, s1, s3
	s_mov_b32 s2, 1
	s_branch .LBB0_250

; #define PG8_STAGEX(rs, bufoff, soff, voff) do { _Pragma("unroll") for (int _i = 0; _i < 2; ++_i) \
;         __builtin_amdgcn_raw_ptr_buffer_load_lds(rs, (LAS unsigned*)(lds + (bufoff) + ldsw + _i * 8192), 16, (voff)[_i], (soff), 0, 0); } while (0)
; #define PG8_LDA(dst, b, h) do { _Pragma("unroll") for (int m = 0; m < 4; ++m) _Pragma("unroll") for (int k = 0; k < 2; ++k) dst[m][k] = *(const LAS bf16x8*)(lds + PG8_SA(b, h) + aoff + m * 2048 + k * 1024); } while (0)
; #define PG8_LDB(dst, b, h) do { _Pragma("unroll") for (int n = 0; n < 2; ++n) _Pragma("unroll") for (int k = 0; k < 2; ++k) dst[n][k] = *(const LAS bf16x8*)(lds + PG8_SB(b, h) + boff + n * 2048 + k * 1024); } while (0)
; #define PG8_WAIT_V(n) asm volatile("s_waitcnt vmcnt(" #n ")" ::: "memory")
; #define PG8_WAIT_L(n) asm volatile("s_waitcnt lgkmcnt(" #n ")" ::: "memory")
; #define PG8_BAR __builtin_amdgcn_s_barrier()
; #define PG8_SCHED __builtin_amdgcn_sched_barrier(0)
;     ...
;             PG8_LDB(B0, 0, 0); PG8_LDB(B1, 0, 1); PG8_SCHED; PG8_LDA(At, 0, 0); PG8_STAGEX(rsA, PG8_SA(1, 1), a1 + hstepA, voffA);
;             PG8_WAIT_V(8); PG8_WAIT_L(0); PG8_BAR; PG8_MMA(0, 0, At, B0); PG8_MMA(0, 1, At, B1); PG8_BAR; PG8_SCHED;
;             PG8_LDA(At, 0, 1); PG8_STAGEX(rsB, PG8_SB(0, 0), b2, voffB); PG8_STAGEX(rsB, PG8_SB(0, 1), b2 + hstepB, voffB); PG8_STAGEX(rsA, PG8_SA(0, 0), a2, voffA);
;             PG8_WAIT_V(8); PG8_WAIT_L(0); PG8_BAR; PG8_MMA(1, 0, At, B0); PG8_MMA(1, 1, At, B1); PG8_BAR; PG8_SCHED;
.LBB0_323:
	v_add_u32_e32 v118, 0x10000, v210
	v_add_u32_e32 v160, 0x14000, v210
	ds_read_b128 v[106:109], v118
	ds_read_b128 v[110:113], v118 offset:1024
	ds_read_b128 v[114:117], v118 offset:2048
	ds_read_b128 v[118:121], v118 offset:3072
	ds_read_b128 v[122:125], v160
	ds_read_b128 v[134:137], v160 offset:1024
	ds_read_b128 v[156:159], v160 offset:2048
	ds_read_b128 v[160:163], v160 offset:3072
	s_add_i32 s42, s51, 0xffea8080
	s_cmpk_eq_i32 s58, 0x52
	s_cselect_b32 s61, s30, s42
	s_cselect_b32 s60, s31, s57
	s_or_b32 s59, s61, 0x80
	s_mov_b32 m0, s68
	ds_read_b128 v[164:167], v211
	ds_read_b128 v[168:171], v211 offset:1024
	ds_read_b128 v[182:185], v211 offset:2048
	ds_read_b128 v[186:189], v211 offset:3072
	ds_read_b128 v[190:193], v211 offset:4096
	ds_read_b128 v[194:197], v211 offset:5120
	ds_read_b128 v[198:201], v211 offset:6144
	ds_read_b128 v[202:205], v211 offset:7168
	buffer_load_dwordx4 v178, s[76:79], s51 offen lds
	s_mov_b32 m0, s69
	s_nop 0
	buffer_load_dwordx4 v206, s[76:79], s51 offen lds
	s_waitcnt vmcnt(8)
	s_waitcnt lgkmcnt(0)
	s_setprio 1
	s_barrier
	v_mfma_f32_16x16x32_bf16 v[150:153], v[106:109], v[164:167], v[150:153]
	v_mfma_f32_16x16x32_bf16 v[150:153], v[110:113], v[168:171], v[150:153]
	v_mfma_f32_16x16x32_bf16 v[146:149], v[118:121], v[168:171], v[146:149]
	v_mfma_f32_16x16x32_bf16 v[146:149], v[114:117], v[164:167], v[146:149]
	v_mfma_f32_16x16x32_bf16 v[138:141], v[114:117], v[182:185], v[138:141]
	v_mfma_f32_16x16x32_bf16 v[138:141], v[118:121], v[186:189], v[138:141]
	v_mfma_f32_16x16x32_bf16 v[142:145], v[110:113], v[186:189], v[142:145]
	v_mfma_f32_16x16x32_bf16 v[142:145], v[106:109], v[182:185], v[142:145]
	v_mfma_f32_16x16x32_bf16 v[130:133], v[106:109], v[190:193], v[130:133]
	v_mfma_f32_16x16x32_bf16 v[130:133], v[110:113], v[194:197], v[130:133]
	v_mfma_f32_16x16x32_bf16 v[126:129], v[118:121], v[194:197], v[126:129]
	v_mfma_f32_16x16x32_bf16 v[126:129], v[114:117], v[190:193], v[126:129]
	v_mfma_f32_16x16x32_bf16 v[98:101], v[114:117], v[198:201], v[98:101]
	v_mfma_f32_16x16x32_bf16 v[98:101], v[118:121], v[202:205], v[98:101]
	v_mfma_f32_16x16x32_bf16 v[102:105], v[110:113], v[202:205], v[102:105]
	v_mfma_f32_16x16x32_bf16 v[102:105], v[106:109], v[198:201], v[102:105]
	v_mfma_f32_16x16x32_bf16 v[62:65], v[122:125], v[164:167], v[62:65]
	v_mfma_f32_16x16x32_bf16 v[62:65], v[134:137], v[168:171], v[62:65]
	v_mfma_f32_16x16x32_bf16 v[58:61], v[160:163], v[168:171], v[58:61]
	v_mfma_f32_16x16x32_bf16 v[58:61], v[156:159], v[164:167], v[58:61]
	v_mfma_f32_16x16x32_bf16 v[50:53], v[156:159], v[182:185], v[50:53]
	v_mfma_f32_16x16x32_bf16 v[50:53], v[160:163], v[186:189], v[50:53]
	v_mfma_f32_16x16x32_bf16 v[54:57], v[134:137], v[186:189], v[54:57]
	v_mfma_f32_16x16x32_bf16 v[54:57], v[122:125], v[182:185], v[54:57]
	v_mfma_f32_16x16x32_bf16 v[46:49], v[122:125], v[190:193], v[46:49]
	v_mfma_f32_16x16x32_bf16 v[46:49], v[134:137], v[194:197], v[46:49]
	v_mfma_f32_16x16x32_bf16 v[42:45], v[160:163], v[194:197], v[42:45]
	v_mfma_f32_16x16x32_bf16 v[42:45], v[156:159], v[190:193], v[42:45]
	v_mfma_f32_16x16x32_bf16 v[34:37], v[156:159], v[198:201], v[34:37]
	v_mfma_f32_16x16x32_bf16 v[34:37], v[160:163], v[202:205], v[34:37]
	v_mfma_f32_16x16x32_bf16 v[38:41], v[134:137], v[202:205], v[38:41]
	v_mfma_f32_16x16x32_bf16 v[38:41], v[122:125], v[198:201], v[38:41]
	s_barrier
	s_setprio 0
	s_mov_b32 m0, s15
	s_mov_b32 s42, s78
	s_mov_b32 s43, s79
	ds_read_b128 v[164:167], v211 offset:16384
	ds_read_b128 v[168:171], v211 offset:17408
	ds_read_b128 v[182:185], v211 offset:18432
	ds_read_b128 v[186:189], v211 offset:19456
	ds_read_b128 v[190:193], v211 offset:20480
	ds_read_b128 v[194:197], v211 offset:21504
	ds_read_b128 v[198:201], v211 offset:22528
	ds_read_b128 v[202:205], v211 offset:23552
	buffer_load_dwordx4 v179, s[40:43], s60 offen lds
	s_mov_b32 m0, s16
	s_add_i32 s62, s60, 0x158000
	buffer_load_dwordx4 v207, s[40:43], s60 offen lds
	s_mov_b32 m0, s17
	s_nop 0
	buffer_load_dwordx4 v179, s[40:43], s62 offen lds
	s_mov_b32 m0, s18
	s_nop 0
	buffer_load_dwordx4 v207, s[40:43], s62 offen lds
	s_mov_b32 m0, s14
	s_nop 0
	buffer_load_dwordx4 v178, s[76:79], s61 offen lds
	s_mov_b32 m0, s19
	s_nop 0
	buffer_load_dwordx4 v206, s[76:79], s61 offen lds
	s_waitcnt vmcnt(8)
	s_waitcnt lgkmcnt(0)
	s_setprio 1
	s_barrier
	v_mfma_f32_16x16x32_bf16 v[94:97], v[106:109], v[164:167], v[94:97]
	v_mfma_f32_16x16x32_bf16 v[94:97], v[110:113], v[168:171], v[94:97]
	v_mfma_f32_16x16x32_bf16 v[90:93], v[118:121], v[168:171], v[90:93]
	v_mfma_f32_16x16x32_bf16 v[90:93], v[114:117], v[164:167], v[90:93]
	v_mfma_f32_16x16x32_bf16 v[82:85], v[114:117], v[182:185], v[82:85]
	v_mfma_f32_16x16x32_bf16 v[82:85], v[118:121], v[186:189], v[82:85]
	v_mfma_f32_16x16x32_bf16 v[86:89], v[110:113], v[186:189], v[86:89]
	v_mfma_f32_16x16x32_bf16 v[86:89], v[106:109], v[182:185], v[86:89]
	v_mfma_f32_16x16x32_bf16 v[78:81], v[106:109], v[190:193], v[78:81]
	v_mfma_f32_16x16x32_bf16 v[78:81], v[110:113], v[194:197], v[78:81]
	v_mfma_f32_16x16x32_bf16 v[74:77], v[118:121], v[194:197], v[74:77]
	v_mfma_f32_16x16x32_bf16 v[74:77], v[114:117], v[190:193], v[74:77]
	v_mfma_f32_16x16x32_bf16 v[66:69], v[114:117], v[198:201], v[66:69]
	v_mfma_f32_16x16x32_bf16 v[66:69], v[118:121], v[202:205], v[66:69]
	v_mfma_f32_16x16x32_bf16 v[70:73], v[110:113], v[202:205], v[70:73]
	v_mfma_f32_16x16x32_bf16 v[70:73], v[106:109], v[198:201], v[70:73]
	v_mfma_f32_16x16x32_bf16 v[30:33], v[122:125], v[164:167], v[30:33]
	v_mfma_f32_16x16x32_bf16 v[30:33], v[134:137], v[168:171], v[30:33]
	v_mfma_f32_16x16x32_bf16 v[26:29], v[160:163], v[168:171], v[26:29]
	v_mfma_f32_16x16x32_bf16 v[26:29], v[156:159], v[164:167], v[26:29]
	v_mfma_f32_16x16x32_bf16 v[18:21], v[156:159], v[182:185], v[18:21]
	v_mfma_f32_16x16x32_bf16 v[18:21], v[160:163], v[186:189], v[18:21]
	v_mfma_f32_16x16x32_bf16 v[22:25], v[134:137], v[186:189], v[22:25]
	v_mfma_f32_16x16x32_bf16 v[22:25], v[122:125], v[182:185], v[22:25]
	v_mfma_f32_16x16x32_bf16 v[14:17], v[122:125], v[190:193], v[14:17]
	v_mfma_f32_16x16x32_bf16 v[14:17], v[134:137], v[194:197], v[14:17]
	v_mfma_f32_16x16x32_bf16 v[10:13], v[160:163], v[194:197], v[10:13]
	v_mfma_f32_16x16x32_bf16 v[10:13], v[156:159], v[190:193], v[10:13]
	v_mfma_f32_16x16x32_bf16 v[2:5], v[156:159], v[198:201], v[2:5]
	v_mfma_f32_16x16x32_bf16 v[2:5], v[160:163], v[202:205], v[2:5]
	v_mfma_f32_16x16x32_bf16 v[6:9], v[134:137], v[202:205], v[6:9]
	v_mfma_f32_16x16x32_bf16 v[6:9], v[122:125], v[198:201], v[6:9]
	s_barrier
; #define PG8_STAGEX(rs, bufoff, soff, voff) do { _Pragma("unroll") for (int _i = 0; _i < 2; ++_i) \
;         __builtin_amdgcn_raw_ptr_buffer_load_lds(rs, (LAS unsigned*)(lds + (bufoff) + ldsw + _i * 8192), 16, (voff)[_i], (soff), 0, 0); } while (0)
; #define PG8_WAIT_V(n) asm volatile("s_waitcnt vmcnt(" #n ")" ::: "memory")
; #define PG8_WAIT_L(n) asm volatile("s_waitcnt lgkmcnt(" #n ")" ::: "memory")
; #define PG8_BAR __builtin_amdgcn_s_barrier()
;     ...
;             PG8_LDB(B0, 1, 0); PG8_LDB(B1, 1, 1); PG8_SCHED; PG8_LDA(At, 1, 0); PG8_STAGEX(rsA, PG8_SA(0, 1), a2 + hstepA, voffA);
;             PG8_WAIT_V(8); PG8_WAIT_L(0); PG8_BAR; PG8_MMA(0, 0, At, B0); PG8_MMA(0, 1, At, B1); PG8_BAR; PG8_SCHED;
;             PG8_LDA(At, 1, 1); PG8_STAGEX(rsB, PG8_SB(1, 0), b3, voffB); PG8_STAGEX(rsB, PG8_SB(1, 1), b3 + hstepB, voffB); PG8_STAGEX(rsA, PG8_SA(1, 0), a3, voffA);
;             PG8_WAIT_V(8); PG8_WAIT_L(0); PG8_BAR; PG8_MMA(1, 0, At, B0); PG8_MMA(1, 1, At, B1); PG8_BAR; PG8_SCHED;
;         }
;         } else {
;             const bool w0 = (QV == 2) || (wr == 0);
; #pragma nounroll
;             for (int t = 0; t < nt; t += 2) {
;                 const bool last = (t == nt - 2);
;                 const unsigned a1 = cA + (unsigned)(t + 1) * kstep;
;                 const unsigned a2 = last ? nA : cA + (unsigned)(t + 2) * kstep, b2 = last ? nB : cB + (unsigned)(t + 2) * kstep;
;                 const unsigned a3 = a2 + kstep, b3 = b2 + kstep;
;                 if (w0) { PG8_LDB(B0, 0, 0); PG8_LDB(B1, 0, 1); PG8_SCHED; PG8_LDA(At, 0, 0); }
;                 PG8_WAIT_L(0); PG8_BAR; if (w0) { PG8_MMA(0, 0, At, B0); PG8_MMA(0, 1, At, B1); } PG8_BAR; PG8_SCHED;
;                 PG8_STAGEX(rsB, PG8_SB(0, 0), b2, voffB); PG8_STAGEX(rsB, PG8_SB(0, 1), b2 + hstepB, voffB); PG8_STAGEX(rsA, PG8_SA(0, 0), a2, voffA);
;                 PG8_WAIT_V(6); PG8_BAR; PG8_BAR; PG8_SCHED;
;                 if (w0) { PG8_LDB(B0, 1, 0); PG8_LDB(B1, 1, 1); PG8_SCHED; PG8_LDA(At, 1, 0); }
;                 PG8_WAIT_L(0); PG8_BAR; if (w0) { PG8_MMA(0, 0, At, B0); PG8_MMA(0, 1, At, B1); } PG8_BAR; PG8_SCHED;
;                 PG8_STAGEX(rsB, PG8_SB(1, 0), b3, voffB); PG8_STAGEX(rsB, PG8_SB(1, 1), b3 + hstepB, voffB); PG8_STAGEX(rsA, PG8_SA(1, 0), a3, voffA);
;                 PG8_WAIT_V(6); PG8_BAR; PG8_BAR; PG8_SCHED;
;             }
;         }
;         if (wr == 0) PG8_BAR;
	s_setprio 0
	v_add_u32_e32 v118, 0x18000, v210
	v_add_u32_e32 v160, 0x1c000, v210
	ds_read_b128 v[106:109], v118
	ds_read_b128 v[110:113], v118 offset:1024
	ds_read_b128 v[114:117], v118 offset:2048
	ds_read_b128 v[118:121], v118 offset:3072
	ds_read_b128 v[122:125], v160
	ds_read_b128 v[134:137], v160 offset:1024
	ds_read_b128 v[156:159], v160 offset:2048
	ds_read_b128 v[160:163], v160 offset:3072
	s_add_i32 s61, s61, 0x158000
	s_mov_b32 m0, s20
	ds_read_b128 v[164:167], v211 offset:32768
	ds_read_b128 v[168:171], v211 offset:33792
	ds_read_b128 v[182:185], v211 offset:34816
	ds_read_b128 v[186:189], v211 offset:35840
	ds_read_b128 v[190:193], v211 offset:36864
	ds_read_b128 v[194:197], v211 offset:37888
	ds_read_b128 v[198:201], v211 offset:38912
	ds_read_b128 v[202:205], v211 offset:39936
	buffer_load_dwordx4 v178, s[76:79], s61 offen lds
	s_mov_b32 m0, s21
	s_nop 0
	buffer_load_dwordx4 v206, s[76:79], s61 offen lds
	s_waitcnt vmcnt(8)
	s_waitcnt lgkmcnt(0)
	s_setprio 1
	s_barrier
	v_mfma_f32_16x16x32_bf16 v[150:153], v[106:109], v[164:167], v[150:153]
	v_mfma_f32_16x16x32_bf16 v[150:153], v[110:113], v[168:171], v[150:153]
	v_mfma_f32_16x16x32_bf16 v[146:149], v[118:121], v[168:171], v[146:149]
	v_mfma_f32_16x16x32_bf16 v[146:149], v[114:117], v[164:167], v[146:149]
	v_mfma_f32_16x16x32_bf16 v[138:141], v[114:117], v[182:185], v[138:141]
	v_mfma_f32_16x16x32_bf16 v[138:141], v[118:121], v[186:189], v[138:141]
	v_mfma_f32_16x16x32_bf16 v[142:145], v[110:113], v[186:189], v[142:145]
	v_mfma_f32_16x16x32_bf16 v[142:145], v[106:109], v[182:185], v[142:145]
	v_mfma_f32_16x16x32_bf16 v[130:133], v[106:109], v[190:193], v[130:133]
	v_mfma_f32_16x16x32_bf16 v[130:133], v[110:113], v[194:197], v[130:133]
	v_mfma_f32_16x16x32_bf16 v[126:129], v[118:121], v[194:197], v[126:129]
	v_mfma_f32_16x16x32_bf16 v[126:129], v[114:117], v[190:193], v[126:129]
	v_mfma_f32_16x16x32_bf16 v[98:101], v[114:117], v[198:201], v[98:101]
	v_mfma_f32_16x16x32_bf16 v[98:101], v[118:121], v[202:205], v[98:101]
	v_mfma_f32_16x16x32_bf16 v[102:105], v[110:113], v[202:205], v[102:105]
	v_mfma_f32_16x16x32_bf16 v[102:105], v[106:109], v[198:201], v[102:105]
	v_mfma_f32_16x16x32_bf16 v[62:65], v[122:125], v[164:167], v[62:65]
	v_mfma_f32_16x16x32_bf16 v[62:65], v[134:137], v[168:171], v[62:65]
	v_mfma_f32_16x16x32_bf16 v[58:61], v[160:163], v[168:171], v[58:61]
	v_mfma_f32_16x16x32_bf16 v[58:61], v[156:159], v[164:167], v[58:61]
	v_mfma_f32_16x16x32_bf16 v[50:53], v[156:159], v[182:185], v[50:53]
	v_mfma_f32_16x16x32_bf16 v[50:53], v[160:163], v[186:189], v[50:53]
	v_mfma_f32_16x16x32_bf16 v[54:57], v[134:137], v[186:189], v[54:57]
	v_mfma_f32_16x16x32_bf16 v[54:57], v[122:125], v[182:185], v[54:57]
	v_mfma_f32_16x16x32_bf16 v[46:49], v[122:125], v[190:193], v[46:49]
	v_mfma_f32_16x16x32_bf16 v[46:49], v[134:137], v[194:197], v[46:49]
	v_mfma_f32_16x16x32_bf16 v[42:45], v[160:163], v[194:197], v[42:45]
	v_mfma_f32_16x16x32_bf16 v[42:45], v[156:159], v[190:193], v[42:45]
	v_mfma_f32_16x16x32_bf16 v[34:37], v[156:159], v[198:201], v[34:37]
	v_mfma_f32_16x16x32_bf16 v[34:37], v[160:163], v[202:205], v[34:37]
	v_mfma_f32_16x16x32_bf16 v[38:41], v[134:137], v[202:205], v[38:41]
	v_mfma_f32_16x16x32_bf16 v[38:41], v[122:125], v[198:201], v[38:41]
	s_barrier
	s_setprio 0
	s_mov_b32 m0, s28
	s_or_b32 s61, s60, 0x80
	ds_read_b128 v[164:167], v211 offset:49152
	ds_read_b128 v[168:171], v211 offset:50176
	ds_read_b128 v[182:185], v211 offset:51200
	ds_read_b128 v[186:189], v211 offset:52224
	ds_read_b128 v[190:193], v211 offset:53248
	ds_read_b128 v[194:197], v211 offset:54272
	ds_read_b128 v[198:201], v211 offset:55296
	ds_read_b128 v[202:205], v211 offset:56320
	buffer_load_dwordx4 v179, s[40:43], s61 offen lds
	s_mov_b32 m0, s29
	s_add_i32 s60, s60, 0x158080
	buffer_load_dwordx4 v207, s[40:43], s61 offen lds
	s_mov_b32 m0, s66
	s_nop 0
	buffer_load_dwordx4 v179, s[40:43], s60 offen lds
	s_mov_b32 m0, s67
	s_nop 0
	buffer_load_dwordx4 v207, s[40:43], s60 offen lds
	s_mov_b32 m0, s54
	s_nop 0
	buffer_load_dwordx4 v178, s[76:79], s59 offen lds
	s_mov_b32 m0, s55
	s_nop 0
	buffer_load_dwordx4 v206, s[76:79], s59 offen lds
	s_waitcnt vmcnt(8)
	s_waitcnt lgkmcnt(0)
	s_setprio 1
	s_barrier
	v_mfma_f32_16x16x32_bf16 v[94:97], v[106:109], v[164:167], v[94:97]
	v_mfma_f32_16x16x32_bf16 v[94:97], v[110:113], v[168:171], v[94:97]
	v_mfma_f32_16x16x32_bf16 v[90:93], v[118:121], v[168:171], v[90:93]
	v_mfma_f32_16x16x32_bf16 v[90:93], v[114:117], v[164:167], v[90:93]
	v_mfma_f32_16x16x32_bf16 v[82:85], v[114:117], v[182:185], v[82:85]
	v_mfma_f32_16x16x32_bf16 v[82:85], v[118:121], v[186:189], v[82:85]
	v_mfma_f32_16x16x32_bf16 v[86:89], v[110:113], v[186:189], v[86:89]
	v_mfma_f32_16x16x32_bf16 v[86:89], v[106:109], v[182:185], v[86:89]
	v_mfma_f32_16x16x32_bf16 v[78:81], v[106:109], v[190:193], v[78:81]
	v_mfma_f32_16x16x32_bf16 v[78:81], v[110:113], v[194:197], v[78:81]
	v_mfma_f32_16x16x32_bf16 v[74:77], v[118:121], v[194:197], v[74:77]
	v_mfma_f32_16x16x32_bf16 v[74:77], v[114:117], v[190:193], v[74:77]
	v_mfma_f32_16x16x32_bf16 v[66:69], v[114:117], v[198:201], v[66:69]
	v_mfma_f32_16x16x32_bf16 v[66:69], v[118:121], v[202:205], v[66:69]
	v_mfma_f32_16x16x32_bf16 v[70:73], v[110:113], v[202:205], v[70:73]
	v_mfma_f32_16x16x32_bf16 v[70:73], v[106:109], v[198:201], v[70:73]
	v_mfma_f32_16x16x32_bf16 v[30:33], v[122:125], v[164:167], v[30:33]
	v_mfma_f32_16x16x32_bf16 v[30:33], v[134:137], v[168:171], v[30:33]
	v_mfma_f32_16x16x32_bf16 v[26:29], v[160:163], v[168:171], v[26:29]
	v_mfma_f32_16x16x32_bf16 v[26:29], v[156:159], v[164:167], v[26:29]
	v_mfma_f32_16x16x32_bf16 v[18:21], v[156:159], v[182:185], v[18:21]
	v_mfma_f32_16x16x32_bf16 v[18:21], v[160:163], v[186:189], v[18:21]
	v_mfma_f32_16x16x32_bf16 v[22:25], v[134:137], v[186:189], v[22:25]
	v_mfma_f32_16x16x32_bf16 v[22:25], v[122:125], v[182:185], v[22:25]
	v_mfma_f32_16x16x32_bf16 v[14:17], v[122:125], v[190:193], v[14:17]
	v_mfma_f32_16x16x32_bf16 v[14:17], v[134:137], v[194:197], v[14:17]
	v_mfma_f32_16x16x32_bf16 v[10:13], v[160:163], v[194:197], v[10:13]
	v_mfma_f32_16x16x32_bf16 v[10:13], v[156:159], v[190:193], v[10:13]
	v_mfma_f32_16x16x32_bf16 v[2:5], v[156:159], v[198:201], v[2:5]
	v_mfma_f32_16x16x32_bf16 v[2:5], v[160:163], v[202:205], v[2:5]
	v_mfma_f32_16x16x32_bf16 v[6:9], v[134:137], v[202:205], v[6:9]
	v_mfma_f32_16x16x32_bf16 v[6:9], v[122:125], v[198:201], v[6:9]
	s_barrier
	s_setprio 0
	s_add_i32 s58, s58, 2
	s_addk_i32 s51, 0x100
	s_addk_i32 s57, 0x100
	s_cmpk_gt_u32 s58, 0x53
	s_cbranch_scc0 .LBB0_323
	s_and_b64 vcc, exec, s[48:49]
	s_cbranch_vccz .LBB0_326
	s_barrier
	s_setprio 1

; __device__ __forceinline__ unsigned xb_ld(unsigned* p)              { return __hip_atomic_load(p, __ATOMIC_RELAXED, __HIP_MEMORY_SCOPE_AGENT); }
; __device__ __forceinline__ void xcd_barrier_complete(unsigned* bar, unsigned x, unsigned& nloc, unsigned& nx) {
;     const unsigned G = gridDim.x * gridDim.y * gridDim.z;
;     unsigned sum, cnt, mine, sp = 0u;
;     for (;;) {
;         sum = 0u; cnt = 0u; mine = 0u;
; #pragma unroll
;         for (unsigned j = 0; j < 16; ++j) { const unsigned c = xb_ld(&bar[XB_XCNT(j)]); sum += c; cnt += (c > 0u) ? 1u : 0u; mine = (j == x) ? c : mine; }
;         if (sum == G) break;
;         __builtin_amdgcn_s_sleep(1);
;         if ((++sp & 255u) == 0u) { if (xb_ld(&bar[XB_TMO])) break; if (sp > XB_SPIN_CAP) { atomicAdd(&bar[XB_TMO], 1u); break; } }
;     }
;     nloc = mine > 0u ? mine : 1u; nx = cnt > 0u ? cnt : 1u;
; }
; __device__ __forceinline__ void xcd_barrier(const XcdBarrier& b) {
;     asm volatile("s_waitcnt vmcnt(0)" ::: "memory");
;     __syncthreads();
;     if (threadIdx.x == 0) {
;         unsigned* bar = b.bar;
;         __builtin_amdgcn_s_waitcnt(0);
;         unsigned nloc = b.st[0], nx = b.st[1];
;         if (nloc == 0u) { xcd_barrier_complete(bar, b.x, nloc, nx); b.st[0] = nloc; b.st[1] = nx; }
.LBB0_374:
	s_waitcnt vmcnt(0)
	s_waitcnt vmcnt(0) lgkmcnt(0)
	s_setprio 0
	s_barrier
	s_and_saveexec_b64 s[30:31], s[94:95]
	s_cbranch_execz .LBB0_426
	v_readlane_b32 s2, v254, 23
	s_waitcnt vmcnt(0) expcnt(0) lgkmcnt(0)
	s_nop 0
	v_mov_b32_e32 v2, s2
	ds_read_b32 v4, v2
	v_readlane_b32 s2, v254, 24
	s_waitcnt lgkmcnt(0)
	v_cmp_ne_u32_e32 vcc, 0, v4
	v_mov_b32_e32 v2, s2
	ds_read_b32 v2, v2
	s_cbranch_vccnz .LBB0_390
	s_load_dwordx2 s[2:3], s[88:89], 0x4
	s_waitcnt lgkmcnt(0)
	s_mul_i32 s1, s2, s1
	s_mul_i32 s1, s1, s3
	s_mov_b32 s2, 1
	s_branch .LBB0_378

; #define PG8_STAGEX(rs, bufoff, soff, voff) do { _Pragma("unroll") for (int _i = 0; _i < 2; ++_i) \
;         __builtin_amdgcn_raw_ptr_buffer_load_lds(rs, (LAS unsigned*)(lds + (bufoff) + ldsw + _i * 8192), 16, (voff)[_i], (soff), 0, 0); } while (0)
; #define PG8_LDA(dst, b, h) do { _Pragma("unroll") for (int m = 0; m < 4; ++m) _Pragma("unroll") for (int k = 0; k < 2; ++k) dst[m][k] = *(const LAS bf16x8*)(lds + PG8_SA(b, h) + aoff + m * 2048 + k * 1024); } while (0)
; #define PG8_LDB(dst, b, h) do { _Pragma("unroll") for (int n = 0; n < 2; ++n) _Pragma("unroll") for (int k = 0; k < 2; ++k) dst[n][k] = *(const LAS bf16x8*)(lds + PG8_SB(b, h) + boff + n * 2048 + k * 1024); } while (0)
; #define PG8_WAIT_V(n) asm volatile("s_waitcnt vmcnt(" #n ")" ::: "memory")
; #define PG8_WAIT_L(n) asm volatile("s_waitcnt lgkmcnt(" #n ")" ::: "memory")
; #define PG8_BAR __builtin_amdgcn_s_barrier()
; #define PG8_SCHED __builtin_amdgcn_sched_barrier(0)
;     ...
;             PG8_LDB(B0, 0, 0); PG8_LDB(B1, 0, 1); PG8_SCHED; PG8_LDA(At, 0, 0); PG8_STAGEX(rsA, PG8_SA(1, 1), a1 + hstepA, voffA);
;             PG8_WAIT_V(8); PG8_WAIT_L(0); PG8_BAR; PG8_MMA(0, 0, At, B0); PG8_MMA(0, 1, At, B1); PG8_BAR; PG8_SCHED;
;             PG8_LDA(At, 0, 1); PG8_STAGEX(rsB, PG8_SB(0, 0), b2, voffB); PG8_STAGEX(rsB, PG8_SB(0, 1), b2 + hstepB, voffB); PG8_STAGEX(rsA, PG8_SA(0, 0), a2, voffA);
;             PG8_WAIT_V(8); PG8_WAIT_L(0); PG8_BAR; PG8_MMA(1, 0, At, B0); PG8_MMA(1, 1, At, B1); PG8_BAR; PG8_SCHED;
.LBB0_437:
	v_add_u32_e32 v142, 0x10000, v220
	v_add_u32_e32 v158, 0x14000, v220
	ds_read_b128 v[130:133], v142
	ds_read_b128 v[134:137], v142 offset:1024
	ds_read_b128 v[138:141], v142 offset:2048
	ds_read_b128 v[142:145], v142 offset:3072
	ds_read_b128 v[146:149], v158
	ds_read_b128 v[150:153], v158 offset:1024
	ds_read_b128 v[154:157], v158 offset:2048
	ds_read_b128 v[158:161], v158 offset:3072
	s_add_i32 s30, s7, 0xfff80080
	s_cmp_eq_u32 s29, 28
	s_cselect_b32 s50, s2, s30
	s_cselect_b32 s31, s5, s28
	s_or_b32 s30, s50, 0x80
	s_mov_b32 m0, s20
	ds_read_b128 v[162:165], v221
	ds_read_b128 v[170:173], v221 offset:1024
	ds_read_b128 v[182:185], v221 offset:2048
	ds_read_b128 v[186:189], v221 offset:3072
	ds_read_b128 v[190:193], v221 offset:4096
	ds_read_b128 v[194:197], v221 offset:5120
	ds_read_b128 v[198:201], v221 offset:6144
	ds_read_b128 v[202:205], v221 offset:7168
	buffer_load_dwordx4 v178, s[76:79], s7 offen lds
	s_mov_b32 m0, s22
	s_nop 0
	buffer_load_dwordx4 v210, s[76:79], s7 offen lds
	s_waitcnt vmcnt(8)
	s_waitcnt lgkmcnt(0)
	s_setprio 1
	s_barrier
	v_mfma_f32_16x16x32_bf16 v[126:129], v[130:133], v[162:165], v[126:129]
	v_mfma_f32_16x16x32_bf16 v[126:129], v[134:137], v[170:173], v[126:129]
	v_mfma_f32_16x16x32_bf16 v[110:113], v[142:145], v[170:173], v[110:113]
	v_mfma_f32_16x16x32_bf16 v[110:113], v[138:141], v[162:165], v[110:113]
	v_mfma_f32_16x16x32_bf16 v[102:105], v[138:141], v[182:185], v[102:105]
	v_mfma_f32_16x16x32_bf16 v[102:105], v[142:145], v[186:189], v[102:105]
	v_mfma_f32_16x16x32_bf16 v[118:121], v[134:137], v[186:189], v[118:121]
	v_mfma_f32_16x16x32_bf16 v[118:121], v[130:133], v[182:185], v[118:121]
	v_mfma_f32_16x16x32_bf16 v[114:117], v[130:133], v[190:193], v[114:117]
	v_mfma_f32_16x16x32_bf16 v[114:117], v[134:137], v[194:197], v[114:117]
	v_mfma_f32_16x16x32_bf16 v[98:101], v[142:145], v[194:197], v[98:101]
	v_mfma_f32_16x16x32_bf16 v[98:101], v[138:141], v[190:193], v[98:101]
	v_mfma_f32_16x16x32_bf16 v[106:109], v[138:141], v[198:201], v[106:109]
	v_mfma_f32_16x16x32_bf16 v[106:109], v[142:145], v[202:205], v[106:109]
	v_mfma_f32_16x16x32_bf16 v[122:125], v[134:137], v[202:205], v[122:125]
	v_mfma_f32_16x16x32_bf16 v[122:125], v[130:133], v[198:201], v[122:125]
	v_mfma_f32_16x16x32_bf16 v[62:65], v[146:149], v[162:165], v[62:65]
	v_mfma_f32_16x16x32_bf16 v[62:65], v[150:153], v[170:173], v[62:65]
	v_mfma_f32_16x16x32_bf16 v[46:49], v[158:161], v[170:173], v[46:49]
	v_mfma_f32_16x16x32_bf16 v[46:49], v[154:157], v[162:165], v[46:49]
	v_mfma_f32_16x16x32_bf16 v[38:41], v[154:157], v[182:185], v[38:41]
	v_mfma_f32_16x16x32_bf16 v[38:41], v[158:161], v[186:189], v[38:41]
	v_mfma_f32_16x16x32_bf16 v[54:57], v[150:153], v[186:189], v[54:57]
	v_mfma_f32_16x16x32_bf16 v[54:57], v[146:149], v[182:185], v[54:57]
	v_mfma_f32_16x16x32_bf16 v[50:53], v[146:149], v[190:193], v[50:53]
	v_mfma_f32_16x16x32_bf16 v[50:53], v[150:153], v[194:197], v[50:53]
	v_mfma_f32_16x16x32_bf16 v[34:37], v[158:161], v[194:197], v[34:37]
	v_mfma_f32_16x16x32_bf16 v[34:37], v[154:157], v[190:193], v[34:37]
	v_mfma_f32_16x16x32_bf16 v[42:45], v[154:157], v[198:201], v[42:45]
	v_mfma_f32_16x16x32_bf16 v[42:45], v[158:161], v[202:205], v[42:45]
	v_mfma_f32_16x16x32_bf16 v[58:61], v[150:153], v[202:205], v[58:61]
	v_mfma_f32_16x16x32_bf16 v[58:61], v[146:149], v[198:201], v[58:61]
	s_barrier
	s_setprio 0
	s_mov_b32 m0, s90
	s_mov_b32 s58, s78
	s_mov_b32 s59, s79
	ds_read_b128 v[162:165], v221 offset:16384
	ds_read_b128 v[170:173], v221 offset:17408
	ds_read_b128 v[182:185], v221 offset:18432
	ds_read_b128 v[186:189], v221 offset:19456
	ds_read_b128 v[190:193], v221 offset:20480
	ds_read_b128 v[194:197], v221 offset:21504
	ds_read_b128 v[198:201], v221 offset:22528
	ds_read_b128 v[202:205], v221 offset:23552
	buffer_load_dwordx4 v179, s[56:59], s31 offen lds
	s_mov_b32 m0, s91
	s_add_i32 s51, s31, 0x80000
	buffer_load_dwordx4 v211, s[56:59], s31 offen lds
	s_mov_b32 m0, s9
	s_nop 0
	buffer_load_dwordx4 v179, s[56:59], s51 offen lds
	s_mov_b32 m0, s10
	s_nop 0
	buffer_load_dwordx4 v211, s[56:59], s51 offen lds
	s_mov_b32 m0, s89
	s_nop 0
	buffer_load_dwordx4 v178, s[76:79], s50 offen lds
	s_mov_b32 m0, s11
	s_nop 0
	buffer_load_dwordx4 v210, s[76:79], s50 offen lds
	s_waitcnt vmcnt(8)
	s_waitcnt lgkmcnt(0)
	s_setprio 1
	s_barrier
	v_mfma_f32_16x16x32_bf16 v[94:97], v[130:133], v[162:165], v[94:97]
	v_mfma_f32_16x16x32_bf16 v[94:97], v[134:137], v[170:173], v[94:97]
	v_mfma_f32_16x16x32_bf16 v[78:81], v[142:145], v[170:173], v[78:81]
	v_mfma_f32_16x16x32_bf16 v[78:81], v[138:141], v[162:165], v[78:81]
	v_mfma_f32_16x16x32_bf16 v[70:73], v[138:141], v[182:185], v[70:73]
	v_mfma_f32_16x16x32_bf16 v[70:73], v[142:145], v[186:189], v[70:73]
	v_mfma_f32_16x16x32_bf16 v[86:89], v[134:137], v[186:189], v[86:89]
	v_mfma_f32_16x16x32_bf16 v[86:89], v[130:133], v[182:185], v[86:89]
	v_mfma_f32_16x16x32_bf16 v[82:85], v[130:133], v[190:193], v[82:85]
	v_mfma_f32_16x16x32_bf16 v[82:85], v[134:137], v[194:197], v[82:85]
	v_mfma_f32_16x16x32_bf16 v[66:69], v[142:145], v[194:197], v[66:69]
	v_mfma_f32_16x16x32_bf16 v[66:69], v[138:141], v[190:193], v[66:69]
	v_mfma_f32_16x16x32_bf16 v[74:77], v[138:141], v[198:201], v[74:77]
	v_mfma_f32_16x16x32_bf16 v[74:77], v[142:145], v[202:205], v[74:77]
	v_mfma_f32_16x16x32_bf16 v[90:93], v[134:137], v[202:205], v[90:93]
	v_mfma_f32_16x16x32_bf16 v[90:93], v[130:133], v[198:201], v[90:93]
	v_mfma_f32_16x16x32_bf16 v[30:33], v[146:149], v[162:165], v[30:33]
	v_mfma_f32_16x16x32_bf16 v[30:33], v[150:153], v[170:173], v[30:33]
	v_mfma_f32_16x16x32_bf16 v[14:17], v[158:161], v[170:173], v[14:17]
	v_mfma_f32_16x16x32_bf16 v[14:17], v[154:157], v[162:165], v[14:17]
	v_mfma_f32_16x16x32_bf16 v[10:13], v[154:157], v[182:185], v[10:13]
	v_mfma_f32_16x16x32_bf16 v[10:13], v[158:161], v[186:189], v[10:13]
	v_mfma_f32_16x16x32_bf16 v[22:25], v[150:153], v[186:189], v[22:25]
	v_mfma_f32_16x16x32_bf16 v[22:25], v[146:149], v[182:185], v[22:25]
	v_mfma_f32_16x16x32_bf16 v[18:21], v[146:149], v[190:193], v[18:21]
	v_mfma_f32_16x16x32_bf16 v[18:21], v[150:153], v[194:197], v[18:21]
	v_mfma_f32_16x16x32_bf16 v[2:5], v[158:161], v[194:197], v[2:5]
	v_mfma_f32_16x16x32_bf16 v[2:5], v[154:157], v[190:193], v[2:5]
	v_mfma_f32_16x16x32_bf16 v[6:9], v[154:157], v[198:201], v[6:9]
	v_mfma_f32_16x16x32_bf16 v[6:9], v[158:161], v[202:205], v[6:9]
	v_mfma_f32_16x16x32_bf16 v[26:29], v[150:153], v[202:205], v[26:29]
	v_mfma_f32_16x16x32_bf16 v[26:29], v[146:149], v[198:201], v[26:29]
	s_barrier
; #define PG8_STAGEX(rs, bufoff, soff, voff) do { _Pragma("unroll") for (int _i = 0; _i < 2; ++_i) \
;         __builtin_amdgcn_raw_ptr_buffer_load_lds(rs, (LAS unsigned*)(lds + (bufoff) + ldsw + _i * 8192), 16, (voff)[_i], (soff), 0, 0); } while (0)
; #define PG8_WAIT_V(n) asm volatile("s_waitcnt vmcnt(" #n ")" ::: "memory")
; #define PG8_WAIT_L(n) asm volatile("s_waitcnt lgkmcnt(" #n ")" ::: "memory")
; #define PG8_BAR __builtin_amdgcn_s_barrier()
;     ...
;             PG8_LDB(B0, 1, 0); PG8_LDB(B1, 1, 1); PG8_SCHED; PG8_LDA(At, 1, 0); PG8_STAGEX(rsA, PG8_SA(0, 1), a2 + hstepA, voffA);
;             PG8_WAIT_V(8); PG8_WAIT_L(0); PG8_BAR; PG8_MMA(0, 0, At, B0); PG8_MMA(0, 1, At, B1); PG8_BAR; PG8_SCHED;
;             PG8_LDA(At, 1, 1); PG8_STAGEX(rsB, PG8_SB(1, 0), b3, voffB); PG8_STAGEX(rsB, PG8_SB(1, 1), b3 + hstepB, voffB); PG8_STAGEX(rsA, PG8_SA(1, 0), a3, voffA);
;             PG8_WAIT_V(8); PG8_WAIT_L(0); PG8_BAR; PG8_MMA(1, 0, At, B0); PG8_MMA(1, 1, At, B1); PG8_BAR; PG8_SCHED;
;         }
;         } else {
;             const bool w0 = (QV == 2) || (wr == 0);
; #pragma nounroll
;             for (int t = 0; t < nt; t += 2) {
;                 const bool last = (t == nt - 2);
;                 const unsigned a1 = cA + (unsigned)(t + 1) * kstep;
;                 const unsigned a2 = last ? nA : cA + (unsigned)(t + 2) * kstep, b2 = last ? nB : cB + (unsigned)(t + 2) * kstep;
;                 const unsigned a3 = a2 + kstep, b3 = b2 + kstep;
;                 if (w0) { PG8_LDB(B0, 0, 0); PG8_LDB(B1, 0, 1); PG8_SCHED; PG8_LDA(At, 0, 0); }
;                 PG8_WAIT_L(0); PG8_BAR; if (w0) { PG8_MMA(0, 0, At, B0); PG8_MMA(0, 1, At, B1); } PG8_BAR; PG8_SCHED;
;                 PG8_STAGEX(rsB, PG8_SB(0, 0), b2, voffB); PG8_STAGEX(rsB, PG8_SB(0, 1), b2 + hstepB, voffB); PG8_STAGEX(rsA, PG8_SA(0, 0), a2, voffA);
;                 PG8_WAIT_V(6); PG8_BAR; PG8_BAR; PG8_SCHED;
;                 if (w0) { PG8_LDB(B0, 1, 0); PG8_LDB(B1, 1, 1); PG8_SCHED; PG8_LDA(At, 1, 0); }
;                 PG8_WAIT_L(0); PG8_BAR; if (w0) { PG8_MMA(0, 0, At, B0); PG8_MMA(0, 1, At, B1); } PG8_BAR; PG8_SCHED;
;                 PG8_STAGEX(rsB, PG8_SB(1, 0), b3, voffB); PG8_STAGEX(rsB, PG8_SB(1, 1), b3 + hstepB, voffB); PG8_STAGEX(rsA, PG8_SA(1, 0), a3, voffA);
;                 PG8_WAIT_V(6); PG8_BAR; PG8_BAR; PG8_SCHED;
;             }
;         }
;         if (wr == 0) PG8_BAR;
	s_setprio 0
	v_add_u32_e32 v142, 0x18000, v220
	v_add_u32_e32 v158, 0x1c000, v220
	ds_read_b128 v[130:133], v142
	ds_read_b128 v[134:137], v142 offset:1024
	ds_read_b128 v[138:141], v142 offset:2048
	ds_read_b128 v[142:145], v142 offset:3072
	ds_read_b128 v[146:149], v158
	ds_read_b128 v[150:153], v158 offset:1024
	ds_read_b128 v[154:157], v158 offset:2048
	ds_read_b128 v[158:161], v158 offset:3072
	s_add_i32 s50, s50, 0x80000
	s_mov_b32 m0, s74
	ds_read_b128 v[162:165], v221 offset:32768
	ds_read_b128 v[170:173], v221 offset:33792
	ds_read_b128 v[182:185], v221 offset:34816
	ds_read_b128 v[186:189], v221 offset:35840
	ds_read_b128 v[190:193], v221 offset:36864
	ds_read_b128 v[194:197], v221 offset:37888
	ds_read_b128 v[198:201], v221 offset:38912
	ds_read_b128 v[202:205], v221 offset:39936
	buffer_load_dwordx4 v178, s[76:79], s50 offen lds
	s_mov_b32 m0, s12
	s_nop 0
	buffer_load_dwordx4 v210, s[76:79], s50 offen lds
	s_waitcnt vmcnt(8)
	s_waitcnt lgkmcnt(0)
	s_setprio 1
	s_barrier
	v_mfma_f32_16x16x32_bf16 v[126:129], v[130:133], v[162:165], v[126:129]
	v_mfma_f32_16x16x32_bf16 v[126:129], v[134:137], v[170:173], v[126:129]
	v_mfma_f32_16x16x32_bf16 v[110:113], v[142:145], v[170:173], v[110:113]
	v_mfma_f32_16x16x32_bf16 v[110:113], v[138:141], v[162:165], v[110:113]
	v_mfma_f32_16x16x32_bf16 v[102:105], v[138:141], v[182:185], v[102:105]
	v_mfma_f32_16x16x32_bf16 v[102:105], v[142:145], v[186:189], v[102:105]
	v_mfma_f32_16x16x32_bf16 v[118:121], v[134:137], v[186:189], v[118:121]
	v_mfma_f32_16x16x32_bf16 v[118:121], v[130:133], v[182:185], v[118:121]
	v_mfma_f32_16x16x32_bf16 v[114:117], v[130:133], v[190:193], v[114:117]
	v_mfma_f32_16x16x32_bf16 v[114:117], v[134:137], v[194:197], v[114:117]
	v_mfma_f32_16x16x32_bf16 v[98:101], v[142:145], v[194:197], v[98:101]
	v_mfma_f32_16x16x32_bf16 v[98:101], v[138:141], v[190:193], v[98:101]
	v_mfma_f32_16x16x32_bf16 v[106:109], v[138:141], v[198:201], v[106:109]
	v_mfma_f32_16x16x32_bf16 v[106:109], v[142:145], v[202:205], v[106:109]
	v_mfma_f32_16x16x32_bf16 v[122:125], v[134:137], v[202:205], v[122:125]
	v_mfma_f32_16x16x32_bf16 v[122:125], v[130:133], v[198:201], v[122:125]
	v_mfma_f32_16x16x32_bf16 v[62:65], v[146:149], v[162:165], v[62:65]
	v_mfma_f32_16x16x32_bf16 v[62:65], v[150:153], v[170:173], v[62:65]
	v_mfma_f32_16x16x32_bf16 v[46:49], v[158:161], v[170:173], v[46:49]
	v_mfma_f32_16x16x32_bf16 v[46:49], v[154:157], v[162:165], v[46:49]
	v_mfma_f32_16x16x32_bf16 v[38:41], v[154:157], v[182:185], v[38:41]
	v_mfma_f32_16x16x32_bf16 v[38:41], v[158:161], v[186:189], v[38:41]
	v_mfma_f32_16x16x32_bf16 v[54:57], v[150:153], v[186:189], v[54:57]
	v_mfma_f32_16x16x32_bf16 v[54:57], v[146:149], v[182:185], v[54:57]
	v_mfma_f32_16x16x32_bf16 v[50:53], v[146:149], v[190:193], v[50:53]
	v_mfma_f32_16x16x32_bf16 v[50:53], v[150:153], v[194:197], v[50:53]
	v_mfma_f32_16x16x32_bf16 v[34:37], v[158:161], v[194:197], v[34:37]
	v_mfma_f32_16x16x32_bf16 v[34:37], v[154:157], v[190:193], v[34:37]
	v_mfma_f32_16x16x32_bf16 v[42:45], v[154:157], v[198:201], v[42:45]
	v_mfma_f32_16x16x32_bf16 v[42:45], v[158:161], v[202:205], v[42:45]
	v_mfma_f32_16x16x32_bf16 v[58:61], v[150:153], v[202:205], v[58:61]
	v_mfma_f32_16x16x32_bf16 v[58:61], v[146:149], v[198:201], v[58:61]
	s_barrier
	s_setprio 0
	s_mov_b32 m0, s13
	s_or_b32 s50, s31, 0x80
	ds_read_b128 v[162:165], v221 offset:49152
	ds_read_b128 v[170:173], v221 offset:50176
	ds_read_b128 v[182:185], v221 offset:51200
	ds_read_b128 v[186:189], v221 offset:52224
	ds_read_b128 v[190:193], v221 offset:53248
	ds_read_b128 v[194:197], v221 offset:54272
	ds_read_b128 v[198:201], v221 offset:55296
	ds_read_b128 v[202:205], v221 offset:56320
	buffer_load_dwordx4 v179, s[56:59], s50 offen lds
	s_mov_b32 m0, s14
	s_add_i32 s31, s31, 0x80080
	buffer_load_dwordx4 v211, s[56:59], s50 offen lds
	s_mov_b32 m0, s17
	s_nop 0
	buffer_load_dwordx4 v179, s[56:59], s31 offen lds
	s_mov_b32 m0, s18
	s_nop 0
	buffer_load_dwordx4 v211, s[56:59], s31 offen lds
	s_mov_b32 m0, s15
	s_nop 0
	buffer_load_dwordx4 v178, s[76:79], s30 offen lds
	s_mov_b32 m0, s16
	s_nop 0
	buffer_load_dwordx4 v210, s[76:79], s30 offen lds
	s_waitcnt vmcnt(8)
	s_waitcnt lgkmcnt(0)
	s_setprio 1
	s_barrier
	v_mfma_f32_16x16x32_bf16 v[94:97], v[130:133], v[162:165], v[94:97]
	v_mfma_f32_16x16x32_bf16 v[94:97], v[134:137], v[170:173], v[94:97]
	v_mfma_f32_16x16x32_bf16 v[78:81], v[142:145], v[170:173], v[78:81]
	v_mfma_f32_16x16x32_bf16 v[78:81], v[138:141], v[162:165], v[78:81]
	v_mfma_f32_16x16x32_bf16 v[70:73], v[138:141], v[182:185], v[70:73]
	v_mfma_f32_16x16x32_bf16 v[70:73], v[142:145], v[186:189], v[70:73]
	v_mfma_f32_16x16x32_bf16 v[86:89], v[134:137], v[186:189], v[86:89]
	v_mfma_f32_16x16x32_bf16 v[86:89], v[130:133], v[182:185], v[86:89]
	v_mfma_f32_16x16x32_bf16 v[82:85], v[130:133], v[190:193], v[82:85]
	v_mfma_f32_16x16x32_bf16 v[82:85], v[134:137], v[194:197], v[82:85]
	v_mfma_f32_16x16x32_bf16 v[66:69], v[142:145], v[194:197], v[66:69]
	v_mfma_f32_16x16x32_bf16 v[66:69], v[138:141], v[190:193], v[66:69]
	v_mfma_f32_16x16x32_bf16 v[74:77], v[138:141], v[198:201], v[74:77]
	v_mfma_f32_16x16x32_bf16 v[74:77], v[142:145], v[202:205], v[74:77]
	v_mfma_f32_16x16x32_bf16 v[90:93], v[134:137], v[202:205], v[90:93]
	v_mfma_f32_16x16x32_bf16 v[90:93], v[130:133], v[198:201], v[90:93]
	v_mfma_f32_16x16x32_bf16 v[30:33], v[146:149], v[162:165], v[30:33]
	v_mfma_f32_16x16x32_bf16 v[30:33], v[150:153], v[170:173], v[30:33]
	v_mfma_f32_16x16x32_bf16 v[14:17], v[158:161], v[170:173], v[14:17]
	v_mfma_f32_16x16x32_bf16 v[14:17], v[154:157], v[162:165], v[14:17]
	v_mfma_f32_16x16x32_bf16 v[10:13], v[154:157], v[182:185], v[10:13]
	v_mfma_f32_16x16x32_bf16 v[10:13], v[158:161], v[186:189], v[10:13]
	v_mfma_f32_16x16x32_bf16 v[22:25], v[150:153], v[186:189], v[22:25]
	v_mfma_f32_16x16x32_bf16 v[22:25], v[146:149], v[182:185], v[22:25]
	v_mfma_f32_16x16x32_bf16 v[18:21], v[146:149], v[190:193], v[18:21]
	v_mfma_f32_16x16x32_bf16 v[18:21], v[150:153], v[194:197], v[18:21]
	v_mfma_f32_16x16x32_bf16 v[2:5], v[158:161], v[194:197], v[2:5]
	v_mfma_f32_16x16x32_bf16 v[2:5], v[154:157], v[190:193], v[2:5]
	v_mfma_f32_16x16x32_bf16 v[6:9], v[154:157], v[198:201], v[6:9]
	v_mfma_f32_16x16x32_bf16 v[6:9], v[158:161], v[202:205], v[6:9]
	v_mfma_f32_16x16x32_bf16 v[26:29], v[150:153], v[202:205], v[26:29]
	v_mfma_f32_16x16x32_bf16 v[26:29], v[146:149], v[198:201], v[26:29]
	s_barrier
	s_setprio 0
	s_add_i32 s29, s29, 2
	s_addk_i32 s7, 0x100
	s_addk_i32 s28, 0x100
	s_cmp_gt_u32 s29, 29
	s_cbranch_scc0 .LBB0_437
	s_and_b64 vcc, exec, s[84:85]
	s_cbranch_vccz .LBB0_440
	s_barrier
	s_setprio 1

; __device__ __forceinline__ unsigned xb_ld(unsigned* p)              { return __hip_atomic_load(p, __ATOMIC_RELAXED, __HIP_MEMORY_SCOPE_AGENT); }
; __device__ __forceinline__ void xcd_barrier_complete(unsigned* bar, unsigned x, unsigned& nloc, unsigned& nx) {
;     const unsigned G = gridDim.x * gridDim.y * gridDim.z;
;     unsigned sum, cnt, mine, sp = 0u;
;     for (;;) {
;         sum = 0u; cnt = 0u; mine = 0u;
; #pragma unroll
;         for (unsigned j = 0; j < 16; ++j) { const unsigned c = xb_ld(&bar[XB_XCNT(j)]); sum += c; cnt += (c > 0u) ? 1u : 0u; mine = (j == x) ? c : mine; }
;         if (sum == G) break;
;         __builtin_amdgcn_s_sleep(1);
;         if ((++sp & 255u) == 0u) { if (xb_ld(&bar[XB_TMO])) break; if (sp > XB_SPIN_CAP) { atomicAdd(&bar[XB_TMO], 1u); break; } }
;     }
;     nloc = mine > 0u ? mine : 1u; nx = cnt > 0u ? cnt : 1u;
; }
; __device__ __forceinline__ void xcd_barrier(const XcdBarrier& b) {
;     asm volatile("s_waitcnt vmcnt(0)" ::: "memory");
;     __syncthreads();
;     if (threadIdx.x == 0) {
;         unsigned* bar = b.bar;
;         __builtin_amdgcn_s_waitcnt(0);
;         unsigned nloc = b.st[0], nx = b.st[1];
;         if (nloc == 0u) { xcd_barrier_complete(bar, b.x, nloc, nx); b.st[0] = nloc; b.st[1] = nx; }
.LBB0_600:
	s_waitcnt vmcnt(0)
	s_setprio 0
	s_barrier
	s_and_saveexec_b64 s[30:31], s[94:95]
	v_readlane_b32 s88, v254, 27
	v_readlane_b32 s89, v254, 28
	v_readlane_b32 s88, v252, 0
	v_readlane_b32 s90, v254, 29
	v_readlane_b32 s91, v254, 30
	v_readlane_b32 s89, v252, 1
	s_movk_i32 s57, 0x2b00
	s_mov_b32 s56, 0x100000
	s_mov_b32 s62, 0xff61b1e6
	s_mov_b32 s63, 0x41000000
	s_cbranch_execz .LBB0_652
	v_readlane_b32 s1, v254, 23
	s_waitcnt vmcnt(0) expcnt(0) lgkmcnt(0)
	s_nop 0
	v_mov_b32_e32 v2, s1
	ds_read_b32 v4, v2
	v_readlane_b32 s1, v254, 24
	s_waitcnt lgkmcnt(0)
	v_cmp_ne_u32_e32 vcc, 0, v4
	v_mov_b32_e32 v2, s1
	ds_read_b32 v2, v2
	s_cbranch_vccnz .LBB0_616
	s_load_dwordx2 s[2:3], s[88:89], 0x4
	s_waitcnt lgkmcnt(0)
	s_mul_i32 s1, s2, s8
	s_mul_i32 s1, s1, s3
	s_mov_b32 s2, 1
	s_branch .LBB0_604

; __device__ __forceinline__ unsigned xb_ld(unsigned* p)              { return __hip_atomic_load(p, __ATOMIC_RELAXED, __HIP_MEMORY_SCOPE_AGENT); }
; __device__ __forceinline__ void xcd_barrier_complete(unsigned* bar, unsigned x, unsigned& nloc, unsigned& nx) {
;     const unsigned G = gridDim.x * gridDim.y * gridDim.z;
;     unsigned sum, cnt, mine, sp = 0u;
;     for (;;) {
;         sum = 0u; cnt = 0u; mine = 0u;
; #pragma unroll
;         for (unsigned j = 0; j < 16; ++j) { const unsigned c = xb_ld(&bar[XB_XCNT(j)]); sum += c; cnt += (c > 0u) ? 1u : 0u; mine = (j == x) ? c : mine; }
;         if (sum == G) break;
;         __builtin_amdgcn_s_sleep(1);
;         if ((++sp & 255u) == 0u) { if (xb_ld(&bar[XB_TMO])) break; if (sp > XB_SPIN_CAP) { atomicAdd(&bar[XB_TMO], 1u); break; } }
;     }
;     nloc = mine > 0u ? mine : 1u; nx = cnt > 0u ? cnt : 1u;
; }
; __device__ __forceinline__ void xcd_barrier(const XcdBarrier& b) {
;     asm volatile("s_waitcnt vmcnt(0)" ::: "memory");
;     __syncthreads();
;     if (threadIdx.x == 0) {
;         unsigned* bar = b.bar;
;         __builtin_amdgcn_s_waitcnt(0);
;         unsigned nloc = b.st[0], nx = b.st[1];
;         if (nloc == 0u) { xcd_barrier_complete(bar, b.x, nloc, nx); b.st[0] = nloc; b.st[1] = nx; }
.LBB0_689:
	s_or_b64 exec, exec, s[30:31]
	s_waitcnt vmcnt(0)
	s_setprio 0
	s_barrier
	s_and_saveexec_b64 s[2:3], s[94:95]
	s_xor_b64 s[30:31], exec, s[2:3]
	s_cbranch_execz .LBB0_742
	v_readlane_b32 s2, v254, 23
	s_waitcnt vmcnt(0) expcnt(0) lgkmcnt(0)
	s_nop 0
	v_mov_b32_e32 v2, s2
	ds_read_b32 v4, v2
	v_readlane_b32 s2, v254, 24
	s_waitcnt lgkmcnt(0)
	v_cmp_ne_u32_e32 vcc, 0, v4
	v_mov_b32_e32 v2, s2
	ds_read_b32 v2, v2
	s_cbranch_vccnz .LBB0_705
	s_load_dwordx2 s[2:3], s[88:89], 0x4
	s_waitcnt lgkmcnt(0)
	s_mul_i32 s1, s2, s1
	s_mul_i32 s1, s1, s3
	s_mov_b32 s2, 1
	s_branch .LBB0_693

; __device__ __forceinline__ unsigned xb_ld(unsigned* p)              { return __hip_atomic_load(p, __ATOMIC_RELAXED, __HIP_MEMORY_SCOPE_AGENT); }
; __device__ __forceinline__ void xcd_barrier_complete(unsigned* bar, unsigned x, unsigned& nloc, unsigned& nx) {
;     const unsigned G = gridDim.x * gridDim.y * gridDim.z;
;     unsigned sum, cnt, mine, sp = 0u;
;     for (;;) {
;         sum = 0u; cnt = 0u; mine = 0u;
; #pragma unroll
;         for (unsigned j = 0; j < 16; ++j) { const unsigned c = xb_ld(&bar[XB_XCNT(j)]); sum += c; cnt += (c > 0u) ? 1u : 0u; mine = (j == x) ? c : mine; }
;         if (sum == G) break;
;         __builtin_amdgcn_s_sleep(1);
;         if ((++sp & 255u) == 0u) { if (xb_ld(&bar[XB_TMO])) break; if (sp > XB_SPIN_CAP) { atomicAdd(&bar[XB_TMO], 1u); break; } }
;     }
;     nloc = mine > 0u ? mine : 1u; nx = cnt > 0u ? cnt : 1u;
; }
; __device__ __forceinline__ void xcd_barrier(const XcdBarrier& b) {
;     asm volatile("s_waitcnt vmcnt(0)" ::: "memory");
;     __syncthreads();
;     if (threadIdx.x == 0) {
;         unsigned* bar = b.bar;
;         __builtin_amdgcn_s_waitcnt(0);
;         unsigned nloc = b.st[0], nx = b.st[1];
;         if (nloc == 0u) { xcd_barrier_complete(bar, b.x, nloc, nx); b.st[0] = nloc; b.st[1] = nx; }
.LBB0_971:
	s_waitcnt vmcnt(0)
	s_setprio 0
	s_barrier
	s_and_saveexec_b64 s[30:31], s[94:95]
	s_cbranch_execz .LBB0_1023
	v_readlane_b32 s1, v254, 23
	s_waitcnt vmcnt(0) expcnt(0) lgkmcnt(0)
	s_nop 0
	v_mov_b32_e32 v2, s1
	ds_read_b32 v4, v2
	v_readlane_b32 s1, v254, 24
	s_waitcnt lgkmcnt(0)
	v_cmp_ne_u32_e32 vcc, 0, v4
	v_mov_b32_e32 v2, s1
	ds_read_b32 v2, v2
	s_cbranch_vccnz .LBB0_987
	s_load_dwordx2 s[2:3], s[88:89], 0x4
	s_waitcnt lgkmcnt(0)
	s_mul_i32 s1, s2, s60
	s_mul_i32 s1, s1, s3
	s_mov_b32 s2, 1
	s_branch .LBB0_975

; __device__ __forceinline__ unsigned xb_ld(unsigned* p)              { return __hip_atomic_load(p, __ATOMIC_RELAXED, __HIP_MEMORY_SCOPE_AGENT); }
; __device__ __forceinline__ void xcd_barrier_complete(unsigned* bar, unsigned x, unsigned& nloc, unsigned& nx) {
;     const unsigned G = gridDim.x * gridDim.y * gridDim.z;
;     unsigned sum, cnt, mine, sp = 0u;
;     for (;;) {
;         sum = 0u; cnt = 0u; mine = 0u;
; #pragma unroll
;         for (unsigned j = 0; j < 16; ++j) { const unsigned c = xb_ld(&bar[XB_XCNT(j)]); sum += c; cnt += (c > 0u) ? 1u : 0u; mine = (j == x) ? c : mine; }
;         if (sum == G) break;
;         __builtin_amdgcn_s_sleep(1);
;         if ((++sp & 255u) == 0u) { if (xb_ld(&bar[XB_TMO])) break; if (sp > XB_SPIN_CAP) { atomicAdd(&bar[XB_TMO], 1u); break; } }
;     }
;     nloc = mine > 0u ? mine : 1u; nx = cnt > 0u ? cnt : 1u;
; }
; __device__ __forceinline__ void xcd_barrier(const XcdBarrier& b) {
;     asm volatile("s_waitcnt vmcnt(0)" ::: "memory");
;     __syncthreads();
;     if (threadIdx.x == 0) {
;         unsigned* bar = b.bar;
;         __builtin_amdgcn_s_waitcnt(0);
;         unsigned nloc = b.st[0], nx = b.st[1];
;         if (nloc == 0u) { xcd_barrier_complete(bar, b.x, nloc, nx); b.st[0] = nloc; b.st[1] = nx; }
.LBB0_1132:
	s_waitcnt vmcnt(0)
	s_setprio 0
	s_barrier
	s_and_saveexec_b64 s[30:31], s[94:95]
	s_cbranch_execz .LBB0_1184
	v_readlane_b32 s1, v254, 23
	s_waitcnt vmcnt(0) expcnt(0) lgkmcnt(0)
	s_nop 0
	v_mov_b32_e32 v2, s1
	ds_read_b32 v4, v2
	v_readlane_b32 s1, v254, 24
	s_waitcnt lgkmcnt(0)
	v_cmp_ne_u32_e32 vcc, 0, v4
	v_mov_b32_e32 v2, s1
	ds_read_b32 v2, v2
	s_cbranch_vccnz .LBB0_1148
	s_load_dwordx2 s[2:3], s[88:89], 0x4
	s_load_dword s1, s[88:89], 0x0
	s_waitcnt lgkmcnt(0)
	s_mul_i32 s1, s2, s1
	s_mul_i32 s1, s1, s3
	s_mov_b32 s2, 1
	s_branch .LBB0_1136

; __device__ __forceinline__ unsigned xb_ld(unsigned* p)              { return __hip_atomic_load(p, __ATOMIC_RELAXED, __HIP_MEMORY_SCOPE_AGENT); }
; __device__ __forceinline__ void xcd_barrier_complete(unsigned* bar, unsigned x, unsigned& nloc, unsigned& nx) {
;     const unsigned G = gridDim.x * gridDim.y * gridDim.z;
;     unsigned sum, cnt, mine, sp = 0u;
;     for (;;) {
;         sum = 0u; cnt = 0u; mine = 0u;
; #pragma unroll
;         for (unsigned j = 0; j < 16; ++j) { const unsigned c = xb_ld(&bar[XB_XCNT(j)]); sum += c; cnt += (c > 0u) ? 1u : 0u; mine = (j == x) ? c : mine; }
;         if (sum == G) break;
;         __builtin_amdgcn_s_sleep(1);
;         if ((++sp & 255u) == 0u) { if (xb_ld(&bar[XB_TMO])) break; if (sp > XB_SPIN_CAP) { atomicAdd(&bar[XB_TMO], 1u); break; } }
;     }
;     nloc = mine > 0u ? mine : 1u; nx = cnt > 0u ? cnt : 1u;
; }
; __device__ __forceinline__ void xcd_barrier(const XcdBarrier& b) {
;     asm volatile("s_waitcnt vmcnt(0)" ::: "memory");
;     __syncthreads();
;     if (threadIdx.x == 0) {
;         unsigned* bar = b.bar;
;         __builtin_amdgcn_s_waitcnt(0);
;         unsigned nloc = b.st[0], nx = b.st[1];
;         if (nloc == 0u) { xcd_barrier_complete(bar, b.x, nloc, nx); b.st[0] = nloc; b.st[1] = nx; }
.LBB0_1191:
	s_waitcnt vmcnt(0)
	s_setprio 0
	s_barrier
	s_and_saveexec_b64 s[2:3], s[94:95]
	v_readlane_b32 s58, v254, 35
	s_xor_b64 s[30:31], exec, s[2:3]
	v_readlane_b32 s59, v254, 36
	s_cbranch_execz .LBB0_1244
	v_readlane_b32 s1, v254, 23
	s_waitcnt vmcnt(0) expcnt(0) lgkmcnt(0)
	s_nop 0
	v_mov_b32_e32 v2, s1
	ds_read_b32 v4, v2
	v_readlane_b32 s1, v254, 24
	s_waitcnt lgkmcnt(0)
	v_cmp_ne_u32_e32 vcc, 0, v4
	v_mov_b32_e32 v2, s1
	ds_read_b32 v2, v2
	s_cbranch_vccnz .LBB0_1207
	s_load_dwordx2 s[2:3], s[88:89], 0x4
	s_waitcnt lgkmcnt(0)
	s_mul_i32 s1, s2, s8
	s_mul_i32 s1, s1, s3
	s_mov_b32 s2, 1
	s_branch .LBB0_1195

; #define PG8_STAGEX(rs, bufoff, soff, voff) do { _Pragma("unroll") for (int _i = 0; _i < 2; ++_i) \
;         __builtin_amdgcn_raw_ptr_buffer_load_lds(rs, (LAS unsigned*)(lds + (bufoff) + ldsw + _i * 8192), 16, (voff)[_i], (soff), 0, 0); } while (0)
; #define PG8_LDA(dst, b, h) do { _Pragma("unroll") for (int m = 0; m < 4; ++m) _Pragma("unroll") for (int k = 0; k < 2; ++k) dst[m][k] = *(const LAS bf16x8*)(lds + PG8_SA(b, h) + aoff + m * 2048 + k * 1024); } while (0)
; #define PG8_LDB(dst, b, h) do { _Pragma("unroll") for (int n = 0; n < 2; ++n) _Pragma("unroll") for (int k = 0; k < 2; ++k) dst[n][k] = *(const LAS bf16x8*)(lds + PG8_SB(b, h) + boff + n * 2048 + k * 1024); } while (0)
; #define PG8_WAIT_V(n) asm volatile("s_waitcnt vmcnt(" #n ")" ::: "memory")
; #define PG8_WAIT_L(n) asm volatile("s_waitcnt lgkmcnt(" #n ")" ::: "memory")
; #define PG8_BAR __builtin_amdgcn_s_barrier()
; #define PG8_SCHED __builtin_amdgcn_sched_barrier(0)
;     ...
;             PG8_LDB(B0, 0, 0); PG8_LDB(B1, 0, 1); PG8_SCHED; PG8_LDA(At, 0, 0); PG8_STAGEX(rsA, PG8_SA(1, 1), a1 + hstepA, voffA);
;             PG8_WAIT_V(8); PG8_WAIT_L(0); PG8_BAR; PG8_MMA(0, 0, At, B0); PG8_MMA(0, 1, At, B1); PG8_BAR; PG8_SCHED;
;             PG8_LDA(At, 0, 1); PG8_STAGEX(rsB, PG8_SB(0, 0), b2, voffB); PG8_STAGEX(rsB, PG8_SB(0, 1), b2 + hstepB, voffB); PG8_STAGEX(rsA, PG8_SA(0, 0), a2, voffA);
;             PG8_WAIT_V(8); PG8_WAIT_L(0); PG8_BAR; PG8_MMA(1, 0, At, B0); PG8_MMA(1, 1, At, B1); PG8_BAR; PG8_SCHED;
.LBB0_1274:
	v_add_u32_e32 v142, 0x10000, v157
	v_add_u32_e32 v159, 0x14000, v157
	ds_read_b128 v[130:133], v142
	ds_read_b128 v[134:137], v142 offset:1024
	ds_read_b128 v[138:141], v142 offset:2048
	ds_read_b128 v[142:145], v142 offset:3072
	ds_read_b128 v[146:149], v159
	ds_read_b128 v[164:167], v159 offset:1024
	ds_read_b128 v[168:171], v159 offset:2048
	ds_read_b128 v[182:185], v159 offset:3072
	s_add_i32 s42, s62, 0xfff80080
	s_cmp_eq_u32 s67, 28
	s_cselect_b32 s70, s30, s42
	s_cselect_b32 s69, s31, s63
	s_or_b32 s68, s70, 0x80
	s_mov_b32 m0, s29
	ds_read_b128 v[186:189], v158
	ds_read_b128 v[190:193], v158 offset:1024
	ds_read_b128 v[194:197], v158 offset:2048
	ds_read_b128 v[198:201], v158 offset:3072
	ds_read_b128 v[202:205], v158 offset:4096
	ds_read_b128 v[206:209], v158 offset:5120
	ds_read_b128 v[210:213], v158 offset:6144
	ds_read_b128 v[214:217], v158 offset:7168
	buffer_load_dwordx4 v150, s[76:79], s62 offen lds
	s_mov_b32 m0, s35
	s_nop 0
	buffer_load_dwordx4 v152, s[76:79], s62 offen lds
	s_waitcnt vmcnt(8)
	s_waitcnt lgkmcnt(0)
	s_setprio 1
	s_barrier
	v_mfma_f32_16x16x32_bf16 v[126:129], v[130:133], v[186:189], v[126:129]
	v_mfma_f32_16x16x32_bf16 v[126:129], v[134:137], v[190:193], v[126:129]
	v_mfma_f32_16x16x32_bf16 v[122:125], v[142:145], v[190:193], v[122:125]
	v_mfma_f32_16x16x32_bf16 v[122:125], v[138:141], v[186:189], v[122:125]
	v_mfma_f32_16x16x32_bf16 v[114:117], v[138:141], v[194:197], v[114:117]
	v_mfma_f32_16x16x32_bf16 v[114:117], v[142:145], v[198:201], v[114:117]
	v_mfma_f32_16x16x32_bf16 v[118:121], v[134:137], v[198:201], v[118:121]
	v_mfma_f32_16x16x32_bf16 v[118:121], v[130:133], v[194:197], v[118:121]
	v_mfma_f32_16x16x32_bf16 v[110:113], v[130:133], v[202:205], v[110:113]
	v_mfma_f32_16x16x32_bf16 v[110:113], v[134:137], v[206:209], v[110:113]
	v_mfma_f32_16x16x32_bf16 v[106:109], v[142:145], v[206:209], v[106:109]
	v_mfma_f32_16x16x32_bf16 v[106:109], v[138:141], v[202:205], v[106:109]
	v_mfma_f32_16x16x32_bf16 v[98:101], v[138:141], v[210:213], v[98:101]
	v_mfma_f32_16x16x32_bf16 v[98:101], v[142:145], v[214:217], v[98:101]
	v_mfma_f32_16x16x32_bf16 v[102:105], v[134:137], v[214:217], v[102:105]
	v_mfma_f32_16x16x32_bf16 v[102:105], v[130:133], v[210:213], v[102:105]
	v_mfma_f32_16x16x32_bf16 v[62:65], v[146:149], v[186:189], v[62:65]
	v_mfma_f32_16x16x32_bf16 v[62:65], v[164:167], v[190:193], v[62:65]
	v_mfma_f32_16x16x32_bf16 v[58:61], v[182:185], v[190:193], v[58:61]
	v_mfma_f32_16x16x32_bf16 v[58:61], v[168:171], v[186:189], v[58:61]
	v_mfma_f32_16x16x32_bf16 v[50:53], v[168:171], v[194:197], v[50:53]
	v_mfma_f32_16x16x32_bf16 v[50:53], v[182:185], v[198:201], v[50:53]
	v_mfma_f32_16x16x32_bf16 v[54:57], v[164:167], v[198:201], v[54:57]
	v_mfma_f32_16x16x32_bf16 v[54:57], v[146:149], v[194:197], v[54:57]
	v_mfma_f32_16x16x32_bf16 v[46:49], v[146:149], v[202:205], v[46:49]
	v_mfma_f32_16x16x32_bf16 v[46:49], v[164:167], v[206:209], v[46:49]
	v_mfma_f32_16x16x32_bf16 v[42:45], v[182:185], v[206:209], v[42:45]
	v_mfma_f32_16x16x32_bf16 v[42:45], v[168:171], v[202:205], v[42:45]
	v_mfma_f32_16x16x32_bf16 v[34:37], v[168:171], v[210:213], v[34:37]
	v_mfma_f32_16x16x32_bf16 v[34:37], v[182:185], v[214:217], v[34:37]
	v_mfma_f32_16x16x32_bf16 v[38:41], v[164:167], v[214:217], v[38:41]
	v_mfma_f32_16x16x32_bf16 v[38:41], v[146:149], v[210:213], v[38:41]
	s_barrier
	s_setprio 0
	s_mov_b32 m0, s16
	s_mov_b32 s42, s78
	s_mov_b32 s43, s79
	ds_read_b128 v[186:189], v158 offset:16384
	ds_read_b128 v[190:193], v158 offset:17408
	ds_read_b128 v[194:197], v158 offset:18432
	ds_read_b128 v[198:201], v158 offset:19456
	ds_read_b128 v[202:205], v158 offset:20480
	ds_read_b128 v[206:209], v158 offset:21504
	ds_read_b128 v[210:213], v158 offset:22528
	ds_read_b128 v[214:217], v158 offset:23552
	buffer_load_dwordx4 v151, s[40:43], s69 offen lds
	s_mov_b32 m0, s17
	s_add_i32 s71, s69, 0x80000
	buffer_load_dwordx4 v153, s[40:43], s69 offen lds
	s_mov_b32 m0, s18
	s_nop 0
	buffer_load_dwordx4 v151, s[40:43], s71 offen lds
	s_mov_b32 m0, s19
	s_nop 0
	buffer_load_dwordx4 v153, s[40:43], s71 offen lds
	s_mov_b32 m0, s15
	s_nop 0
	buffer_load_dwordx4 v150, s[76:79], s70 offen lds
	s_mov_b32 m0, s20
	s_nop 0
	buffer_load_dwordx4 v152, s[76:79], s70 offen lds
	s_waitcnt vmcnt(8)
	s_waitcnt lgkmcnt(0)
	s_setprio 1
	s_barrier
	v_mfma_f32_16x16x32_bf16 v[94:97], v[130:133], v[186:189], v[94:97]
	v_mfma_f32_16x16x32_bf16 v[94:97], v[134:137], v[190:193], v[94:97]
	v_mfma_f32_16x16x32_bf16 v[90:93], v[142:145], v[190:193], v[90:93]
	v_mfma_f32_16x16x32_bf16 v[90:93], v[138:141], v[186:189], v[90:93]
	v_mfma_f32_16x16x32_bf16 v[82:85], v[138:141], v[194:197], v[82:85]
	v_mfma_f32_16x16x32_bf16 v[82:85], v[142:145], v[198:201], v[82:85]
	v_mfma_f32_16x16x32_bf16 v[86:89], v[134:137], v[198:201], v[86:89]
	v_mfma_f32_16x16x32_bf16 v[86:89], v[130:133], v[194:197], v[86:89]
	v_mfma_f32_16x16x32_bf16 v[78:81], v[130:133], v[202:205], v[78:81]
	v_mfma_f32_16x16x32_bf16 v[78:81], v[134:137], v[206:209], v[78:81]
	v_mfma_f32_16x16x32_bf16 v[74:77], v[142:145], v[206:209], v[74:77]
	v_mfma_f32_16x16x32_bf16 v[74:77], v[138:141], v[202:205], v[74:77]
	v_mfma_f32_16x16x32_bf16 v[66:69], v[138:141], v[210:213], v[66:69]
	v_mfma_f32_16x16x32_bf16 v[66:69], v[142:145], v[214:217], v[66:69]
	v_mfma_f32_16x16x32_bf16 v[70:73], v[134:137], v[214:217], v[70:73]
	v_mfma_f32_16x16x32_bf16 v[70:73], v[130:133], v[210:213], v[70:73]
	v_mfma_f32_16x16x32_bf16 v[30:33], v[146:149], v[186:189], v[30:33]
	v_mfma_f32_16x16x32_bf16 v[30:33], v[164:167], v[190:193], v[30:33]
	v_mfma_f32_16x16x32_bf16 v[26:29], v[182:185], v[190:193], v[26:29]
	v_mfma_f32_16x16x32_bf16 v[26:29], v[168:171], v[186:189], v[26:29]
	v_mfma_f32_16x16x32_bf16 v[18:21], v[168:171], v[194:197], v[18:21]
	v_mfma_f32_16x16x32_bf16 v[18:21], v[182:185], v[198:201], v[18:21]
	v_mfma_f32_16x16x32_bf16 v[22:25], v[164:167], v[198:201], v[22:25]
	v_mfma_f32_16x16x32_bf16 v[22:25], v[146:149], v[194:197], v[22:25]
	v_mfma_f32_16x16x32_bf16 v[14:17], v[146:149], v[202:205], v[14:17]
	v_mfma_f32_16x16x32_bf16 v[14:17], v[164:167], v[206:209], v[14:17]
	v_mfma_f32_16x16x32_bf16 v[10:13], v[182:185], v[206:209], v[10:13]
	v_mfma_f32_16x16x32_bf16 v[10:13], v[168:171], v[202:205], v[10:13]
	v_mfma_f32_16x16x32_bf16 v[2:5], v[168:171], v[210:213], v[2:5]
	v_mfma_f32_16x16x32_bf16 v[2:5], v[182:185], v[214:217], v[2:5]
	v_mfma_f32_16x16x32_bf16 v[6:9], v[164:167], v[214:217], v[6:9]
	v_mfma_f32_16x16x32_bf16 v[6:9], v[146:149], v[210:213], v[6:9]
	s_barrier
; #define PG8_STAGEX(rs, bufoff, soff, voff) do { _Pragma("unroll") for (int _i = 0; _i < 2; ++_i) \
;         __builtin_amdgcn_raw_ptr_buffer_load_lds(rs, (LAS unsigned*)(lds + (bufoff) + ldsw + _i * 8192), 16, (voff)[_i], (soff), 0, 0); } while (0)
; #define PG8_WAIT_V(n) asm volatile("s_waitcnt vmcnt(" #n ")" ::: "memory")
; #define PG8_WAIT_L(n) asm volatile("s_waitcnt lgkmcnt(" #n ")" ::: "memory")
; #define PG8_BAR __builtin_amdgcn_s_barrier()
;     ...
;             PG8_LDB(B0, 1, 0); PG8_LDB(B1, 1, 1); PG8_SCHED; PG8_LDA(At, 1, 0); PG8_STAGEX(rsA, PG8_SA(0, 1), a2 + hstepA, voffA);
;             PG8_WAIT_V(8); PG8_WAIT_L(0); PG8_BAR; PG8_MMA(0, 0, At, B0); PG8_MMA(0, 1, At, B1); PG8_BAR; PG8_SCHED;
;             PG8_LDA(At, 1, 1); PG8_STAGEX(rsB, PG8_SB(1, 0), b3, voffB); PG8_STAGEX(rsB, PG8_SB(1, 1), b3 + hstepB, voffB); PG8_STAGEX(rsA, PG8_SA(1, 0), a3, voffA);
;             PG8_WAIT_V(8); PG8_WAIT_L(0); PG8_BAR; PG8_MMA(1, 0, At, B0); PG8_MMA(1, 1, At, B1); PG8_BAR; PG8_SCHED;
;         }
;         } else {
;             const bool w0 = (QV == 2) || (wr == 0);
; #pragma nounroll
;             for (int t = 0; t < nt; t += 2) {
;                 const bool last = (t == nt - 2);
;                 const unsigned a1 = cA + (unsigned)(t + 1) * kstep;
;                 const unsigned a2 = last ? nA : cA + (unsigned)(t + 2) * kstep, b2 = last ? nB : cB + (unsigned)(t + 2) * kstep;
;                 const unsigned a3 = a2 + kstep, b3 = b2 + kstep;
;                 if (w0) { PG8_LDB(B0, 0, 0); PG8_LDB(B1, 0, 1); PG8_SCHED; PG8_LDA(At, 0, 0); }
;                 PG8_WAIT_L(0); PG8_BAR; if (w0) { PG8_MMA(0, 0, At, B0); PG8_MMA(0, 1, At, B1); } PG8_BAR; PG8_SCHED;
;                 PG8_STAGEX(rsB, PG8_SB(0, 0), b2, voffB); PG8_STAGEX(rsB, PG8_SB(0, 1), b2 + hstepB, voffB); PG8_STAGEX(rsA, PG8_SA(0, 0), a2, voffA);
;                 PG8_WAIT_V(6); PG8_BAR; PG8_BAR; PG8_SCHED;
;                 if (w0) { PG8_LDB(B0, 1, 0); PG8_LDB(B1, 1, 1); PG8_SCHED; PG8_LDA(At, 1, 0); }
;                 PG8_WAIT_L(0); PG8_BAR; if (w0) { PG8_MMA(0, 0, At, B0); PG8_MMA(0, 1, At, B1); } PG8_BAR; PG8_SCHED;
;                 PG8_STAGEX(rsB, PG8_SB(1, 0), b3, voffB); PG8_STAGEX(rsB, PG8_SB(1, 1), b3 + hstepB, voffB); PG8_STAGEX(rsA, PG8_SA(1, 0), a3, voffA);
;                 PG8_WAIT_V(6); PG8_BAR; PG8_BAR; PG8_SCHED;
;             }
;         }
;         if (wr == 0) PG8_BAR;
	s_setprio 0
	v_add_u32_e32 v142, 0x18000, v157
	v_add_u32_e32 v159, 0x1c000, v157
	ds_read_b128 v[130:133], v142
	ds_read_b128 v[134:137], v142 offset:1024
	ds_read_b128 v[138:141], v142 offset:2048
	ds_read_b128 v[142:145], v142 offset:3072
	ds_read_b128 v[146:149], v159
	ds_read_b128 v[164:167], v159 offset:1024
	ds_read_b128 v[168:171], v159 offset:2048
	ds_read_b128 v[182:185], v159 offset:3072
	s_add_i32 s70, s70, 0x80000
	s_mov_b32 m0, s21
	ds_read_b128 v[186:189], v158 offset:32768
	ds_read_b128 v[190:193], v158 offset:33792
	ds_read_b128 v[194:197], v158 offset:34816
	ds_read_b128 v[198:201], v158 offset:35840
	ds_read_b128 v[202:205], v158 offset:36864
	ds_read_b128 v[206:209], v158 offset:37888
	ds_read_b128 v[210:213], v158 offset:38912
	ds_read_b128 v[214:217], v158 offset:39936
	buffer_load_dwordx4 v150, s[76:79], s70 offen lds
	s_mov_b32 m0, s22
	s_nop 0
	buffer_load_dwordx4 v152, s[76:79], s70 offen lds
	s_waitcnt vmcnt(8)
	s_waitcnt lgkmcnt(0)
	s_setprio 1
	s_barrier
	v_mfma_f32_16x16x32_bf16 v[126:129], v[130:133], v[186:189], v[126:129]
	v_mfma_f32_16x16x32_bf16 v[126:129], v[134:137], v[190:193], v[126:129]
	v_mfma_f32_16x16x32_bf16 v[122:125], v[142:145], v[190:193], v[122:125]
	v_mfma_f32_16x16x32_bf16 v[122:125], v[138:141], v[186:189], v[122:125]
	v_mfma_f32_16x16x32_bf16 v[114:117], v[138:141], v[194:197], v[114:117]
	v_mfma_f32_16x16x32_bf16 v[114:117], v[142:145], v[198:201], v[114:117]
	v_mfma_f32_16x16x32_bf16 v[118:121], v[134:137], v[198:201], v[118:121]
	v_mfma_f32_16x16x32_bf16 v[118:121], v[130:133], v[194:197], v[118:121]
	v_mfma_f32_16x16x32_bf16 v[110:113], v[130:133], v[202:205], v[110:113]
	v_mfma_f32_16x16x32_bf16 v[110:113], v[134:137], v[206:209], v[110:113]
	v_mfma_f32_16x16x32_bf16 v[106:109], v[142:145], v[206:209], v[106:109]
	v_mfma_f32_16x16x32_bf16 v[106:109], v[138:141], v[202:205], v[106:109]
	v_mfma_f32_16x16x32_bf16 v[98:101], v[138:141], v[210:213], v[98:101]
	v_mfma_f32_16x16x32_bf16 v[98:101], v[142:145], v[214:217], v[98:101]
	v_mfma_f32_16x16x32_bf16 v[102:105], v[134:137], v[214:217], v[102:105]
	v_mfma_f32_16x16x32_bf16 v[102:105], v[130:133], v[210:213], v[102:105]
	v_mfma_f32_16x16x32_bf16 v[62:65], v[146:149], v[186:189], v[62:65]
	v_mfma_f32_16x16x32_bf16 v[62:65], v[164:167], v[190:193], v[62:65]
	v_mfma_f32_16x16x32_bf16 v[58:61], v[182:185], v[190:193], v[58:61]
	v_mfma_f32_16x16x32_bf16 v[58:61], v[168:171], v[186:189], v[58:61]
	v_mfma_f32_16x16x32_bf16 v[50:53], v[168:171], v[194:197], v[50:53]
	v_mfma_f32_16x16x32_bf16 v[50:53], v[182:185], v[198:201], v[50:53]
	v_mfma_f32_16x16x32_bf16 v[54:57], v[164:167], v[198:201], v[54:57]
	v_mfma_f32_16x16x32_bf16 v[54:57], v[146:149], v[194:197], v[54:57]
	v_mfma_f32_16x16x32_bf16 v[46:49], v[146:149], v[202:205], v[46:49]
	v_mfma_f32_16x16x32_bf16 v[46:49], v[164:167], v[206:209], v[46:49]
	v_mfma_f32_16x16x32_bf16 v[42:45], v[182:185], v[206:209], v[42:45]
	v_mfma_f32_16x16x32_bf16 v[42:45], v[168:171], v[202:205], v[42:45]
	v_mfma_f32_16x16x32_bf16 v[34:37], v[168:171], v[210:213], v[34:37]
	v_mfma_f32_16x16x32_bf16 v[34:37], v[182:185], v[214:217], v[34:37]
	v_mfma_f32_16x16x32_bf16 v[38:41], v[164:167], v[214:217], v[38:41]
	v_mfma_f32_16x16x32_bf16 v[38:41], v[146:149], v[210:213], v[38:41]
	s_barrier
	s_setprio 0
	s_mov_b32 m0, s23
	s_or_b32 s70, s69, 0x80
	ds_read_b128 v[186:189], v158 offset:49152
	ds_read_b128 v[190:193], v158 offset:50176
	ds_read_b128 v[194:197], v158 offset:51200
	ds_read_b128 v[198:201], v158 offset:52224
	ds_read_b128 v[202:205], v158 offset:53248
	ds_read_b128 v[206:209], v158 offset:54272
	ds_read_b128 v[210:213], v158 offset:55296
	ds_read_b128 v[214:217], v158 offset:56320
	buffer_load_dwordx4 v151, s[40:43], s70 offen lds
	s_mov_b32 m0, s24
	s_add_i32 s69, s69, 0x80080
	buffer_load_dwordx4 v153, s[40:43], s70 offen lds
	s_mov_b32 m0, s27
	s_nop 0
	buffer_load_dwordx4 v151, s[40:43], s69 offen lds
	s_mov_b32 m0, s28
	s_nop 0
	buffer_load_dwordx4 v153, s[40:43], s69 offen lds
	s_mov_b32 m0, s25
	s_nop 0
	buffer_load_dwordx4 v150, s[76:79], s68 offen lds
	s_mov_b32 m0, s26
	s_nop 0
	buffer_load_dwordx4 v152, s[76:79], s68 offen lds
	s_waitcnt vmcnt(8)
	s_waitcnt lgkmcnt(0)
	s_setprio 1
	s_barrier
	v_mfma_f32_16x16x32_bf16 v[94:97], v[130:133], v[186:189], v[94:97]
	v_mfma_f32_16x16x32_bf16 v[94:97], v[134:137], v[190:193], v[94:97]
	v_mfma_f32_16x16x32_bf16 v[90:93], v[142:145], v[190:193], v[90:93]
	v_mfma_f32_16x16x32_bf16 v[90:93], v[138:141], v[186:189], v[90:93]
	v_mfma_f32_16x16x32_bf16 v[82:85], v[138:141], v[194:197], v[82:85]
	v_mfma_f32_16x16x32_bf16 v[82:85], v[142:145], v[198:201], v[82:85]
	v_mfma_f32_16x16x32_bf16 v[86:89], v[134:137], v[198:201], v[86:89]
	v_mfma_f32_16x16x32_bf16 v[86:89], v[130:133], v[194:197], v[86:89]
	v_mfma_f32_16x16x32_bf16 v[78:81], v[130:133], v[202:205], v[78:81]
	v_mfma_f32_16x16x32_bf16 v[78:81], v[134:137], v[206:209], v[78:81]
	v_mfma_f32_16x16x32_bf16 v[74:77], v[142:145], v[206:209], v[74:77]
	v_mfma_f32_16x16x32_bf16 v[74:77], v[138:141], v[202:205], v[74:77]
	v_mfma_f32_16x16x32_bf16 v[66:69], v[138:141], v[210:213], v[66:69]
	v_mfma_f32_16x16x32_bf16 v[66:69], v[142:145], v[214:217], v[66:69]
	v_mfma_f32_16x16x32_bf16 v[70:73], v[134:137], v[214:217], v[70:73]
	v_mfma_f32_16x16x32_bf16 v[70:73], v[130:133], v[210:213], v[70:73]
	v_mfma_f32_16x16x32_bf16 v[30:33], v[146:149], v[186:189], v[30:33]
	v_mfma_f32_16x16x32_bf16 v[30:33], v[164:167], v[190:193], v[30:33]
	v_mfma_f32_16x16x32_bf16 v[26:29], v[182:185], v[190:193], v[26:29]
	v_mfma_f32_16x16x32_bf16 v[26:29], v[168:171], v[186:189], v[26:29]
	v_mfma_f32_16x16x32_bf16 v[18:21], v[168:171], v[194:197], v[18:21]
	v_mfma_f32_16x16x32_bf16 v[18:21], v[182:185], v[198:201], v[18:21]
	v_mfma_f32_16x16x32_bf16 v[22:25], v[164:167], v[198:201], v[22:25]
	v_mfma_f32_16x16x32_bf16 v[22:25], v[146:149], v[194:197], v[22:25]
	v_mfma_f32_16x16x32_bf16 v[14:17], v[146:149], v[202:205], v[14:17]
	v_mfma_f32_16x16x32_bf16 v[14:17], v[164:167], v[206:209], v[14:17]
	v_mfma_f32_16x16x32_bf16 v[10:13], v[182:185], v[206:209], v[10:13]
	v_mfma_f32_16x16x32_bf16 v[10:13], v[168:171], v[202:205], v[10:13]
	v_mfma_f32_16x16x32_bf16 v[2:5], v[168:171], v[210:213], v[2:5]
	v_mfma_f32_16x16x32_bf16 v[2:5], v[182:185], v[214:217], v[2:5]
	v_mfma_f32_16x16x32_bf16 v[6:9], v[164:167], v[214:217], v[6:9]
	v_mfma_f32_16x16x32_bf16 v[6:9], v[146:149], v[210:213], v[6:9]
	s_barrier
	s_setprio 0
	s_add_i32 s67, s67, 2
	s_addk_i32 s62, 0x100
	s_addk_i32 s63, 0x100
	s_cmp_gt_u32 s67, 29
	s_cbranch_scc0 .LBB0_1274
	s_and_b64 vcc, exec, s[50:51]
	s_cbranch_vccz .LBB0_1277
	s_barrier
	s_setprio 1

; __device__ __forceinline__ unsigned xb_ld(unsigned* p)              { return __hip_atomic_load(p, __ATOMIC_RELAXED, __HIP_MEMORY_SCOPE_AGENT); }
; __device__ __forceinline__ void xcd_barrier_complete(unsigned* bar, unsigned x, unsigned& nloc, unsigned& nx) {
;     const unsigned G = gridDim.x * gridDim.y * gridDim.z;
;     unsigned sum, cnt, mine, sp = 0u;
;     for (;;) {
;         sum = 0u; cnt = 0u; mine = 0u;
; #pragma unroll
;         for (unsigned j = 0; j < 16; ++j) { const unsigned c = xb_ld(&bar[XB_XCNT(j)]); sum += c; cnt += (c > 0u) ? 1u : 0u; mine = (j == x) ? c : mine; }
;         if (sum == G) break;
;         __builtin_amdgcn_s_sleep(1);
;         if ((++sp & 255u) == 0u) { if (xb_ld(&bar[XB_TMO])) break; if (sp > XB_SPIN_CAP) { atomicAdd(&bar[XB_TMO], 1u); break; } }
;     }
;     nloc = mine > 0u ? mine : 1u; nx = cnt > 0u ? cnt : 1u;
; }
; __device__ __forceinline__ void xcd_barrier(const XcdBarrier& b) {
;     asm volatile("s_waitcnt vmcnt(0)" ::: "memory");
;     __syncthreads();
;     if (threadIdx.x == 0) {
;         unsigned* bar = b.bar;
;         __builtin_amdgcn_s_waitcnt(0);
;         unsigned nloc = b.st[0], nx = b.st[1];
;         if (nloc == 0u) { xcd_barrier_complete(bar, b.x, nloc, nx); b.st[0] = nloc; b.st[1] = nx; }
.LBB0_1312:
	s_waitcnt vmcnt(0)
	s_setprio 0
	s_barrier
	s_and_saveexec_b64 s[30:31], s[94:95]
	v_readlane_b32 s58, v254, 35
	v_readlane_b32 s59, v254, 36
	s_mov_b32 s62, 0xff61b1e6
	s_mov_b32 s63, 0x41000000
	s_cbranch_execz .LBB0_1364
	v_readlane_b32 s1, v254, 23
	s_waitcnt vmcnt(0) expcnt(0) lgkmcnt(0)
	s_nop 0
	v_mov_b32_e32 v2, s1
	ds_read_b32 v4, v2
	v_readlane_b32 s1, v254, 24
	s_waitcnt lgkmcnt(0)
	v_cmp_ne_u32_e32 vcc, 0, v4
	v_mov_b32_e32 v2, s1
	ds_read_b32 v2, v2
	s_cbranch_vccnz .LBB0_1328
	s_load_dwordx2 s[2:3], s[88:89], 0x4
	s_waitcnt lgkmcnt(0)
	s_mul_i32 s1, s2, s8
	s_mul_i32 s1, s1, s3
	s_mov_b32 s2, 1
	s_branch .LBB0_1316

; #define PG8_STAGEX(rs, bufoff, soff, voff) do { _Pragma("unroll") for (int _i = 0; _i < 2; ++_i) \
;         __builtin_amdgcn_raw_ptr_buffer_load_lds(rs, (LAS unsigned*)(lds + (bufoff) + ldsw + _i * 8192), 16, (voff)[_i], (soff), 0, 0); } while (0)
; #define PG8_LDA(dst, b, h) do { _Pragma("unroll") for (int m = 0; m < 4; ++m) _Pragma("unroll") for (int k = 0; k < 2; ++k) dst[m][k] = *(const LAS bf16x8*)(lds + PG8_SA(b, h) + aoff + m * 2048 + k * 1024); } while (0)
; #define PG8_LDB(dst, b, h) do { _Pragma("unroll") for (int n = 0; n < 2; ++n) _Pragma("unroll") for (int k = 0; k < 2; ++k) dst[n][k] = *(const LAS bf16x8*)(lds + PG8_SB(b, h) + boff + n * 2048 + k * 1024); } while (0)
; #define PG8_WAIT_V(n) asm volatile("s_waitcnt vmcnt(" #n ")" ::: "memory")
; #define PG8_WAIT_L(n) asm volatile("s_waitcnt lgkmcnt(" #n ")" ::: "memory")
; #define PG8_BAR __builtin_amdgcn_s_barrier()
; #define PG8_SCHED __builtin_amdgcn_sched_barrier(0)
;     ...
;             PG8_LDB(B0, 0, 0); PG8_LDB(B1, 0, 1); PG8_SCHED; PG8_LDA(At, 0, 0); PG8_STAGEX(rsA, PG8_SA(1, 1), a1 + hstepA, voffA);
;             PG8_WAIT_V(8); PG8_WAIT_L(0); PG8_BAR; PG8_MMA(0, 0, At, B0); PG8_MMA(0, 1, At, B1); PG8_BAR; PG8_SCHED;
;             PG8_LDA(At, 0, 1); PG8_STAGEX(rsB, PG8_SB(0, 0), b2, voffB); PG8_STAGEX(rsB, PG8_SB(0, 1), b2 + hstepB, voffB); PG8_STAGEX(rsA, PG8_SA(0, 0), a2, voffA);
;             PG8_WAIT_V(8); PG8_WAIT_L(0); PG8_BAR; PG8_MMA(1, 0, At, B0); PG8_MMA(1, 1, At, B1); PG8_BAR; PG8_SCHED;
.LBB0_1377:
	v_add_u32_e32 v142, 0x10000, v185
	v_add_u32_e32 v158, 0x14000, v185
	ds_read_b128 v[130:133], v142
	ds_read_b128 v[134:137], v142 offset:1024
	ds_read_b128 v[138:141], v142 offset:2048
	ds_read_b128 v[142:145], v142 offset:3072
	ds_read_b128 v[146:149], v158
	ds_read_b128 v[150:153], v158 offset:1024
	ds_read_b128 v[154:157], v158 offset:2048
	ds_read_b128 v[158:161], v158 offset:3072
	s_add_i32 s50, s43, 0xfff40080
	s_cmp_eq_u32 s60, 12
	s_cselect_b32 s63, s30, s50
	s_cselect_b32 s62, s31, s59
	s_add_i32 s61, s63, 0x80
	s_mov_b32 m0, s23
	ds_read_b128 v[162:165], v186
	ds_read_b128 v[166:169], v186 offset:1024
	ds_read_b128 v[190:193], v186 offset:2048
	ds_read_b128 v[194:197], v186 offset:3072
	ds_read_b128 v[198:201], v186 offset:4096
	ds_read_b128 v[202:205], v186 offset:5120
	ds_read_b128 v[206:209], v186 offset:6144
	ds_read_b128 v[210:213], v186 offset:7168
	buffer_load_dwordx4 v173, s[76:79], s43 offen lds
	s_mov_b32 m0, s24
	s_nop 0
	buffer_load_dwordx4 v178, s[76:79], s43 offen lds
	s_waitcnt vmcnt(8)
	s_waitcnt lgkmcnt(0)
	s_setprio 1
	s_barrier
	v_mfma_f32_16x16x32_bf16 v[126:129], v[130:133], v[162:165], v[126:129]
	v_mfma_f32_16x16x32_bf16 v[126:129], v[134:137], v[166:169], v[126:129]
	v_mfma_f32_16x16x32_bf16 v[122:125], v[142:145], v[166:169], v[122:125]
	v_mfma_f32_16x16x32_bf16 v[122:125], v[138:141], v[162:165], v[122:125]
	v_mfma_f32_16x16x32_bf16 v[114:117], v[138:141], v[190:193], v[114:117]
	v_mfma_f32_16x16x32_bf16 v[114:117], v[142:145], v[194:197], v[114:117]
	v_mfma_f32_16x16x32_bf16 v[118:121], v[134:137], v[194:197], v[118:121]
	v_mfma_f32_16x16x32_bf16 v[118:121], v[130:133], v[190:193], v[118:121]
	v_mfma_f32_16x16x32_bf16 v[110:113], v[130:133], v[198:201], v[110:113]
	v_mfma_f32_16x16x32_bf16 v[110:113], v[134:137], v[202:205], v[110:113]
	v_mfma_f32_16x16x32_bf16 v[106:109], v[142:145], v[202:205], v[106:109]
	v_mfma_f32_16x16x32_bf16 v[106:109], v[138:141], v[198:201], v[106:109]
	v_mfma_f32_16x16x32_bf16 v[98:101], v[138:141], v[206:209], v[98:101]
	v_mfma_f32_16x16x32_bf16 v[98:101], v[142:145], v[210:213], v[98:101]
	v_mfma_f32_16x16x32_bf16 v[102:105], v[134:137], v[210:213], v[102:105]
	v_mfma_f32_16x16x32_bf16 v[102:105], v[130:133], v[206:209], v[102:105]
	v_mfma_f32_16x16x32_bf16 v[94:97], v[146:149], v[162:165], v[94:97]
	v_mfma_f32_16x16x32_bf16 v[94:97], v[150:153], v[166:169], v[94:97]
	v_mfma_f32_16x16x32_bf16 v[90:93], v[158:161], v[166:169], v[90:93]
	v_mfma_f32_16x16x32_bf16 v[90:93], v[154:157], v[162:165], v[90:93]
	v_mfma_f32_16x16x32_bf16 v[82:85], v[154:157], v[190:193], v[82:85]
	v_mfma_f32_16x16x32_bf16 v[82:85], v[158:161], v[194:197], v[82:85]
	v_mfma_f32_16x16x32_bf16 v[86:89], v[150:153], v[194:197], v[86:89]
	v_mfma_f32_16x16x32_bf16 v[86:89], v[146:149], v[190:193], v[86:89]
	v_mfma_f32_16x16x32_bf16 v[78:81], v[146:149], v[198:201], v[78:81]
	v_mfma_f32_16x16x32_bf16 v[78:81], v[150:153], v[202:205], v[78:81]
	v_mfma_f32_16x16x32_bf16 v[74:77], v[158:161], v[202:205], v[74:77]
	v_mfma_f32_16x16x32_bf16 v[74:77], v[154:157], v[198:201], v[74:77]
	v_mfma_f32_16x16x32_bf16 v[66:69], v[154:157], v[206:209], v[66:69]
	v_mfma_f32_16x16x32_bf16 v[66:69], v[158:161], v[210:213], v[66:69]
	v_mfma_f32_16x16x32_bf16 v[70:73], v[150:153], v[210:213], v[70:73]
	v_mfma_f32_16x16x32_bf16 v[70:73], v[146:149], v[206:209], v[70:73]
	s_barrier
	s_setprio 0
	s_mov_b32 m0, s7
	s_mov_b32 s50, s78
	s_mov_b32 s51, s79
	ds_read_b128 v[162:165], v186 offset:16384
	ds_read_b128 v[166:169], v186 offset:17408
	ds_read_b128 v[190:193], v186 offset:18432
	ds_read_b128 v[194:197], v186 offset:19456
	ds_read_b128 v[198:201], v186 offset:20480
	ds_read_b128 v[202:205], v186 offset:21504
	ds_read_b128 v[206:209], v186 offset:22528
	ds_read_b128 v[210:213], v186 offset:23552
	buffer_load_dwordx4 v177, s[48:51], s62 offen lds
	s_mov_b32 m0, s11
	s_add_i32 s64, s62, 0x40000
	buffer_load_dwordx4 v179, s[48:51], s62 offen lds
	s_mov_b32 m0, s12
	s_nop 0
	buffer_load_dwordx4 v177, s[48:51], s64 offen lds
	s_mov_b32 m0, s13
	s_nop 0
	buffer_load_dwordx4 v179, s[48:51], s64 offen lds
	s_mov_b32 m0, s5
	s_nop 0
	buffer_load_dwordx4 v173, s[76:79], s63 offen lds
	s_mov_b32 m0, s14
	s_nop 0
	buffer_load_dwordx4 v178, s[76:79], s63 offen lds
	s_waitcnt vmcnt(8)
	s_waitcnt lgkmcnt(0)
	s_setprio 1
	s_barrier
	v_mfma_f32_16x16x32_bf16 v[62:65], v[130:133], v[162:165], v[62:65]
	v_mfma_f32_16x16x32_bf16 v[62:65], v[134:137], v[166:169], v[62:65]
	v_mfma_f32_16x16x32_bf16 v[58:61], v[142:145], v[166:169], v[58:61]
	v_mfma_f32_16x16x32_bf16 v[58:61], v[138:141], v[162:165], v[58:61]
	v_mfma_f32_16x16x32_bf16 v[50:53], v[138:141], v[190:193], v[50:53]
	v_mfma_f32_16x16x32_bf16 v[50:53], v[142:145], v[194:197], v[50:53]
	v_mfma_f32_16x16x32_bf16 v[54:57], v[134:137], v[194:197], v[54:57]
	v_mfma_f32_16x16x32_bf16 v[54:57], v[130:133], v[190:193], v[54:57]
	v_mfma_f32_16x16x32_bf16 v[46:49], v[130:133], v[198:201], v[46:49]
	v_mfma_f32_16x16x32_bf16 v[46:49], v[134:137], v[202:205], v[46:49]
	v_mfma_f32_16x16x32_bf16 v[42:45], v[142:145], v[202:205], v[42:45]
	v_mfma_f32_16x16x32_bf16 v[42:45], v[138:141], v[198:201], v[42:45]
	v_mfma_f32_16x16x32_bf16 v[34:37], v[138:141], v[206:209], v[34:37]
	v_mfma_f32_16x16x32_bf16 v[34:37], v[142:145], v[210:213], v[34:37]
	v_mfma_f32_16x16x32_bf16 v[38:41], v[134:137], v[210:213], v[38:41]
	v_mfma_f32_16x16x32_bf16 v[38:41], v[130:133], v[206:209], v[38:41]
	v_mfma_f32_16x16x32_bf16 v[30:33], v[146:149], v[162:165], v[30:33]
	v_mfma_f32_16x16x32_bf16 v[30:33], v[150:153], v[166:169], v[30:33]
	v_mfma_f32_16x16x32_bf16 v[26:29], v[158:161], v[166:169], v[26:29]
	v_mfma_f32_16x16x32_bf16 v[26:29], v[154:157], v[162:165], v[26:29]
	v_mfma_f32_16x16x32_bf16 v[18:21], v[154:157], v[190:193], v[18:21]
	v_mfma_f32_16x16x32_bf16 v[18:21], v[158:161], v[194:197], v[18:21]
	v_mfma_f32_16x16x32_bf16 v[22:25], v[150:153], v[194:197], v[22:25]
	v_mfma_f32_16x16x32_bf16 v[22:25], v[146:149], v[190:193], v[22:25]
	v_mfma_f32_16x16x32_bf16 v[14:17], v[146:149], v[198:201], v[14:17]
	v_mfma_f32_16x16x32_bf16 v[14:17], v[150:153], v[202:205], v[14:17]
	v_mfma_f32_16x16x32_bf16 v[10:13], v[158:161], v[202:205], v[10:13]
	v_mfma_f32_16x16x32_bf16 v[10:13], v[154:157], v[198:201], v[10:13]
	v_mfma_f32_16x16x32_bf16 v[2:5], v[154:157], v[206:209], v[2:5]
	v_mfma_f32_16x16x32_bf16 v[2:5], v[158:161], v[210:213], v[2:5]
	v_mfma_f32_16x16x32_bf16 v[6:9], v[150:153], v[210:213], v[6:9]
	v_mfma_f32_16x16x32_bf16 v[6:9], v[146:149], v[206:209], v[6:9]
	s_barrier
; #define PG8_STAGEX(rs, bufoff, soff, voff) do { _Pragma("unroll") for (int _i = 0; _i < 2; ++_i) \
;         __builtin_amdgcn_raw_ptr_buffer_load_lds(rs, (LAS unsigned*)(lds + (bufoff) + ldsw + _i * 8192), 16, (voff)[_i], (soff), 0, 0); } while (0)
; #define PG8_WAIT_V(n) asm volatile("s_waitcnt vmcnt(" #n ")" ::: "memory")
; #define PG8_WAIT_L(n) asm volatile("s_waitcnt lgkmcnt(" #n ")" ::: "memory")
; #define PG8_BAR __builtin_amdgcn_s_barrier()
;     ...
;             PG8_LDB(B0, 1, 0); PG8_LDB(B1, 1, 1); PG8_SCHED; PG8_LDA(At, 1, 0); PG8_STAGEX(rsA, PG8_SA(0, 1), a2 + hstepA, voffA);
;             PG8_WAIT_V(8); PG8_WAIT_L(0); PG8_BAR; PG8_MMA(0, 0, At, B0); PG8_MMA(0, 1, At, B1); PG8_BAR; PG8_SCHED;
;             PG8_LDA(At, 1, 1); PG8_STAGEX(rsB, PG8_SB(1, 0), b3, voffB); PG8_STAGEX(rsB, PG8_SB(1, 1), b3 + hstepB, voffB); PG8_STAGEX(rsA, PG8_SA(1, 0), a3, voffA);
;             PG8_WAIT_V(8); PG8_WAIT_L(0); PG8_BAR; PG8_MMA(1, 0, At, B0); PG8_MMA(1, 1, At, B1); PG8_BAR; PG8_SCHED;
;         }
;         } else {
;             const bool w0 = (QV == 2) || (wr == 0);
; #pragma nounroll
;             for (int t = 0; t < nt; t += 2) {
;                 const bool last = (t == nt - 2);
;                 const unsigned a1 = cA + (unsigned)(t + 1) * kstep;
;                 const unsigned a2 = last ? nA : cA + (unsigned)(t + 2) * kstep, b2 = last ? nB : cB + (unsigned)(t + 2) * kstep;
;                 const unsigned a3 = a2 + kstep, b3 = b2 + kstep;
;                 if (w0) { PG8_LDB(B0, 0, 0); PG8_LDB(B1, 0, 1); PG8_SCHED; PG8_LDA(At, 0, 0); }
;                 PG8_WAIT_L(0); PG8_BAR; if (w0) { PG8_MMA(0, 0, At, B0); PG8_MMA(0, 1, At, B1); } PG8_BAR; PG8_SCHED;
;                 PG8_STAGEX(rsB, PG8_SB(0, 0), b2, voffB); PG8_STAGEX(rsB, PG8_SB(0, 1), b2 + hstepB, voffB); PG8_STAGEX(rsA, PG8_SA(0, 0), a2, voffA);
;                 PG8_WAIT_V(6); PG8_BAR; PG8_BAR; PG8_SCHED;
;                 if (w0) { PG8_LDB(B0, 1, 0); PG8_LDB(B1, 1, 1); PG8_SCHED; PG8_LDA(At, 1, 0); }
;                 PG8_WAIT_L(0); PG8_BAR; if (w0) { PG8_MMA(0, 0, At, B0); PG8_MMA(0, 1, At, B1); } PG8_BAR; PG8_SCHED;
;                 PG8_STAGEX(rsB, PG8_SB(1, 0), b3, voffB); PG8_STAGEX(rsB, PG8_SB(1, 1), b3 + hstepB, voffB); PG8_STAGEX(rsA, PG8_SA(1, 0), a3, voffA);
;                 PG8_WAIT_V(6); PG8_BAR; PG8_BAR; PG8_SCHED;
;             }
;         }
;         if (wr == 0) PG8_BAR;
	s_setprio 0
	v_add_u32_e32 v142, 0x18000, v185
	v_add_u32_e32 v158, 0x1c000, v185
	ds_read_b128 v[130:133], v142
	ds_read_b128 v[134:137], v142 offset:1024
	ds_read_b128 v[138:141], v142 offset:2048
	ds_read_b128 v[142:145], v142 offset:3072
	ds_read_b128 v[146:149], v158
	ds_read_b128 v[150:153], v158 offset:1024
	ds_read_b128 v[154:157], v158 offset:2048
	ds_read_b128 v[158:161], v158 offset:3072
	s_add_i32 s63, s63, 0xc0000
	s_mov_b32 m0, s15
	ds_read_b128 v[162:165], v186 offset:32768
	ds_read_b128 v[166:169], v186 offset:33792
	ds_read_b128 v[190:193], v186 offset:34816
	ds_read_b128 v[194:197], v186 offset:35840
	ds_read_b128 v[198:201], v186 offset:36864
	ds_read_b128 v[202:205], v186 offset:37888
	ds_read_b128 v[206:209], v186 offset:38912
	ds_read_b128 v[210:213], v186 offset:39936
	buffer_load_dwordx4 v173, s[76:79], s63 offen lds
	s_mov_b32 m0, s16
	s_nop 0
	buffer_load_dwordx4 v178, s[76:79], s63 offen lds
	s_waitcnt vmcnt(8)
	s_waitcnt lgkmcnt(0)
	s_setprio 1
	s_barrier
	v_mfma_f32_16x16x32_bf16 v[126:129], v[130:133], v[162:165], v[126:129]
	v_mfma_f32_16x16x32_bf16 v[126:129], v[134:137], v[166:169], v[126:129]
	v_mfma_f32_16x16x32_bf16 v[122:125], v[142:145], v[166:169], v[122:125]
	v_mfma_f32_16x16x32_bf16 v[122:125], v[138:141], v[162:165], v[122:125]
	v_mfma_f32_16x16x32_bf16 v[114:117], v[138:141], v[190:193], v[114:117]
	v_mfma_f32_16x16x32_bf16 v[114:117], v[142:145], v[194:197], v[114:117]
	v_mfma_f32_16x16x32_bf16 v[118:121], v[134:137], v[194:197], v[118:121]
	v_mfma_f32_16x16x32_bf16 v[118:121], v[130:133], v[190:193], v[118:121]
	v_mfma_f32_16x16x32_bf16 v[110:113], v[130:133], v[198:201], v[110:113]
	v_mfma_f32_16x16x32_bf16 v[110:113], v[134:137], v[202:205], v[110:113]
	v_mfma_f32_16x16x32_bf16 v[106:109], v[142:145], v[202:205], v[106:109]
	v_mfma_f32_16x16x32_bf16 v[106:109], v[138:141], v[198:201], v[106:109]
	v_mfma_f32_16x16x32_bf16 v[98:101], v[138:141], v[206:209], v[98:101]
	v_mfma_f32_16x16x32_bf16 v[98:101], v[142:145], v[210:213], v[98:101]
	v_mfma_f32_16x16x32_bf16 v[102:105], v[134:137], v[210:213], v[102:105]
	v_mfma_f32_16x16x32_bf16 v[102:105], v[130:133], v[206:209], v[102:105]
	v_mfma_f32_16x16x32_bf16 v[94:97], v[146:149], v[162:165], v[94:97]
	v_mfma_f32_16x16x32_bf16 v[94:97], v[150:153], v[166:169], v[94:97]
	v_mfma_f32_16x16x32_bf16 v[90:93], v[158:161], v[166:169], v[90:93]
	v_mfma_f32_16x16x32_bf16 v[90:93], v[154:157], v[162:165], v[90:93]
	v_mfma_f32_16x16x32_bf16 v[82:85], v[154:157], v[190:193], v[82:85]
	v_mfma_f32_16x16x32_bf16 v[82:85], v[158:161], v[194:197], v[82:85]
	v_mfma_f32_16x16x32_bf16 v[86:89], v[150:153], v[194:197], v[86:89]
	v_mfma_f32_16x16x32_bf16 v[86:89], v[146:149], v[190:193], v[86:89]
	v_mfma_f32_16x16x32_bf16 v[78:81], v[146:149], v[198:201], v[78:81]
	v_mfma_f32_16x16x32_bf16 v[78:81], v[150:153], v[202:205], v[78:81]
	v_mfma_f32_16x16x32_bf16 v[74:77], v[158:161], v[202:205], v[74:77]
	v_mfma_f32_16x16x32_bf16 v[74:77], v[154:157], v[198:201], v[74:77]
	v_mfma_f32_16x16x32_bf16 v[66:69], v[154:157], v[206:209], v[66:69]
	v_mfma_f32_16x16x32_bf16 v[66:69], v[158:161], v[210:213], v[66:69]
	v_mfma_f32_16x16x32_bf16 v[70:73], v[150:153], v[210:213], v[70:73]
	v_mfma_f32_16x16x32_bf16 v[70:73], v[146:149], v[206:209], v[70:73]
	s_barrier
	s_setprio 0
	s_mov_b32 m0, s17
	s_add_i32 s63, s62, 0x80
	ds_read_b128 v[162:165], v186 offset:49152
	ds_read_b128 v[166:169], v186 offset:50176
	ds_read_b128 v[190:193], v186 offset:51200
	ds_read_b128 v[194:197], v186 offset:52224
	ds_read_b128 v[198:201], v186 offset:53248
	ds_read_b128 v[202:205], v186 offset:54272
	ds_read_b128 v[206:209], v186 offset:55296
	ds_read_b128 v[210:213], v186 offset:56320
	buffer_load_dwordx4 v177, s[48:51], s63 offen lds
	s_mov_b32 m0, s18
	s_add_i32 s62, s62, 0x40080
	buffer_load_dwordx4 v179, s[48:51], s63 offen lds
	s_mov_b32 m0, s21
	s_nop 0
	buffer_load_dwordx4 v177, s[48:51], s62 offen lds
	s_mov_b32 m0, s22
	s_nop 0
	buffer_load_dwordx4 v179, s[48:51], s62 offen lds
	s_mov_b32 m0, s19
	s_nop 0
	buffer_load_dwordx4 v173, s[76:79], s61 offen lds
	s_mov_b32 m0, s20
	s_nop 0
	buffer_load_dwordx4 v178, s[76:79], s61 offen lds
	s_waitcnt vmcnt(8)
	s_waitcnt lgkmcnt(0)
	s_setprio 1
	s_barrier
	v_mfma_f32_16x16x32_bf16 v[62:65], v[130:133], v[162:165], v[62:65]
	v_mfma_f32_16x16x32_bf16 v[62:65], v[134:137], v[166:169], v[62:65]
	v_mfma_f32_16x16x32_bf16 v[58:61], v[142:145], v[166:169], v[58:61]
	v_mfma_f32_16x16x32_bf16 v[58:61], v[138:141], v[162:165], v[58:61]
	v_mfma_f32_16x16x32_bf16 v[50:53], v[138:141], v[190:193], v[50:53]
	v_mfma_f32_16x16x32_bf16 v[50:53], v[142:145], v[194:197], v[50:53]
	v_mfma_f32_16x16x32_bf16 v[54:57], v[134:137], v[194:197], v[54:57]
	v_mfma_f32_16x16x32_bf16 v[54:57], v[130:133], v[190:193], v[54:57]
	v_mfma_f32_16x16x32_bf16 v[46:49], v[130:133], v[198:201], v[46:49]
	v_mfma_f32_16x16x32_bf16 v[46:49], v[134:137], v[202:205], v[46:49]
	v_mfma_f32_16x16x32_bf16 v[42:45], v[142:145], v[202:205], v[42:45]
	v_mfma_f32_16x16x32_bf16 v[42:45], v[138:141], v[198:201], v[42:45]
	v_mfma_f32_16x16x32_bf16 v[34:37], v[138:141], v[206:209], v[34:37]
	v_mfma_f32_16x16x32_bf16 v[34:37], v[142:145], v[210:213], v[34:37]
	v_mfma_f32_16x16x32_bf16 v[38:41], v[134:137], v[210:213], v[38:41]
	v_mfma_f32_16x16x32_bf16 v[38:41], v[130:133], v[206:209], v[38:41]
	v_mfma_f32_16x16x32_bf16 v[30:33], v[146:149], v[162:165], v[30:33]
	v_mfma_f32_16x16x32_bf16 v[30:33], v[150:153], v[166:169], v[30:33]
	v_mfma_f32_16x16x32_bf16 v[26:29], v[158:161], v[166:169], v[26:29]
	v_mfma_f32_16x16x32_bf16 v[26:29], v[154:157], v[162:165], v[26:29]
	v_mfma_f32_16x16x32_bf16 v[18:21], v[154:157], v[190:193], v[18:21]
	v_mfma_f32_16x16x32_bf16 v[18:21], v[158:161], v[194:197], v[18:21]
	v_mfma_f32_16x16x32_bf16 v[22:25], v[150:153], v[194:197], v[22:25]
	v_mfma_f32_16x16x32_bf16 v[22:25], v[146:149], v[190:193], v[22:25]
	v_mfma_f32_16x16x32_bf16 v[14:17], v[146:149], v[198:201], v[14:17]
	v_mfma_f32_16x16x32_bf16 v[14:17], v[150:153], v[202:205], v[14:17]
	v_mfma_f32_16x16x32_bf16 v[10:13], v[158:161], v[202:205], v[10:13]
	v_mfma_f32_16x16x32_bf16 v[10:13], v[154:157], v[198:201], v[10:13]
	v_mfma_f32_16x16x32_bf16 v[2:5], v[154:157], v[206:209], v[2:5]
	v_mfma_f32_16x16x32_bf16 v[2:5], v[158:161], v[210:213], v[2:5]
	v_mfma_f32_16x16x32_bf16 v[6:9], v[150:153], v[210:213], v[6:9]
	v_mfma_f32_16x16x32_bf16 v[6:9], v[146:149], v[206:209], v[6:9]
	s_barrier
	s_setprio 0
	s_add_i32 s60, s60, 2
	s_addk_i32 s43, 0x100
	s_addk_i32 s59, 0x100
	s_cmp_gt_u32 s60, 13
	s_cbranch_scc0 .LBB0_1377
	s_and_b64 vcc, exec, s[52:53]
	s_cbranch_vccz .LBB0_1380
	s_barrier
	s_setprio 1

; #define PG8_STAGEX(rs, bufoff, soff, voff) do { _Pragma("unroll") for (int _i = 0; _i < 2; ++_i) \
;         __builtin_amdgcn_raw_ptr_buffer_load_lds(rs, (LAS unsigned*)(lds + (bufoff) + ldsw + _i * 8192), 16, (voff)[_i], (soff), 0, 0); } while (0)
; #define PG8_LDA(dst, b, h) do { _Pragma("unroll") for (int m = 0; m < 4; ++m) _Pragma("unroll") for (int k = 0; k < 2; ++k) dst[m][k] = *(const LAS bf16x8*)(lds + PG8_SA(b, h) + aoff + m * 2048 + k * 1024); } while (0)
; #define PG8_LDB(dst, b, h) do { _Pragma("unroll") for (int n = 0; n < 2; ++n) _Pragma("unroll") for (int k = 0; k < 2; ++k) dst[n][k] = *(const LAS bf16x8*)(lds + PG8_SB(b, h) + boff + n * 2048 + k * 1024); } while (0)
; #define PG8_WAIT_V(n) asm volatile("s_waitcnt vmcnt(" #n ")" ::: "memory")
; #define PG8_WAIT_L(n) asm volatile("s_waitcnt lgkmcnt(" #n ")" ::: "memory")
; #define PG8_BAR __builtin_amdgcn_s_barrier()
; #define PG8_SCHED __builtin_amdgcn_sched_barrier(0)
;     ...
;             for (int t = 0; t < nt; t += 2) {
;                 const bool last = (t == nt - 2);
;                 const unsigned a1 = cA + (unsigned)(t + 1) * kstep;
;                 const unsigned a2 = last ? nA : cA + (unsigned)(t + 2) * kstep, b2 = last ? nB : cB + (unsigned)(t + 2) * kstep;
;                 const unsigned a3 = a2 + kstep, b3 = b2 + kstep;
;                 if (w0) { PG8_LDB(B0, 0, 0); PG8_LDB(B1, 0, 1); PG8_SCHED; PG8_LDA(At, 0, 0); }
;                 PG8_WAIT_L(0); PG8_BAR; if (w0) { PG8_MMA(0, 0, At, B0); PG8_MMA(0, 1, At, B1); } PG8_BAR; PG8_SCHED;
;                 PG8_STAGEX(rsB, PG8_SB(0, 0), b2, voffB); PG8_STAGEX(rsB, PG8_SB(0, 1), b2 + hstepB, voffB); PG8_STAGEX(rsA, PG8_SA(0, 0), a2, voffA);
;                 PG8_WAIT_V(6); PG8_BAR; PG8_BAR; PG8_SCHED;
.LBB0_1429:
	v_add_u32_e32 v78, 0x10000, v95
	v_add_u32_e32 v86, 0x14000, v95
	ds_read_b128 v[66:69], v78
	ds_read_b128 v[70:73], v78 offset:1024
	ds_read_b128 v[74:77], v78 offset:2048
	ds_read_b128 v[78:81], v78 offset:3072
	ds_read_b128 v[82:85], v86
	ds_read_b128 v[100:103], v86 offset:1024
	ds_read_b128 v[104:107], v86 offset:2048
	ds_read_b128 v[108:111], v86 offset:3072
	s_cmp_eq_u32 s40, 12
	s_cselect_b32 s41, s38, s39
	s_cselect_b32 s46, s30, s31
	s_add_i32 s47, s41, 0x80
	ds_read_b128 v[112:115], v96
	ds_read_b128 v[116:119], v96 offset:1024
	ds_read_b128 v[120:123], v96 offset:2048
	ds_read_b128 v[124:127], v96 offset:3072
	ds_read_b128 v[128:131], v96 offset:4096
	ds_read_b128 v[132:135], v96 offset:5120
	ds_read_b128 v[136:139], v96 offset:6144
	ds_read_b128 v[140:143], v96 offset:7168
	s_waitcnt lgkmcnt(0)
	s_setprio 1
	s_barrier
	v_mfma_f32_16x16x32_bf16 v[62:65], v[66:69], v[112:115], v[62:65]
	v_mfma_f32_16x16x32_bf16 v[62:65], v[70:73], v[116:119], v[62:65]
	v_mfma_f32_16x16x32_bf16 v[58:61], v[78:81], v[116:119], v[58:61]
	v_mfma_f32_16x16x32_bf16 v[58:61], v[74:77], v[112:115], v[58:61]
	v_mfma_f32_16x16x32_bf16 v[50:53], v[74:77], v[120:123], v[50:53]
	v_mfma_f32_16x16x32_bf16 v[50:53], v[78:81], v[124:127], v[50:53]
	v_mfma_f32_16x16x32_bf16 v[54:57], v[70:73], v[124:127], v[54:57]
	v_mfma_f32_16x16x32_bf16 v[54:57], v[66:69], v[120:123], v[54:57]
	v_mfma_f32_16x16x32_bf16 v[46:49], v[66:69], v[128:131], v[46:49]
	v_mfma_f32_16x16x32_bf16 v[46:49], v[70:73], v[132:135], v[46:49]
	v_mfma_f32_16x16x32_bf16 v[42:45], v[78:81], v[132:135], v[42:45]
	v_mfma_f32_16x16x32_bf16 v[42:45], v[74:77], v[128:131], v[42:45]
	v_mfma_f32_16x16x32_bf16 v[34:37], v[74:77], v[136:139], v[34:37]
	v_mfma_f32_16x16x32_bf16 v[34:37], v[78:81], v[140:143], v[34:37]
	v_mfma_f32_16x16x32_bf16 v[38:41], v[70:73], v[140:143], v[38:41]
	v_mfma_f32_16x16x32_bf16 v[38:41], v[66:69], v[136:139], v[38:41]
	v_mfma_f32_16x16x32_bf16 v[30:33], v[82:85], v[112:115], v[30:33]
	v_mfma_f32_16x16x32_bf16 v[30:33], v[100:103], v[116:119], v[30:33]
	v_mfma_f32_16x16x32_bf16 v[26:29], v[108:111], v[116:119], v[26:29]
	v_mfma_f32_16x16x32_bf16 v[26:29], v[104:107], v[112:115], v[26:29]
	v_mfma_f32_16x16x32_bf16 v[18:21], v[104:107], v[120:123], v[18:21]
	v_mfma_f32_16x16x32_bf16 v[18:21], v[108:111], v[124:127], v[18:21]
	v_mfma_f32_16x16x32_bf16 v[22:25], v[100:103], v[124:127], v[22:25]
	v_mfma_f32_16x16x32_bf16 v[22:25], v[82:85], v[120:123], v[22:25]
	v_mfma_f32_16x16x32_bf16 v[14:17], v[82:85], v[128:131], v[14:17]
	v_mfma_f32_16x16x32_bf16 v[14:17], v[100:103], v[132:135], v[14:17]
	v_mfma_f32_16x16x32_bf16 v[10:13], v[108:111], v[132:135], v[10:13]
	v_mfma_f32_16x16x32_bf16 v[10:13], v[104:107], v[128:131], v[10:13]
	v_mfma_f32_16x16x32_bf16 v[2:5], v[104:107], v[136:139], v[2:5]
	v_mfma_f32_16x16x32_bf16 v[2:5], v[108:111], v[140:143], v[2:5]
	v_mfma_f32_16x16x32_bf16 v[6:9], v[100:103], v[140:143], v[6:9]
	v_mfma_f32_16x16x32_bf16 v[6:9], v[82:85], v[136:139], v[6:9]
	s_barrier
	s_setprio 0
	s_mov_b32 m0, s5
	s_mov_b32 s50, s78
	s_mov_b32 s51, s79
	buffer_load_dwordx4 v89, s[48:51], s46 offen lds
	s_mov_b32 m0, s7
	s_add_i32 s52, s46, 0x40000
	buffer_load_dwordx4 v91, s[48:51], s46 offen lds
	s_mov_b32 m0, s11
	s_nop 0
	buffer_load_dwordx4 v89, s[48:51], s52 offen lds
	s_mov_b32 m0, s12
	s_nop 0
	buffer_load_dwordx4 v91, s[48:51], s52 offen lds
	s_mov_b32 m0, s3
	s_nop 0
	buffer_load_dwordx4 v88, s[76:79], s41 offen lds
	s_mov_b32 m0, s13
	s_nop 0
	buffer_load_dwordx4 v90, s[76:79], s41 offen lds
	s_waitcnt vmcnt(6)
	s_barrier
	s_barrier
; #define PG8_STAGEX(rs, bufoff, soff, voff) do { _Pragma("unroll") for (int _i = 0; _i < 2; ++_i) \
;         __builtin_amdgcn_raw_ptr_buffer_load_lds(rs, (LAS unsigned*)(lds + (bufoff) + ldsw + _i * 8192), 16, (voff)[_i], (soff), 0, 0); } while (0)
; #define PG8_LDA(dst, b, h) do { _Pragma("unroll") for (int m = 0; m < 4; ++m) _Pragma("unroll") for (int k = 0; k < 2; ++k) dst[m][k] = *(const LAS bf16x8*)(lds + PG8_SA(b, h) + aoff + m * 2048 + k * 1024); } while (0)
; #define PG8_LDB(dst, b, h) do { _Pragma("unroll") for (int n = 0; n < 2; ++n) _Pragma("unroll") for (int k = 0; k < 2; ++k) dst[n][k] = *(const LAS bf16x8*)(lds + PG8_SB(b, h) + boff + n * 2048 + k * 1024); } while (0)
; #define PG8_WAIT_V(n) asm volatile("s_waitcnt vmcnt(" #n ")" ::: "memory")
; #define PG8_WAIT_L(n) asm volatile("s_waitcnt lgkmcnt(" #n ")" ::: "memory")
; #define PG8_BAR __builtin_amdgcn_s_barrier()
; #define PG8_SCHED __builtin_amdgcn_sched_barrier(0)
;     ...
;                 if (w0) { PG8_LDB(B0, 1, 0); PG8_LDB(B1, 1, 1); PG8_SCHED; PG8_LDA(At, 1, 0); }
;                 PG8_WAIT_L(0); PG8_BAR; if (w0) { PG8_MMA(0, 0, At, B0); PG8_MMA(0, 1, At, B1); } PG8_BAR; PG8_SCHED;
;                 PG8_STAGEX(rsB, PG8_SB(1, 0), b3, voffB); PG8_STAGEX(rsB, PG8_SB(1, 1), b3 + hstepB, voffB); PG8_STAGEX(rsA, PG8_SA(1, 0), a3, voffA);
;                 PG8_WAIT_V(6); PG8_BAR; PG8_BAR; PG8_SCHED;
;             }
;         }
;         if (wr == 0) PG8_BAR;
	v_add_u32_e32 v78, 0x18000, v95
	v_add_u32_e32 v86, 0x1c000, v95
	ds_read_b128 v[66:69], v78
	ds_read_b128 v[70:73], v78 offset:1024
	ds_read_b128 v[74:77], v78 offset:2048
	ds_read_b128 v[78:81], v78 offset:3072
	ds_read_b128 v[82:85], v86
	ds_read_b128 v[100:103], v86 offset:1024
	ds_read_b128 v[104:107], v86 offset:2048
	ds_read_b128 v[108:111], v86 offset:3072
	ds_read_b128 v[112:115], v96 offset:32768
	ds_read_b128 v[116:119], v96 offset:33792
	ds_read_b128 v[120:123], v96 offset:34816
	ds_read_b128 v[124:127], v96 offset:35840
	ds_read_b128 v[128:131], v96 offset:36864
	ds_read_b128 v[132:135], v96 offset:37888
	ds_read_b128 v[136:139], v96 offset:38912
	ds_read_b128 v[140:143], v96 offset:39936
	s_waitcnt lgkmcnt(0)
	s_setprio 1
	s_barrier
	v_mfma_f32_16x16x32_bf16 v[62:65], v[66:69], v[112:115], v[62:65]
	v_mfma_f32_16x16x32_bf16 v[58:61], v[74:77], v[112:115], v[58:61]
	v_mfma_f32_16x16x32_bf16 v[54:57], v[66:69], v[120:123], v[54:57]
	v_mfma_f32_16x16x32_bf16 v[50:53], v[74:77], v[120:123], v[50:53]
	v_mfma_f32_16x16x32_bf16 v[46:49], v[66:69], v[128:131], v[46:49]
	v_mfma_f32_16x16x32_bf16 v[42:45], v[74:77], v[128:131], v[42:45]
	v_mfma_f32_16x16x32_bf16 v[38:41], v[66:69], v[136:139], v[38:41]
	v_mfma_f32_16x16x32_bf16 v[34:37], v[74:77], v[136:139], v[34:37]
	v_mfma_f32_16x16x32_bf16 v[62:65], v[70:73], v[116:119], v[62:65]
	v_mfma_f32_16x16x32_bf16 v[58:61], v[78:81], v[116:119], v[58:61]
	v_mfma_f32_16x16x32_bf16 v[54:57], v[70:73], v[124:127], v[54:57]
	v_mfma_f32_16x16x32_bf16 v[50:53], v[78:81], v[124:127], v[50:53]
	v_mfma_f32_16x16x32_bf16 v[46:49], v[70:73], v[132:135], v[46:49]
	v_mfma_f32_16x16x32_bf16 v[42:45], v[78:81], v[132:135], v[42:45]
	v_mfma_f32_16x16x32_bf16 v[38:41], v[70:73], v[140:143], v[38:41]
	v_mfma_f32_16x16x32_bf16 v[34:37], v[78:81], v[140:143], v[34:37]
	v_mfma_f32_16x16x32_bf16 v[30:33], v[82:85], v[112:115], v[30:33]
	s_add_i32 s41, s46, 0x80
	v_mfma_f32_16x16x32_bf16 v[26:29], v[104:107], v[112:115], v[26:29]
	v_mfma_f32_16x16x32_bf16 v[22:25], v[82:85], v[120:123], v[22:25]
	v_mfma_f32_16x16x32_bf16 v[18:21], v[104:107], v[120:123], v[18:21]
	v_mfma_f32_16x16x32_bf16 v[14:17], v[82:85], v[128:131], v[14:17]
	v_mfma_f32_16x16x32_bf16 v[10:13], v[104:107], v[128:131], v[10:13]
	v_mfma_f32_16x16x32_bf16 v[6:9], v[82:85], v[136:139], v[6:9]
	v_mfma_f32_16x16x32_bf16 v[2:5], v[104:107], v[136:139], v[2:5]
	v_mfma_f32_16x16x32_bf16 v[30:33], v[100:103], v[116:119], v[30:33]
	v_mfma_f32_16x16x32_bf16 v[26:29], v[108:111], v[116:119], v[26:29]
	v_mfma_f32_16x16x32_bf16 v[22:25], v[100:103], v[124:127], v[22:25]
	v_mfma_f32_16x16x32_bf16 v[18:21], v[108:111], v[124:127], v[18:21]
	v_mfma_f32_16x16x32_bf16 v[14:17], v[100:103], v[132:135], v[14:17]
	v_mfma_f32_16x16x32_bf16 v[10:13], v[108:111], v[132:135], v[10:13]
	v_mfma_f32_16x16x32_bf16 v[6:9], v[100:103], v[140:143], v[6:9]
	v_mfma_f32_16x16x32_bf16 v[2:5], v[108:111], v[140:143], v[2:5]
	s_barrier
	s_setprio 0
	s_mov_b32 m0, s14
	s_add_i32 s46, s46, 0x40080
	buffer_load_dwordx4 v89, s[48:51], s41 offen lds
	s_mov_b32 m0, s15
	s_nop 0
	buffer_load_dwordx4 v91, s[48:51], s41 offen lds
	s_mov_b32 m0, s18
	s_nop 0
	buffer_load_dwordx4 v89, s[48:51], s46 offen lds
	s_mov_b32 m0, s19
	s_nop 0
	buffer_load_dwordx4 v91, s[48:51], s46 offen lds
	s_mov_b32 m0, s16
	s_nop 0
	buffer_load_dwordx4 v88, s[76:79], s47 offen lds
	s_mov_b32 m0, s17
	s_nop 0
	buffer_load_dwordx4 v90, s[76:79], s47 offen lds
	s_waitcnt vmcnt(6)
	s_barrier
	s_barrier
	s_add_i32 s40, s40, 2
	s_addk_i32 s31, 0x100
	s_addk_i32 s39, 0x100
	s_cmp_gt_u32 s40, 13
	s_cbranch_scc0 .LBB0_1429
	s_and_b64 vcc, exec, s[42:43]
	s_cbranch_vccz .LBB0_1432
	s_barrier
	s_setprio 1

; #define PG8_WAIT_V(n) asm volatile("s_waitcnt vmcnt(" #n ")" ::: "memory")
; #define PG8_BAR __builtin_amdgcn_s_barrier()
;     ...
;     PG8_WAIT_V(0);
;     PG8_BAR;
; __device__ __forceinline__ void xcd_barrier(const XcdBarrier& b) {
;     asm volatile("s_waitcnt vmcnt(0)" ::: "memory");
;     __syncthreads();
;     if (threadIdx.x == 0) {
;         unsigned* bar = b.bar;
;         __builtin_amdgcn_s_waitcnt(0);
;         unsigned nloc = b.st[0], nx = b.st[1];
;         if (nloc == 0u) { xcd_barrier_complete(bar, b.x, nloc, nx); b.st[0] = nloc; b.st[1] = nx; }
.LBB0_1454:
	s_waitcnt vmcnt(0)
	s_setprio 0
	s_barrier
	s_and_saveexec_b64 s[30:31], s[94:95]
	s_mov_b32 s27, 0xac00
	s_mov_b32 s28, 0x70000
	s_cbranch_execz .LBB0_1506
	v_readlane_b32 s1, v254, 23
	s_waitcnt vmcnt(0) expcnt(0) lgkmcnt(0)
	s_nop 0
	v_mov_b32_e32 v2, s1
	ds_read_b32 v4, v2
	v_readlane_b32 s1, v254, 24
	s_waitcnt lgkmcnt(0)
	v_cmp_ne_u32_e32 vcc, 0, v4
	v_mov_b32_e32 v2, s1
	ds_read_b32 v2, v2
	s_cbranch_vccnz .LBB0_1470
	s_load_dwordx2 s[2:3], s[88:89], 0x4
	s_waitcnt lgkmcnt(0)
	s_mul_i32 s1, s2, s8
	s_mul_i32 s1, s1, s3
	s_mov_b32 s2, 1
	s_branch .LBB0_1458

; #define PG8_STAGEX(rs, bufoff, soff, voff) do { _Pragma("unroll") for (int _i = 0; _i < 2; ++_i) \
;         __builtin_amdgcn_raw_ptr_buffer_load_lds(rs, (LAS unsigned*)(lds + (bufoff) + ldsw + _i * 8192), 16, (voff)[_i], (soff), 0, 0); } while (0)
; #define PG8_LDA(dst, b, h) do { _Pragma("unroll") for (int m = 0; m < 4; ++m) _Pragma("unroll") for (int k = 0; k < 2; ++k) dst[m][k] = *(const LAS bf16x8*)(lds + PG8_SA(b, h) + aoff + m * 2048 + k * 1024); } while (0)
; #define PG8_LDB(dst, b, h) do { _Pragma("unroll") for (int n = 0; n < 2; ++n) _Pragma("unroll") for (int k = 0; k < 2; ++k) dst[n][k] = *(const LAS bf16x8*)(lds + PG8_SB(b, h) + boff + n * 2048 + k * 1024); } while (0)
; #define PG8_WAIT_V(n) asm volatile("s_waitcnt vmcnt(" #n ")" ::: "memory")
; #define PG8_WAIT_L(n) asm volatile("s_waitcnt lgkmcnt(" #n ")" ::: "memory")
; #define PG8_BAR __builtin_amdgcn_s_barrier()
; #define PG8_SCHED __builtin_amdgcn_sched_barrier(0)
;     ...
;             const unsigned a1 = cA + (unsigned)(t + 1) * kstep;
;             const unsigned a2 = last ? nA : cA + (unsigned)(t + 2) * kstep, b2 = last ? nB : cB + (unsigned)(t + 2) * kstep;
;             const unsigned a3 = a2 + kstep, b3 = b2 + kstep;
;             PG8_LDB(B0, 0, 0); PG8_LDB(B1, 0, 1); PG8_SCHED; PG8_LDA(At, 0, 0); PG8_STAGEX(rsA, PG8_SA(1, 1), a1 + hstepA, voffA);
;             PG8_WAIT_V(8); PG8_WAIT_L(0); PG8_BAR; PG8_MMA(0, 0, At, B0); PG8_MMA(0, 1, At, B1); PG8_BAR; PG8_SCHED;
;             PG8_LDA(At, 0, 1); PG8_STAGEX(rsB, PG8_SB(0, 0), b2, voffB); PG8_STAGEX(rsB, PG8_SB(0, 1), b2 + hstepB, voffB); PG8_STAGEX(rsA, PG8_SA(0, 0), a2, voffA);
;             PG8_WAIT_V(8); PG8_WAIT_L(0); PG8_BAR; PG8_MMA(1, 0, At, B0); PG8_MMA(1, 1, At, B1); PG8_BAR; PG8_SCHED;
.LBB0_1529:
	v_add_u32_e32 v118, 0x10000, v210
	v_add_u32_e32 v142, 0x14000, v210
	ds_read_b128 v[106:109], v118
	ds_read_b128 v[110:113], v118 offset:1024
	ds_read_b128 v[114:117], v118 offset:2048
	ds_read_b128 v[118:121], v118 offset:3072
	ds_read_b128 v[122:125], v142
	ds_read_b128 v[126:129], v142 offset:1024
	ds_read_b128 v[130:133], v142 offset:2048
	ds_read_b128 v[142:145], v142 offset:3072
	s_add_i32 s46, s59, 0xfff80080
	s_cmp_eq_u32 s64, 28
	s_cselect_b32 s67, s30, s46
	s_cselect_b32 s66, s31, s63
	s_or_b32 s65, s67, 0x80
	s_mov_b32 m0, s76
	ds_read_b128 v[164:167], v211
	ds_read_b128 v[168:171], v211 offset:1024
	ds_read_b128 v[182:185], v211 offset:2048
	ds_read_b128 v[186:189], v211 offset:3072
	ds_read_b128 v[190:193], v211 offset:4096
	ds_read_b128 v[194:197], v211 offset:5120
	ds_read_b128 v[198:201], v211 offset:6144
	ds_read_b128 v[202:205], v211 offset:7168
	buffer_load_dwordx4 v178, s[40:43], s59 offen lds
	s_mov_b32 m0, s77
	s_nop 0
	buffer_load_dwordx4 v206, s[40:43], s59 offen lds
	s_waitcnt vmcnt(8)
	s_waitcnt lgkmcnt(0)
	s_setprio 1
	s_barrier
	v_mfma_f32_16x16x32_bf16 v[158:161], v[106:109], v[164:167], v[158:161]
	v_mfma_f32_16x16x32_bf16 v[158:161], v[110:113], v[168:171], v[158:161]
	v_mfma_f32_16x16x32_bf16 v[154:157], v[118:121], v[168:171], v[154:157]
	v_mfma_f32_16x16x32_bf16 v[154:157], v[114:117], v[164:167], v[154:157]
	v_mfma_f32_16x16x32_bf16 v[146:149], v[114:117], v[182:185], v[146:149]
	v_mfma_f32_16x16x32_bf16 v[146:149], v[118:121], v[186:189], v[146:149]
	v_mfma_f32_16x16x32_bf16 v[150:153], v[110:113], v[186:189], v[150:153]
	v_mfma_f32_16x16x32_bf16 v[150:153], v[106:109], v[182:185], v[150:153]
	v_mfma_f32_16x16x32_bf16 v[138:141], v[106:109], v[190:193], v[138:141]
	v_mfma_f32_16x16x32_bf16 v[138:141], v[110:113], v[194:197], v[138:141]
	v_mfma_f32_16x16x32_bf16 v[134:137], v[118:121], v[194:197], v[134:137]
	v_mfma_f32_16x16x32_bf16 v[134:137], v[114:117], v[190:193], v[134:137]
	v_mfma_f32_16x16x32_bf16 v[98:101], v[114:117], v[198:201], v[98:101]
	v_mfma_f32_16x16x32_bf16 v[98:101], v[118:121], v[202:205], v[98:101]
	v_mfma_f32_16x16x32_bf16 v[102:105], v[110:113], v[202:205], v[102:105]
	v_mfma_f32_16x16x32_bf16 v[102:105], v[106:109], v[198:201], v[102:105]
	v_mfma_f32_16x16x32_bf16 v[62:65], v[122:125], v[164:167], v[62:65]
	v_mfma_f32_16x16x32_bf16 v[62:65], v[126:129], v[168:171], v[62:65]
	v_mfma_f32_16x16x32_bf16 v[58:61], v[142:145], v[168:171], v[58:61]
	v_mfma_f32_16x16x32_bf16 v[58:61], v[130:133], v[164:167], v[58:61]
	v_mfma_f32_16x16x32_bf16 v[50:53], v[130:133], v[182:185], v[50:53]
	v_mfma_f32_16x16x32_bf16 v[50:53], v[142:145], v[186:189], v[50:53]
	v_mfma_f32_16x16x32_bf16 v[54:57], v[126:129], v[186:189], v[54:57]
	v_mfma_f32_16x16x32_bf16 v[54:57], v[122:125], v[182:185], v[54:57]
	v_mfma_f32_16x16x32_bf16 v[46:49], v[122:125], v[190:193], v[46:49]
	v_mfma_f32_16x16x32_bf16 v[46:49], v[126:129], v[194:197], v[46:49]
	v_mfma_f32_16x16x32_bf16 v[42:45], v[142:145], v[194:197], v[42:45]
	v_mfma_f32_16x16x32_bf16 v[42:45], v[130:133], v[190:193], v[42:45]
	v_mfma_f32_16x16x32_bf16 v[34:37], v[130:133], v[198:201], v[34:37]
	v_mfma_f32_16x16x32_bf16 v[34:37], v[142:145], v[202:205], v[34:37]
	v_mfma_f32_16x16x32_bf16 v[38:41], v[126:129], v[202:205], v[38:41]
	v_mfma_f32_16x16x32_bf16 v[38:41], v[122:125], v[198:201], v[38:41]
	s_barrier
	s_setprio 0
	s_mov_b32 m0, s17
	s_mov_b32 s46, s42
	s_mov_b32 s47, s43
	ds_read_b128 v[164:167], v211 offset:16384
	ds_read_b128 v[168:171], v211 offset:17408
	ds_read_b128 v[182:185], v211 offset:18432
	ds_read_b128 v[186:189], v211 offset:19456
	ds_read_b128 v[190:193], v211 offset:20480
	ds_read_b128 v[194:197], v211 offset:21504
	ds_read_b128 v[198:201], v211 offset:22528
	ds_read_b128 v[202:205], v211 offset:23552
	buffer_load_dwordx4 v179, s[44:47], s66 offen lds
	s_mov_b32 m0, s18
	s_add_i32 s68, s66, 0x80000
	buffer_load_dwordx4 v207, s[44:47], s66 offen lds
	s_mov_b32 m0, s19
	s_nop 0
	buffer_load_dwordx4 v179, s[44:47], s68 offen lds
	s_mov_b32 m0, s20
	s_nop 0
	buffer_load_dwordx4 v207, s[44:47], s68 offen lds
	s_mov_b32 m0, s16
	s_nop 0
	buffer_load_dwordx4 v178, s[40:43], s67 offen lds
	s_mov_b32 m0, s21
	s_nop 0
	buffer_load_dwordx4 v206, s[40:43], s67 offen lds
	s_waitcnt vmcnt(8)
	s_waitcnt lgkmcnt(0)
	s_setprio 1
	s_barrier
	v_mfma_f32_16x16x32_bf16 v[94:97], v[106:109], v[164:167], v[94:97]
	v_mfma_f32_16x16x32_bf16 v[94:97], v[110:113], v[168:171], v[94:97]
	v_mfma_f32_16x16x32_bf16 v[90:93], v[118:121], v[168:171], v[90:93]
	v_mfma_f32_16x16x32_bf16 v[90:93], v[114:117], v[164:167], v[90:93]
	v_mfma_f32_16x16x32_bf16 v[82:85], v[114:117], v[182:185], v[82:85]
	v_mfma_f32_16x16x32_bf16 v[82:85], v[118:121], v[186:189], v[82:85]
	v_mfma_f32_16x16x32_bf16 v[86:89], v[110:113], v[186:189], v[86:89]
	v_mfma_f32_16x16x32_bf16 v[86:89], v[106:109], v[182:185], v[86:89]
	v_mfma_f32_16x16x32_bf16 v[78:81], v[106:109], v[190:193], v[78:81]
	v_mfma_f32_16x16x32_bf16 v[78:81], v[110:113], v[194:197], v[78:81]
	v_mfma_f32_16x16x32_bf16 v[74:77], v[118:121], v[194:197], v[74:77]
	v_mfma_f32_16x16x32_bf16 v[74:77], v[114:117], v[190:193], v[74:77]
	v_mfma_f32_16x16x32_bf16 v[66:69], v[114:117], v[198:201], v[66:69]
	v_mfma_f32_16x16x32_bf16 v[66:69], v[118:121], v[202:205], v[66:69]
	v_mfma_f32_16x16x32_bf16 v[70:73], v[110:113], v[202:205], v[70:73]
	v_mfma_f32_16x16x32_bf16 v[70:73], v[106:109], v[198:201], v[70:73]
	v_mfma_f32_16x16x32_bf16 v[30:33], v[122:125], v[164:167], v[30:33]
	v_mfma_f32_16x16x32_bf16 v[30:33], v[126:129], v[168:171], v[30:33]
	v_mfma_f32_16x16x32_bf16 v[26:29], v[142:145], v[168:171], v[26:29]
	v_mfma_f32_16x16x32_bf16 v[26:29], v[130:133], v[164:167], v[26:29]
	v_mfma_f32_16x16x32_bf16 v[18:21], v[130:133], v[182:185], v[18:21]
	v_mfma_f32_16x16x32_bf16 v[18:21], v[142:145], v[186:189], v[18:21]
	v_mfma_f32_16x16x32_bf16 v[22:25], v[126:129], v[186:189], v[22:25]
	v_mfma_f32_16x16x32_bf16 v[22:25], v[122:125], v[182:185], v[22:25]
	v_mfma_f32_16x16x32_bf16 v[14:17], v[122:125], v[190:193], v[14:17]
	v_mfma_f32_16x16x32_bf16 v[14:17], v[126:129], v[194:197], v[14:17]
	v_mfma_f32_16x16x32_bf16 v[10:13], v[142:145], v[194:197], v[10:13]
	v_mfma_f32_16x16x32_bf16 v[10:13], v[130:133], v[190:193], v[10:13]
	v_mfma_f32_16x16x32_bf16 v[2:5], v[130:133], v[198:201], v[2:5]
	v_mfma_f32_16x16x32_bf16 v[2:5], v[142:145], v[202:205], v[2:5]
	v_mfma_f32_16x16x32_bf16 v[6:9], v[126:129], v[202:205], v[6:9]
	v_mfma_f32_16x16x32_bf16 v[6:9], v[122:125], v[198:201], v[6:9]
	s_barrier
; #define PG8_STAGEX(rs, bufoff, soff, voff) do { _Pragma("unroll") for (int _i = 0; _i < 2; ++_i) \
;         __builtin_amdgcn_raw_ptr_buffer_load_lds(rs, (LAS unsigned*)(lds + (bufoff) + ldsw + _i * 8192), 16, (voff)[_i], (soff), 0, 0); } while (0)
; #define PG8_WAIT_V(n) asm volatile("s_waitcnt vmcnt(" #n ")" ::: "memory")
; #define PG8_WAIT_L(n) asm volatile("s_waitcnt lgkmcnt(" #n ")" ::: "memory")
; #define PG8_BAR __builtin_amdgcn_s_barrier()
;     ...
;             PG8_LDB(B0, 1, 0); PG8_LDB(B1, 1, 1); PG8_SCHED; PG8_LDA(At, 1, 0); PG8_STAGEX(rsA, PG8_SA(0, 1), a2 + hstepA, voffA);
;             PG8_WAIT_V(8); PG8_WAIT_L(0); PG8_BAR; PG8_MMA(0, 0, At, B0); PG8_MMA(0, 1, At, B1); PG8_BAR; PG8_SCHED;
;             PG8_LDA(At, 1, 1); PG8_STAGEX(rsB, PG8_SB(1, 0), b3, voffB); PG8_STAGEX(rsB, PG8_SB(1, 1), b3 + hstepB, voffB); PG8_STAGEX(rsA, PG8_SA(1, 0), a3, voffA);
;             PG8_WAIT_V(8); PG8_WAIT_L(0); PG8_BAR; PG8_MMA(1, 0, At, B0); PG8_MMA(1, 1, At, B1); PG8_BAR; PG8_SCHED;
;         }
;         } else {
;             const bool w0 = (QV == 2) || (wr == 0);
; #pragma nounroll
;             for (int t = 0; t < nt; t += 2) {
;                 const bool last = (t == nt - 2);
;                 const unsigned a1 = cA + (unsigned)(t + 1) * kstep;
;                 const unsigned a2 = last ? nA : cA + (unsigned)(t + 2) * kstep, b2 = last ? nB : cB + (unsigned)(t + 2) * kstep;
;                 const unsigned a3 = a2 + kstep, b3 = b2 + kstep;
;                 if (w0) { PG8_LDB(B0, 0, 0); PG8_LDB(B1, 0, 1); PG8_SCHED; PG8_LDA(At, 0, 0); }
;                 PG8_WAIT_L(0); PG8_BAR; if (w0) { PG8_MMA(0, 0, At, B0); PG8_MMA(0, 1, At, B1); } PG8_BAR; PG8_SCHED;
;                 PG8_STAGEX(rsB, PG8_SB(0, 0), b2, voffB); PG8_STAGEX(rsB, PG8_SB(0, 1), b2 + hstepB, voffB); PG8_STAGEX(rsA, PG8_SA(0, 0), a2, voffA);
;                 PG8_WAIT_V(6); PG8_BAR; PG8_BAR; PG8_SCHED;
;                 if (w0) { PG8_LDB(B0, 1, 0); PG8_LDB(B1, 1, 1); PG8_SCHED; PG8_LDA(At, 1, 0); }
;                 PG8_WAIT_L(0); PG8_BAR; if (w0) { PG8_MMA(0, 0, At, B0); PG8_MMA(0, 1, At, B1); } PG8_BAR; PG8_SCHED;
;                 PG8_STAGEX(rsB, PG8_SB(1, 0), b3, voffB); PG8_STAGEX(rsB, PG8_SB(1, 1), b3 + hstepB, voffB); PG8_STAGEX(rsA, PG8_SA(1, 0), a3, voffA);
;                 PG8_WAIT_V(6); PG8_BAR; PG8_BAR; PG8_SCHED;
;             }
;         }
;         if (wr == 0) PG8_BAR;
	s_setprio 0
	v_add_u32_e32 v118, 0x18000, v210
	v_add_u32_e32 v142, 0x1c000, v210
	ds_read_b128 v[106:109], v118
	ds_read_b128 v[110:113], v118 offset:1024
	ds_read_b128 v[114:117], v118 offset:2048
	ds_read_b128 v[118:121], v118 offset:3072
	ds_read_b128 v[122:125], v142
	ds_read_b128 v[126:129], v142 offset:1024
	ds_read_b128 v[130:133], v142 offset:2048
	ds_read_b128 v[142:145], v142 offset:3072
	s_add_i32 s67, s67, 0x80000
	s_mov_b32 m0, s22
	ds_read_b128 v[164:167], v211 offset:32768
	ds_read_b128 v[168:171], v211 offset:33792
	ds_read_b128 v[182:185], v211 offset:34816
	ds_read_b128 v[186:189], v211 offset:35840
	ds_read_b128 v[190:193], v211 offset:36864
	ds_read_b128 v[194:197], v211 offset:37888
	ds_read_b128 v[198:201], v211 offset:38912
	ds_read_b128 v[202:205], v211 offset:39936
	buffer_load_dwordx4 v178, s[40:43], s67 offen lds
	s_mov_b32 m0, s23
	s_nop 0
	buffer_load_dwordx4 v206, s[40:43], s67 offen lds
	s_waitcnt vmcnt(8)
	s_waitcnt lgkmcnt(0)
	s_setprio 1
	s_barrier
	v_mfma_f32_16x16x32_bf16 v[158:161], v[106:109], v[164:167], v[158:161]
	v_mfma_f32_16x16x32_bf16 v[158:161], v[110:113], v[168:171], v[158:161]
	v_mfma_f32_16x16x32_bf16 v[154:157], v[118:121], v[168:171], v[154:157]
	v_mfma_f32_16x16x32_bf16 v[154:157], v[114:117], v[164:167], v[154:157]
	v_mfma_f32_16x16x32_bf16 v[146:149], v[114:117], v[182:185], v[146:149]
	v_mfma_f32_16x16x32_bf16 v[146:149], v[118:121], v[186:189], v[146:149]
	v_mfma_f32_16x16x32_bf16 v[150:153], v[110:113], v[186:189], v[150:153]
	v_mfma_f32_16x16x32_bf16 v[150:153], v[106:109], v[182:185], v[150:153]
	v_mfma_f32_16x16x32_bf16 v[138:141], v[106:109], v[190:193], v[138:141]
	v_mfma_f32_16x16x32_bf16 v[138:141], v[110:113], v[194:197], v[138:141]
	v_mfma_f32_16x16x32_bf16 v[134:137], v[118:121], v[194:197], v[134:137]
	v_mfma_f32_16x16x32_bf16 v[134:137], v[114:117], v[190:193], v[134:137]
	v_mfma_f32_16x16x32_bf16 v[98:101], v[114:117], v[198:201], v[98:101]
	v_mfma_f32_16x16x32_bf16 v[98:101], v[118:121], v[202:205], v[98:101]
	v_mfma_f32_16x16x32_bf16 v[102:105], v[110:113], v[202:205], v[102:105]
	v_mfma_f32_16x16x32_bf16 v[102:105], v[106:109], v[198:201], v[102:105]
	v_mfma_f32_16x16x32_bf16 v[62:65], v[122:125], v[164:167], v[62:65]
	v_mfma_f32_16x16x32_bf16 v[62:65], v[126:129], v[168:171], v[62:65]
	v_mfma_f32_16x16x32_bf16 v[58:61], v[142:145], v[168:171], v[58:61]
	v_mfma_f32_16x16x32_bf16 v[58:61], v[130:133], v[164:167], v[58:61]
	v_mfma_f32_16x16x32_bf16 v[50:53], v[130:133], v[182:185], v[50:53]
	v_mfma_f32_16x16x32_bf16 v[50:53], v[142:145], v[186:189], v[50:53]
	v_mfma_f32_16x16x32_bf16 v[54:57], v[126:129], v[186:189], v[54:57]
	v_mfma_f32_16x16x32_bf16 v[54:57], v[122:125], v[182:185], v[54:57]
	v_mfma_f32_16x16x32_bf16 v[46:49], v[122:125], v[190:193], v[46:49]
	v_mfma_f32_16x16x32_bf16 v[46:49], v[126:129], v[194:197], v[46:49]
	v_mfma_f32_16x16x32_bf16 v[42:45], v[142:145], v[194:197], v[42:45]
	v_mfma_f32_16x16x32_bf16 v[42:45], v[130:133], v[190:193], v[42:45]
	v_mfma_f32_16x16x32_bf16 v[34:37], v[130:133], v[198:201], v[34:37]
	v_mfma_f32_16x16x32_bf16 v[34:37], v[142:145], v[202:205], v[34:37]
	v_mfma_f32_16x16x32_bf16 v[38:41], v[126:129], v[202:205], v[38:41]
	v_mfma_f32_16x16x32_bf16 v[38:41], v[122:125], v[198:201], v[38:41]
	s_barrier
	s_setprio 0
	s_mov_b32 m0, s54
	s_or_b32 s67, s66, 0x80
	ds_read_b128 v[164:167], v211 offset:49152
	ds_read_b128 v[168:171], v211 offset:50176
	ds_read_b128 v[182:185], v211 offset:51200
	ds_read_b128 v[186:189], v211 offset:52224
	ds_read_b128 v[190:193], v211 offset:53248
	ds_read_b128 v[194:197], v211 offset:54272
	ds_read_b128 v[198:201], v211 offset:55296
	ds_read_b128 v[202:205], v211 offset:56320
	buffer_load_dwordx4 v179, s[44:47], s67 offen lds
	s_mov_b32 m0, s55
	s_add_i32 s66, s66, 0x80080
	buffer_load_dwordx4 v207, s[44:47], s67 offen lds
	s_mov_b32 m0, s74
	s_nop 0
	buffer_load_dwordx4 v179, s[44:47], s66 offen lds
	s_mov_b32 m0, s75
	s_nop 0
	buffer_load_dwordx4 v207, s[44:47], s66 offen lds
	s_mov_b32 m0, s72
	s_nop 0
	buffer_load_dwordx4 v178, s[40:43], s65 offen lds
	s_mov_b32 m0, s73
	s_nop 0
	buffer_load_dwordx4 v206, s[40:43], s65 offen lds
	s_waitcnt vmcnt(8)
	s_waitcnt lgkmcnt(0)
	s_setprio 1
	s_barrier
	v_mfma_f32_16x16x32_bf16 v[94:97], v[106:109], v[164:167], v[94:97]
	v_mfma_f32_16x16x32_bf16 v[94:97], v[110:113], v[168:171], v[94:97]
	v_mfma_f32_16x16x32_bf16 v[90:93], v[118:121], v[168:171], v[90:93]
	v_mfma_f32_16x16x32_bf16 v[90:93], v[114:117], v[164:167], v[90:93]
	v_mfma_f32_16x16x32_bf16 v[82:85], v[114:117], v[182:185], v[82:85]
	v_mfma_f32_16x16x32_bf16 v[82:85], v[118:121], v[186:189], v[82:85]
	v_mfma_f32_16x16x32_bf16 v[86:89], v[110:113], v[186:189], v[86:89]
	v_mfma_f32_16x16x32_bf16 v[86:89], v[106:109], v[182:185], v[86:89]
	v_mfma_f32_16x16x32_bf16 v[78:81], v[106:109], v[190:193], v[78:81]
	v_mfma_f32_16x16x32_bf16 v[78:81], v[110:113], v[194:197], v[78:81]
	v_mfma_f32_16x16x32_bf16 v[74:77], v[118:121], v[194:197], v[74:77]
	v_mfma_f32_16x16x32_bf16 v[74:77], v[114:117], v[190:193], v[74:77]
	v_mfma_f32_16x16x32_bf16 v[66:69], v[114:117], v[198:201], v[66:69]
	v_mfma_f32_16x16x32_bf16 v[66:69], v[118:121], v[202:205], v[66:69]
	v_mfma_f32_16x16x32_bf16 v[70:73], v[110:113], v[202:205], v[70:73]
	v_mfma_f32_16x16x32_bf16 v[70:73], v[106:109], v[198:201], v[70:73]
	v_mfma_f32_16x16x32_bf16 v[30:33], v[122:125], v[164:167], v[30:33]
	v_mfma_f32_16x16x32_bf16 v[30:33], v[126:129], v[168:171], v[30:33]
	v_mfma_f32_16x16x32_bf16 v[26:29], v[142:145], v[168:171], v[26:29]
	v_mfma_f32_16x16x32_bf16 v[26:29], v[130:133], v[164:167], v[26:29]
	v_mfma_f32_16x16x32_bf16 v[18:21], v[130:133], v[182:185], v[18:21]
	v_mfma_f32_16x16x32_bf16 v[18:21], v[142:145], v[186:189], v[18:21]
	v_mfma_f32_16x16x32_bf16 v[22:25], v[126:129], v[186:189], v[22:25]
	v_mfma_f32_16x16x32_bf16 v[22:25], v[122:125], v[182:185], v[22:25]
	v_mfma_f32_16x16x32_bf16 v[14:17], v[122:125], v[190:193], v[14:17]
	v_mfma_f32_16x16x32_bf16 v[14:17], v[126:129], v[194:197], v[14:17]
	v_mfma_f32_16x16x32_bf16 v[10:13], v[142:145], v[194:197], v[10:13]
	v_mfma_f32_16x16x32_bf16 v[10:13], v[130:133], v[190:193], v[10:13]
	v_mfma_f32_16x16x32_bf16 v[2:5], v[130:133], v[198:201], v[2:5]
	v_mfma_f32_16x16x32_bf16 v[2:5], v[142:145], v[202:205], v[2:5]
	v_mfma_f32_16x16x32_bf16 v[6:9], v[126:129], v[202:205], v[6:9]
	v_mfma_f32_16x16x32_bf16 v[6:9], v[122:125], v[198:201], v[6:9]
	s_barrier
	s_setprio 0
	s_add_i32 s64, s64, 2
	s_addk_i32 s59, 0x100
	s_addk_i32 s63, 0x100
	s_cmp_gt_u32 s64, 29
	s_cbranch_scc0 .LBB0_1529
	s_and_b64 vcc, exec, s[52:53]
	s_cbranch_vccz .LBB0_1532
	s_barrier
	s_setprio 1

; #define PG8_STAGEX(rs, bufoff, soff, voff) do { _Pragma("unroll") for (int _i = 0; _i < 2; ++_i) \
;         __builtin_amdgcn_raw_ptr_buffer_load_lds(rs, (LAS unsigned*)(lds + (bufoff) + ldsw + _i * 8192), 16, (voff)[_i], (soff), 0, 0); } while (0)
; #define PG8_LDA(dst, b, h) do { _Pragma("unroll") for (int m = 0; m < 4; ++m) _Pragma("unroll") for (int k = 0; k < 2; ++k) dst[m][k] = *(const LAS bf16x8*)(lds + PG8_SA(b, h) + aoff + m * 2048 + k * 1024); } while (0)
; #define PG8_LDB(dst, b, h) do { _Pragma("unroll") for (int n = 0; n < 2; ++n) _Pragma("unroll") for (int k = 0; k < 2; ++k) dst[n][k] = *(const LAS bf16x8*)(lds + PG8_SB(b, h) + boff + n * 2048 + k * 1024); } while (0)
; #define PG8_WAIT_V(n) asm volatile("s_waitcnt vmcnt(" #n ")" ::: "memory")
; #define PG8_WAIT_L(n) asm volatile("s_waitcnt lgkmcnt(" #n ")" ::: "memory")
; #define PG8_BAR __builtin_amdgcn_s_barrier()
; #define PG8_SCHED __builtin_amdgcn_sched_barrier(0)
;     ...
;             const unsigned a1 = cA + (unsigned)(t + 1) * kstep;
;             const unsigned a2 = last ? nA : cA + (unsigned)(t + 2) * kstep, b2 = last ? nB : cB + (unsigned)(t + 2) * kstep;
;             const unsigned a3 = a2 + kstep, b3 = b2 + kstep;
;             PG8_LDB(B0, 0, 0); PG8_LDB(B1, 0, 1); PG8_SCHED; PG8_LDA(At, 0, 0); PG8_STAGEX(rsA, PG8_SA(1, 1), a1 + hstepA, voffA);
;             PG8_WAIT_V(8); PG8_WAIT_L(0); PG8_BAR; PG8_MMA(0, 0, At, B0); PG8_MMA(0, 1, At, B1); PG8_BAR; PG8_SCHED;
;             PG8_LDA(At, 0, 1); PG8_STAGEX(rsB, PG8_SB(0, 0), b2, voffB); PG8_STAGEX(rsB, PG8_SB(0, 1), b2 + hstepB, voffB); PG8_STAGEX(rsA, PG8_SA(0, 0), a2, voffA);
;             PG8_WAIT_V(8); PG8_WAIT_L(0); PG8_BAR; PG8_MMA(1, 0, At, B0); PG8_MMA(1, 1, At, B1); PG8_BAR; PG8_SCHED;
.LBB0_1651:
	v_add_u32_e32 v102, 0x10000, v172
	v_add_u32_e32 v146, 0x14000, v172
	ds_read_b128 v[82:85], v102
	ds_read_b128 v[86:89], v102 offset:1024
	ds_read_b128 v[98:101], v102 offset:2048
	ds_read_b128 v[102:105], v102 offset:3072
	ds_read_b128 v[150:153], v146
	ds_read_b128 v[154:157], v146 offset:1024
	ds_read_b128 v[182:185], v146 offset:2048
	ds_read_b128 v[186:189], v146 offset:3072
	s_add_i32 s42, s61, 0xfff80080
	s_cmp_eq_u32 s63, 28
	s_cselect_b32 s66, s30, s42
	s_cselect_b32 s65, s31, s62
	s_or_b32 s64, s66, 0x80
	s_mov_b32 m0, s29
	ds_read_b128 v[190:193], v173
	ds_read_b128 v[194:197], v173 offset:1024
	ds_read_b128 v[198:201], v173 offset:2048
	ds_read_b128 v[202:205], v173 offset:3072
	ds_read_b128 v[206:209], v173 offset:4096
	ds_read_b128 v[210:213], v173 offset:5120
	ds_read_b128 v[214:217], v173 offset:6144
	ds_read_b128 v[218:221], v173 offset:7168
	buffer_load_dwordx4 v159, s[76:79], s61 offen lds
	s_mov_b32 m0, s50
	s_nop 0
	buffer_load_dwordx4 v163, s[76:79], s61 offen lds
	s_waitcnt vmcnt(8)
	s_waitcnt lgkmcnt(0)
	s_setprio 1
	s_barrier
	v_mfma_f32_16x16x32_bf16 v[142:145], v[82:85], v[190:193], v[142:145]
	v_mfma_f32_16x16x32_bf16 v[142:145], v[86:89], v[194:197], v[142:145]
	v_mfma_f32_16x16x32_bf16 v[134:137], v[102:105], v[194:197], v[134:137]
	v_mfma_f32_16x16x32_bf16 v[134:137], v[98:101], v[190:193], v[134:137]
	v_mfma_f32_16x16x32_bf16 v[118:121], v[98:101], v[198:201], v[118:121]
	v_mfma_f32_16x16x32_bf16 v[118:121], v[102:105], v[202:205], v[118:121]
	v_mfma_f32_16x16x32_bf16 v[126:129], v[86:89], v[202:205], v[126:129]
	v_mfma_f32_16x16x32_bf16 v[126:129], v[82:85], v[198:201], v[126:129]
	v_mfma_f32_16x16x32_bf16 v[110:113], v[82:85], v[206:209], v[110:113]
	v_mfma_f32_16x16x32_bf16 v[110:113], v[86:89], v[210:213], v[110:113]
	v_mfma_f32_16x16x32_bf16 v[94:97], v[102:105], v[210:213], v[94:97]
	v_mfma_f32_16x16x32_bf16 v[94:97], v[98:101], v[206:209], v[94:97]
	v_mfma_f32_16x16x32_bf16 v[70:73], v[98:101], v[214:217], v[70:73]
	v_mfma_f32_16x16x32_bf16 v[70:73], v[102:105], v[218:221], v[70:73]
	v_mfma_f32_16x16x32_bf16 v[78:81], v[86:89], v[218:221], v[78:81]
	v_mfma_f32_16x16x32_bf16 v[78:81], v[82:85], v[214:217], v[78:81]
	v_mfma_f32_16x16x32_bf16 v[138:141], v[150:153], v[190:193], v[138:141]
	v_mfma_f32_16x16x32_bf16 v[138:141], v[154:157], v[194:197], v[138:141]
	v_mfma_f32_16x16x32_bf16 v[130:133], v[186:189], v[194:197], v[130:133]
	v_mfma_f32_16x16x32_bf16 v[130:133], v[182:185], v[190:193], v[130:133]
	v_mfma_f32_16x16x32_bf16 v[114:117], v[182:185], v[198:201], v[114:117]
	v_mfma_f32_16x16x32_bf16 v[114:117], v[186:189], v[202:205], v[114:117]
	v_mfma_f32_16x16x32_bf16 v[122:125], v[154:157], v[202:205], v[122:125]
	v_mfma_f32_16x16x32_bf16 v[122:125], v[150:153], v[198:201], v[122:125]
	v_mfma_f32_16x16x32_bf16 v[106:109], v[150:153], v[206:209], v[106:109]
	v_mfma_f32_16x16x32_bf16 v[106:109], v[154:157], v[210:213], v[106:109]
	v_mfma_f32_16x16x32_bf16 v[90:93], v[186:189], v[210:213], v[90:93]
	v_mfma_f32_16x16x32_bf16 v[90:93], v[182:185], v[206:209], v[90:93]
	v_mfma_f32_16x16x32_bf16 v[66:69], v[182:185], v[214:217], v[66:69]
	v_mfma_f32_16x16x32_bf16 v[66:69], v[186:189], v[218:221], v[66:69]
	v_mfma_f32_16x16x32_bf16 v[74:77], v[154:157], v[218:221], v[74:77]
	v_mfma_f32_16x16x32_bf16 v[74:77], v[150:153], v[214:217], v[74:77]
	s_barrier
	s_setprio 0
	s_mov_b32 m0, s16
	s_mov_b32 s42, s78
	s_mov_b32 s43, s79
	ds_read_b128 v[190:193], v173 offset:16384
	ds_read_b128 v[194:197], v173 offset:17408
	ds_read_b128 v[198:201], v173 offset:18432
	ds_read_b128 v[202:205], v173 offset:19456
	ds_read_b128 v[206:209], v173 offset:20480
	ds_read_b128 v[210:213], v173 offset:21504
	ds_read_b128 v[214:217], v173 offset:22528
	ds_read_b128 v[218:221], v173 offset:23552
	buffer_load_dwordx4 v161, s[40:43], s65 offen lds
	s_mov_b32 m0, s17
	s_add_i32 s67, s65, 0x80000
	buffer_load_dwordx4 v165, s[40:43], s65 offen lds
	s_mov_b32 m0, s18
	s_nop 0
	buffer_load_dwordx4 v161, s[40:43], s67 offen lds
	s_mov_b32 m0, s19
	s_nop 0
	buffer_load_dwordx4 v165, s[40:43], s67 offen lds
	s_mov_b32 m0, s15
	s_nop 0
	buffer_load_dwordx4 v159, s[76:79], s66 offen lds
	s_mov_b32 m0, s20
	s_nop 0
	buffer_load_dwordx4 v163, s[76:79], s66 offen lds
	s_waitcnt vmcnt(8)
	s_waitcnt lgkmcnt(0)
	s_setprio 1
	s_barrier
	v_mfma_f32_16x16x32_bf16 v[62:65], v[82:85], v[190:193], v[62:65]
	v_mfma_f32_16x16x32_bf16 v[62:65], v[86:89], v[194:197], v[62:65]
	v_mfma_f32_16x16x32_bf16 v[54:57], v[102:105], v[194:197], v[54:57]
	v_mfma_f32_16x16x32_bf16 v[54:57], v[98:101], v[190:193], v[54:57]
	v_mfma_f32_16x16x32_bf16 v[38:41], v[98:101], v[198:201], v[38:41]
	v_mfma_f32_16x16x32_bf16 v[38:41], v[102:105], v[202:205], v[38:41]
	v_mfma_f32_16x16x32_bf16 v[46:49], v[86:89], v[202:205], v[46:49]
	v_mfma_f32_16x16x32_bf16 v[46:49], v[82:85], v[198:201], v[46:49]
	v_mfma_f32_16x16x32_bf16 v[30:33], v[82:85], v[206:209], v[30:33]
	v_mfma_f32_16x16x32_bf16 v[30:33], v[86:89], v[210:213], v[30:33]
	v_mfma_f32_16x16x32_bf16 v[22:25], v[102:105], v[210:213], v[22:25]
	v_mfma_f32_16x16x32_bf16 v[22:25], v[98:101], v[206:209], v[22:25]
	v_mfma_f32_16x16x32_bf16 v[6:9], v[98:101], v[214:217], v[6:9]
	v_mfma_f32_16x16x32_bf16 v[6:9], v[102:105], v[218:221], v[6:9]
	v_mfma_f32_16x16x32_bf16 v[14:17], v[86:89], v[218:221], v[14:17]
	v_mfma_f32_16x16x32_bf16 v[14:17], v[82:85], v[214:217], v[14:17]
	v_mfma_f32_16x16x32_bf16 v[58:61], v[150:153], v[190:193], v[58:61]
	v_mfma_f32_16x16x32_bf16 v[58:61], v[154:157], v[194:197], v[58:61]
	v_mfma_f32_16x16x32_bf16 v[50:53], v[186:189], v[194:197], v[50:53]
	v_mfma_f32_16x16x32_bf16 v[50:53], v[182:185], v[190:193], v[50:53]
	v_mfma_f32_16x16x32_bf16 v[34:37], v[182:185], v[198:201], v[34:37]
	v_mfma_f32_16x16x32_bf16 v[34:37], v[186:189], v[202:205], v[34:37]
	v_mfma_f32_16x16x32_bf16 v[42:45], v[154:157], v[202:205], v[42:45]
	v_mfma_f32_16x16x32_bf16 v[42:45], v[150:153], v[198:201], v[42:45]
	v_mfma_f32_16x16x32_bf16 v[26:29], v[150:153], v[206:209], v[26:29]
	v_mfma_f32_16x16x32_bf16 v[26:29], v[154:157], v[210:213], v[26:29]
	v_mfma_f32_16x16x32_bf16 v[18:21], v[186:189], v[210:213], v[18:21]
	v_mfma_f32_16x16x32_bf16 v[18:21], v[182:185], v[206:209], v[18:21]
	v_mfma_f32_16x16x32_bf16 v[2:5], v[182:185], v[214:217], v[2:5]
	v_mfma_f32_16x16x32_bf16 v[2:5], v[186:189], v[218:221], v[2:5]
	v_mfma_f32_16x16x32_bf16 v[10:13], v[154:157], v[218:221], v[10:13]
	v_mfma_f32_16x16x32_bf16 v[10:13], v[150:153], v[214:217], v[10:13]
	s_barrier
; #define PG8_STAGEX(rs, bufoff, soff, voff) do { _Pragma("unroll") for (int _i = 0; _i < 2; ++_i) \
;         __builtin_amdgcn_raw_ptr_buffer_load_lds(rs, (LAS unsigned*)(lds + (bufoff) + ldsw + _i * 8192), 16, (voff)[_i], (soff), 0, 0); } while (0)
; #define PG8_WAIT_V(n) asm volatile("s_waitcnt vmcnt(" #n ")" ::: "memory")
; #define PG8_WAIT_L(n) asm volatile("s_waitcnt lgkmcnt(" #n ")" ::: "memory")
; #define PG8_BAR __builtin_amdgcn_s_barrier()
;     ...
;             PG8_LDB(B0, 1, 0); PG8_LDB(B1, 1, 1); PG8_SCHED; PG8_LDA(At, 1, 0); PG8_STAGEX(rsA, PG8_SA(0, 1), a2 + hstepA, voffA);
;             PG8_WAIT_V(8); PG8_WAIT_L(0); PG8_BAR; PG8_MMA(0, 0, At, B0); PG8_MMA(0, 1, At, B1); PG8_BAR; PG8_SCHED;
;             PG8_LDA(At, 1, 1); PG8_STAGEX(rsB, PG8_SB(1, 0), b3, voffB); PG8_STAGEX(rsB, PG8_SB(1, 1), b3 + hstepB, voffB); PG8_STAGEX(rsA, PG8_SA(1, 0), a3, voffA);
;             PG8_WAIT_V(8); PG8_WAIT_L(0); PG8_BAR; PG8_MMA(1, 0, At, B0); PG8_MMA(1, 1, At, B1); PG8_BAR; PG8_SCHED;
;         }
;         } else {
;             const bool w0 = (QV == 2) || (wr == 0);
; #pragma nounroll
;             for (int t = 0; t < nt; t += 2) {
;                 const bool last = (t == nt - 2);
;                 const unsigned a1 = cA + (unsigned)(t + 1) * kstep;
;                 const unsigned a2 = last ? nA : cA + (unsigned)(t + 2) * kstep, b2 = last ? nB : cB + (unsigned)(t + 2) * kstep;
;                 const unsigned a3 = a2 + kstep, b3 = b2 + kstep;
;                 if (w0) { PG8_LDB(B0, 0, 0); PG8_LDB(B1, 0, 1); PG8_SCHED; PG8_LDA(At, 0, 0); }
;                 PG8_WAIT_L(0); PG8_BAR; if (w0) { PG8_MMA(0, 0, At, B0); PG8_MMA(0, 1, At, B1); } PG8_BAR; PG8_SCHED;
;                 PG8_STAGEX(rsB, PG8_SB(0, 0), b2, voffB); PG8_STAGEX(rsB, PG8_SB(0, 1), b2 + hstepB, voffB); PG8_STAGEX(rsA, PG8_SA(0, 0), a2, voffA);
;                 PG8_WAIT_V(6); PG8_BAR; PG8_BAR; PG8_SCHED;
;                 if (w0) { PG8_LDB(B0, 1, 0); PG8_LDB(B1, 1, 1); PG8_SCHED; PG8_LDA(At, 1, 0); }
;                 PG8_WAIT_L(0); PG8_BAR; if (w0) { PG8_MMA(0, 0, At, B0); PG8_MMA(0, 1, At, B1); } PG8_BAR; PG8_SCHED;
;                 PG8_STAGEX(rsB, PG8_SB(1, 0), b3, voffB); PG8_STAGEX(rsB, PG8_SB(1, 1), b3 + hstepB, voffB); PG8_STAGEX(rsA, PG8_SA(1, 0), a3, voffA);
;                 PG8_WAIT_V(6); PG8_BAR; PG8_BAR; PG8_SCHED;
;             }
;         }
;         if (wr == 0) PG8_BAR;
	s_setprio 0
	v_add_u32_e32 v102, 0x18000, v172
	v_add_u32_e32 v146, 0x1c000, v172
	ds_read_b128 v[82:85], v102
	ds_read_b128 v[86:89], v102 offset:1024
	ds_read_b128 v[98:101], v102 offset:2048
	ds_read_b128 v[102:105], v102 offset:3072
	ds_read_b128 v[150:153], v146
	ds_read_b128 v[154:157], v146 offset:1024
	ds_read_b128 v[182:185], v146 offset:2048
	ds_read_b128 v[186:189], v146 offset:3072
	s_add_i32 s66, s66, 0x80000
	s_mov_b32 m0, s21
	ds_read_b128 v[190:193], v173 offset:32768
	ds_read_b128 v[194:197], v173 offset:33792
	ds_read_b128 v[198:201], v173 offset:34816
	ds_read_b128 v[202:205], v173 offset:35840
	ds_read_b128 v[206:209], v173 offset:36864
	ds_read_b128 v[210:213], v173 offset:37888
	ds_read_b128 v[214:217], v173 offset:38912
	ds_read_b128 v[218:221], v173 offset:39936
	buffer_load_dwordx4 v159, s[76:79], s66 offen lds
	s_mov_b32 m0, s22
	s_nop 0
	buffer_load_dwordx4 v163, s[76:79], s66 offen lds
	s_waitcnt vmcnt(8)
	s_waitcnt lgkmcnt(0)
	s_setprio 1
	s_barrier
	v_mfma_f32_16x16x32_bf16 v[142:145], v[82:85], v[190:193], v[142:145]
	v_mfma_f32_16x16x32_bf16 v[142:145], v[86:89], v[194:197], v[142:145]
	v_mfma_f32_16x16x32_bf16 v[134:137], v[102:105], v[194:197], v[134:137]
	v_mfma_f32_16x16x32_bf16 v[134:137], v[98:101], v[190:193], v[134:137]
	v_mfma_f32_16x16x32_bf16 v[118:121], v[98:101], v[198:201], v[118:121]
	v_mfma_f32_16x16x32_bf16 v[118:121], v[102:105], v[202:205], v[118:121]
	v_mfma_f32_16x16x32_bf16 v[126:129], v[86:89], v[202:205], v[126:129]
	v_mfma_f32_16x16x32_bf16 v[126:129], v[82:85], v[198:201], v[126:129]
	v_mfma_f32_16x16x32_bf16 v[110:113], v[82:85], v[206:209], v[110:113]
	v_mfma_f32_16x16x32_bf16 v[110:113], v[86:89], v[210:213], v[110:113]
	v_mfma_f32_16x16x32_bf16 v[94:97], v[102:105], v[210:213], v[94:97]
	v_mfma_f32_16x16x32_bf16 v[94:97], v[98:101], v[206:209], v[94:97]
	v_mfma_f32_16x16x32_bf16 v[70:73], v[98:101], v[214:217], v[70:73]
	v_mfma_f32_16x16x32_bf16 v[70:73], v[102:105], v[218:221], v[70:73]
	v_mfma_f32_16x16x32_bf16 v[78:81], v[86:89], v[218:221], v[78:81]
	v_mfma_f32_16x16x32_bf16 v[78:81], v[82:85], v[214:217], v[78:81]
	v_mfma_f32_16x16x32_bf16 v[138:141], v[150:153], v[190:193], v[138:141]
	v_mfma_f32_16x16x32_bf16 v[138:141], v[154:157], v[194:197], v[138:141]
	v_mfma_f32_16x16x32_bf16 v[130:133], v[186:189], v[194:197], v[130:133]
	v_mfma_f32_16x16x32_bf16 v[130:133], v[182:185], v[190:193], v[130:133]
	v_mfma_f32_16x16x32_bf16 v[114:117], v[182:185], v[198:201], v[114:117]
	v_mfma_f32_16x16x32_bf16 v[114:117], v[186:189], v[202:205], v[114:117]
	v_mfma_f32_16x16x32_bf16 v[122:125], v[154:157], v[202:205], v[122:125]
	v_mfma_f32_16x16x32_bf16 v[122:125], v[150:153], v[198:201], v[122:125]
	v_mfma_f32_16x16x32_bf16 v[106:109], v[150:153], v[206:209], v[106:109]
	v_mfma_f32_16x16x32_bf16 v[106:109], v[154:157], v[210:213], v[106:109]
	v_mfma_f32_16x16x32_bf16 v[90:93], v[186:189], v[210:213], v[90:93]
	v_mfma_f32_16x16x32_bf16 v[90:93], v[182:185], v[206:209], v[90:93]
	v_mfma_f32_16x16x32_bf16 v[66:69], v[182:185], v[214:217], v[66:69]
	v_mfma_f32_16x16x32_bf16 v[66:69], v[186:189], v[218:221], v[66:69]
	v_mfma_f32_16x16x32_bf16 v[74:77], v[154:157], v[218:221], v[74:77]
	v_mfma_f32_16x16x32_bf16 v[74:77], v[150:153], v[214:217], v[74:77]
	s_barrier
	s_setprio 0
	s_mov_b32 m0, s23
	s_or_b32 s66, s65, 0x80
	ds_read_b128 v[190:193], v173 offset:49152
	ds_read_b128 v[194:197], v173 offset:50176
	ds_read_b128 v[198:201], v173 offset:51200
	ds_read_b128 v[202:205], v173 offset:52224
	ds_read_b128 v[206:209], v173 offset:53248
	ds_read_b128 v[210:213], v173 offset:54272
	ds_read_b128 v[214:217], v173 offset:55296
	ds_read_b128 v[218:221], v173 offset:56320
	buffer_load_dwordx4 v161, s[40:43], s66 offen lds
	s_mov_b32 m0, s24
	s_add_i32 s65, s65, 0x80080
	buffer_load_dwordx4 v165, s[40:43], s66 offen lds
	s_mov_b32 m0, s27
	s_nop 0
	buffer_load_dwordx4 v161, s[40:43], s65 offen lds
	s_mov_b32 m0, s28
	s_nop 0
	buffer_load_dwordx4 v165, s[40:43], s65 offen lds
	s_mov_b32 m0, s25
	s_nop 0
	buffer_load_dwordx4 v159, s[76:79], s64 offen lds
	s_mov_b32 m0, s26
	s_nop 0
	buffer_load_dwordx4 v163, s[76:79], s64 offen lds
	s_waitcnt vmcnt(8)
	s_waitcnt lgkmcnt(0)
	s_setprio 1
	s_barrier
	v_mfma_f32_16x16x32_bf16 v[62:65], v[82:85], v[190:193], v[62:65]
	v_mfma_f32_16x16x32_bf16 v[62:65], v[86:89], v[194:197], v[62:65]
	v_mfma_f32_16x16x32_bf16 v[54:57], v[102:105], v[194:197], v[54:57]
	v_mfma_f32_16x16x32_bf16 v[54:57], v[98:101], v[190:193], v[54:57]
	v_mfma_f32_16x16x32_bf16 v[38:41], v[98:101], v[198:201], v[38:41]
	v_mfma_f32_16x16x32_bf16 v[38:41], v[102:105], v[202:205], v[38:41]
	v_mfma_f32_16x16x32_bf16 v[46:49], v[86:89], v[202:205], v[46:49]
	v_mfma_f32_16x16x32_bf16 v[46:49], v[82:85], v[198:201], v[46:49]
	v_mfma_f32_16x16x32_bf16 v[30:33], v[82:85], v[206:209], v[30:33]
	v_mfma_f32_16x16x32_bf16 v[30:33], v[86:89], v[210:213], v[30:33]
	v_mfma_f32_16x16x32_bf16 v[22:25], v[102:105], v[210:213], v[22:25]
	v_mfma_f32_16x16x32_bf16 v[22:25], v[98:101], v[206:209], v[22:25]
	v_mfma_f32_16x16x32_bf16 v[6:9], v[98:101], v[214:217], v[6:9]
	v_mfma_f32_16x16x32_bf16 v[6:9], v[102:105], v[218:221], v[6:9]
	v_mfma_f32_16x16x32_bf16 v[14:17], v[86:89], v[218:221], v[14:17]
	v_mfma_f32_16x16x32_bf16 v[14:17], v[82:85], v[214:217], v[14:17]
	v_mfma_f32_16x16x32_bf16 v[58:61], v[150:153], v[190:193], v[58:61]
	v_mfma_f32_16x16x32_bf16 v[58:61], v[154:157], v[194:197], v[58:61]
	v_mfma_f32_16x16x32_bf16 v[50:53], v[186:189], v[194:197], v[50:53]
	v_mfma_f32_16x16x32_bf16 v[50:53], v[182:185], v[190:193], v[50:53]
	v_mfma_f32_16x16x32_bf16 v[34:37], v[182:185], v[198:201], v[34:37]
	v_mfma_f32_16x16x32_bf16 v[34:37], v[186:189], v[202:205], v[34:37]
	v_mfma_f32_16x16x32_bf16 v[42:45], v[154:157], v[202:205], v[42:45]
	v_mfma_f32_16x16x32_bf16 v[42:45], v[150:153], v[198:201], v[42:45]
	v_mfma_f32_16x16x32_bf16 v[26:29], v[150:153], v[206:209], v[26:29]
	v_mfma_f32_16x16x32_bf16 v[26:29], v[154:157], v[210:213], v[26:29]
	v_mfma_f32_16x16x32_bf16 v[18:21], v[186:189], v[210:213], v[18:21]
	v_mfma_f32_16x16x32_bf16 v[18:21], v[182:185], v[206:209], v[18:21]
	v_mfma_f32_16x16x32_bf16 v[2:5], v[182:185], v[214:217], v[2:5]
	v_mfma_f32_16x16x32_bf16 v[2:5], v[186:189], v[218:221], v[2:5]
	v_mfma_f32_16x16x32_bf16 v[10:13], v[154:157], v[218:221], v[10:13]
	v_mfma_f32_16x16x32_bf16 v[10:13], v[150:153], v[214:217], v[10:13]
	s_barrier
	s_setprio 0
	s_add_i32 s63, s63, 2
	s_addk_i32 s61, 0x100
	s_addk_i32 s62, 0x100
	s_cmp_gt_u32 s63, 29
	s_cbranch_scc0 .LBB0_1651
	s_and_b64 vcc, exec, s[48:49]
	s_cbranch_vccz .LBB0_1654
	s_barrier
	s_setprio 1

; #define PG8_STAGEX(rs, bufoff, soff, voff) do { _Pragma("unroll") for (int _i = 0; _i < 2; ++_i) \
;         __builtin_amdgcn_raw_ptr_buffer_load_lds(rs, (LAS unsigned*)(lds + (bufoff) + ldsw + _i * 8192), 16, (voff)[_i], (soff), 0, 0); } while (0)
; #define PG8_LDA(dst, b, h) do { _Pragma("unroll") for (int m = 0; m < 4; ++m) _Pragma("unroll") for (int k = 0; k < 2; ++k) dst[m][k] = *(const LAS bf16x8*)(lds + PG8_SA(b, h) + aoff + m * 2048 + k * 1024); } while (0)
; #define PG8_LDB(dst, b, h) do { _Pragma("unroll") for (int n = 0; n < 2; ++n) _Pragma("unroll") for (int k = 0; k < 2; ++k) dst[n][k] = *(const LAS bf16x8*)(lds + PG8_SB(b, h) + boff + n * 2048 + k * 1024); } while (0)
; #define PG8_WAIT_V(n) asm volatile("s_waitcnt vmcnt(" #n ")" ::: "memory")
; #define PG8_WAIT_L(n) asm volatile("s_waitcnt lgkmcnt(" #n ")" ::: "memory")
; #define PG8_BAR __builtin_amdgcn_s_barrier()
; #define PG8_SCHED __builtin_amdgcn_sched_barrier(0)
;     ...
;             const unsigned a1 = cA + (unsigned)(t + 1) * kstep;
;             const unsigned a2 = last ? nA : cA + (unsigned)(t + 2) * kstep, b2 = last ? nB : cB + (unsigned)(t + 2) * kstep;
;             const unsigned a3 = a2 + kstep, b3 = b2 + kstep;
;             PG8_LDB(B0, 0, 0); PG8_LDB(B1, 0, 1); PG8_SCHED; PG8_LDA(At, 0, 0); PG8_STAGEX(rsA, PG8_SA(1, 1), a1 + hstepA, voffA);
;             PG8_WAIT_V(8); PG8_WAIT_L(0); PG8_BAR; PG8_MMA(0, 0, At, B0); PG8_MMA(0, 1, At, B1); PG8_BAR; PG8_SCHED;
;             PG8_LDA(At, 0, 1); PG8_STAGEX(rsB, PG8_SB(0, 0), b2, voffB); PG8_STAGEX(rsB, PG8_SB(0, 1), b2 + hstepB, voffB); PG8_STAGEX(rsA, PG8_SA(0, 0), a2, voffA);
;             PG8_WAIT_V(8); PG8_WAIT_L(0); PG8_BAR; PG8_MMA(1, 0, At, B0); PG8_MMA(1, 1, At, B1); PG8_BAR; PG8_SCHED;
.LBB0_1750:
	v_add_u32_e32 v70, 0x10000, v241
	ds_read_b128 v[134:137], v70
	ds_read_b128 v[138:141], v70 offset:1024
	ds_read_b128 v[142:145], v70 offset:2048
	ds_read_b128 v[146:149], v70 offset:3072
	v_add_u32_e32 v70, 0x14000, v241
	ds_read_b128 v[150:153], v70
	ds_read_b128 v[154:157], v70 offset:1024
	ds_read_b128 v[158:161], v70 offset:2048
	ds_read_b128 v[162:165], v70 offset:3072
	s_add_i32 s46, s40, 0xffea8080
	s_cmpk_eq_i32 s60, 0x52
	s_cselect_b32 s63, s30, s46
	s_cselect_b32 s62, s31, s41
	s_or_b32 s61, s63, 0x80
	s_mov_b32 m0, s72
	ds_read_b128 v[166:169], v242
	ds_read_b128 v[170:173], v242 offset:1024
	ds_read_b128 v[184:187], v242 offset:2048
	ds_read_b128 v[188:191], v242 offset:3072
	ds_read_b128 v[192:195], v242 offset:4096
	ds_read_b128 v[196:199], v242 offset:5120
	ds_read_b128 v[200:203], v242 offset:6144
	ds_read_b128 v[204:207], v242 offset:7168
	buffer_load_dwordx4 v178, s[76:79], s40 offen lds
	s_mov_b32 m0, s73
	s_nop 0
	buffer_load_dwordx4 v237, s[76:79], s40 offen lds
	s_waitcnt vmcnt(8)
	s_waitcnt lgkmcnt(0)
	s_setprio 1
	s_barrier
	v_mfma_f32_16x16x32_bf16 v[130:133], v[134:137], v[166:169], v[130:133]
	v_mfma_f32_16x16x32_bf16 v[130:133], v[138:141], v[170:173], v[130:133]
	v_mfma_f32_16x16x32_bf16 v[126:129], v[146:149], v[170:173], v[126:129]
	v_mfma_f32_16x16x32_bf16 v[126:129], v[142:145], v[166:169], v[126:129]
	v_mfma_f32_16x16x32_bf16 v[118:121], v[142:145], v[184:187], v[118:121]
	v_mfma_f32_16x16x32_bf16 v[118:121], v[146:149], v[188:191], v[118:121]
	v_mfma_f32_16x16x32_bf16 v[122:125], v[138:141], v[188:191], v[122:125]
	v_mfma_f32_16x16x32_bf16 v[122:125], v[134:137], v[184:187], v[122:125]
	v_mfma_f32_16x16x32_bf16 v[114:117], v[134:137], v[192:195], v[114:117]
	v_mfma_f32_16x16x32_bf16 v[114:117], v[138:141], v[196:199], v[114:117]
	v_mfma_f32_16x16x32_bf16 v[110:113], v[146:149], v[196:199], v[110:113]
	v_mfma_f32_16x16x32_bf16 v[110:113], v[142:145], v[192:195], v[110:113]
	v_mfma_f32_16x16x32_bf16 v[102:105], v[142:145], v[200:203], v[102:105]
	v_mfma_f32_16x16x32_bf16 v[102:105], v[146:149], v[204:207], v[102:105]
	v_mfma_f32_16x16x32_bf16 v[106:109], v[138:141], v[204:207], v[106:109]
	v_mfma_f32_16x16x32_bf16 v[106:109], v[134:137], v[200:203], v[106:109]
	v_mfma_f32_16x16x32_bf16 v[62:65], v[150:153], v[166:169], v[62:65]
	v_mfma_f32_16x16x32_bf16 v[62:65], v[154:157], v[170:173], v[62:65]
	v_mfma_f32_16x16x32_bf16 v[58:61], v[162:165], v[170:173], v[58:61]
	v_mfma_f32_16x16x32_bf16 v[58:61], v[158:161], v[166:169], v[58:61]
	v_mfma_f32_16x16x32_bf16 v[50:53], v[158:161], v[184:187], v[50:53]
	v_mfma_f32_16x16x32_bf16 v[50:53], v[162:165], v[188:191], v[50:53]
	v_mfma_f32_16x16x32_bf16 v[54:57], v[154:157], v[188:191], v[54:57]
	v_mfma_f32_16x16x32_bf16 v[54:57], v[150:153], v[184:187], v[54:57]
	v_mfma_f32_16x16x32_bf16 v[46:49], v[150:153], v[192:195], v[46:49]
	v_mfma_f32_16x16x32_bf16 v[46:49], v[154:157], v[196:199], v[46:49]
	v_mfma_f32_16x16x32_bf16 v[42:45], v[162:165], v[196:199], v[42:45]
	v_mfma_f32_16x16x32_bf16 v[42:45], v[158:161], v[192:195], v[42:45]
	v_mfma_f32_16x16x32_bf16 v[34:37], v[158:161], v[200:203], v[34:37]
	v_mfma_f32_16x16x32_bf16 v[34:37], v[162:165], v[204:207], v[34:37]
	v_mfma_f32_16x16x32_bf16 v[38:41], v[154:157], v[204:207], v[38:41]
	v_mfma_f32_16x16x32_bf16 v[38:41], v[150:153], v[200:203], v[38:41]
	s_barrier
	s_setprio 0
	s_mov_b32 m0, s17
	s_mov_b32 s46, s78
	s_mov_b32 s47, s79
	ds_read_b128 v[166:169], v242 offset:16384
	ds_read_b128 v[170:173], v242 offset:17408
	ds_read_b128 v[184:187], v242 offset:18432
	ds_read_b128 v[188:191], v242 offset:19456
	ds_read_b128 v[192:195], v242 offset:20480
	ds_read_b128 v[196:199], v242 offset:21504
	ds_read_b128 v[200:203], v242 offset:22528
	ds_read_b128 v[204:207], v242 offset:23552
	buffer_load_dwordx4 v179, s[44:47], s62 offen lds
	s_mov_b32 m0, s18
	s_add_i32 s64, s62, 0x158000
	buffer_load_dwordx4 v238, s[44:47], s62 offen lds
	s_mov_b32 m0, s19
	s_nop 0
	buffer_load_dwordx4 v179, s[44:47], s64 offen lds
	s_mov_b32 m0, s20
	s_nop 0
	buffer_load_dwordx4 v238, s[44:47], s64 offen lds
	s_mov_b32 m0, s16
	s_nop 0
	buffer_load_dwordx4 v178, s[76:79], s63 offen lds
	s_mov_b32 m0, s21
	s_nop 0
	buffer_load_dwordx4 v237, s[76:79], s63 offen lds
	s_waitcnt vmcnt(8)
	s_waitcnt lgkmcnt(0)
	s_setprio 1
	s_barrier
	v_mfma_f32_16x16x32_bf16 v[98:101], v[134:137], v[166:169], v[98:101]
	v_mfma_f32_16x16x32_bf16 v[94:97], v[142:145], v[166:169], v[94:97]
	v_mfma_f32_16x16x32_bf16 v[90:93], v[134:137], v[184:187], v[90:93]
	v_mfma_f32_16x16x32_bf16 v[86:89], v[142:145], v[184:187], v[86:89]
	v_mfma_f32_16x16x32_bf16 v[82:85], v[134:137], v[192:195], v[82:85]
	v_mfma_f32_16x16x32_bf16 v[76:79], v[142:145], v[192:195], v[78:81]
	v_mfma_f32_16x16x32_bf16 v[70:73], v[134:137], v[200:203], v[72:75]
	v_mfma_f32_16x16x32_bf16 v[66:69], v[142:145], v[200:203], v[66:69]
	v_mfma_f32_16x16x32_bf16 v[98:101], v[138:141], v[170:173], v[98:101]
	v_mfma_f32_16x16x32_bf16 v[94:97], v[146:149], v[170:173], v[94:97]
	v_mfma_f32_16x16x32_bf16 v[90:93], v[138:141], v[188:191], v[90:93]
	v_mfma_f32_16x16x32_bf16 v[86:89], v[146:149], v[188:191], v[86:89]
	v_mfma_f32_16x16x32_bf16 v[82:85], v[138:141], v[196:199], v[82:85]
	v_mfma_f32_16x16x32_bf16 v[76:79], v[146:149], v[196:199], v[76:79]
	v_mfma_f32_16x16x32_bf16 v[70:73], v[138:141], v[204:207], v[70:73]
	v_mfma_f32_16x16x32_bf16 v[66:69], v[146:149], v[204:207], v[66:69]
	v_mfma_f32_16x16x32_bf16 v[30:33], v[150:153], v[166:169], v[30:33]
	v_mfma_f32_16x16x32_bf16 v[26:29], v[158:161], v[166:169], v[26:29]
	v_mfma_f32_16x16x32_bf16 v[22:25], v[150:153], v[184:187], v[22:25]
	v_mfma_f32_16x16x32_bf16 v[18:21], v[158:161], v[184:187], v[18:21]
	v_mfma_f32_16x16x32_bf16 v[14:17], v[150:153], v[192:195], v[14:17]
	v_mfma_f32_16x16x32_bf16 v[10:13], v[158:161], v[192:195], v[10:13]
	v_mfma_f32_16x16x32_bf16 v[6:9], v[150:153], v[200:203], v[6:9]
	v_mfma_f32_16x16x32_bf16 v[2:5], v[158:161], v[200:203], v[2:5]
	v_mfma_f32_16x16x32_bf16 v[30:33], v[154:157], v[170:173], v[30:33]
	v_mfma_f32_16x16x32_bf16 v[26:29], v[162:165], v[170:173], v[26:29]
	v_mfma_f32_16x16x32_bf16 v[22:25], v[154:157], v[188:191], v[22:25]
	v_mfma_f32_16x16x32_bf16 v[18:21], v[162:165], v[188:191], v[18:21]
	v_mfma_f32_16x16x32_bf16 v[14:17], v[154:157], v[196:199], v[14:17]
	v_mfma_f32_16x16x32_bf16 v[10:13], v[162:165], v[196:199], v[10:13]
	v_mfma_f32_16x16x32_bf16 v[6:9], v[154:157], v[204:207], v[6:9]
	v_mfma_f32_16x16x32_bf16 v[2:5], v[162:165], v[204:207], v[2:5]
	s_barrier
; #define PG8_STAGEX(rs, bufoff, soff, voff) do { _Pragma("unroll") for (int _i = 0; _i < 2; ++_i) \
;         __builtin_amdgcn_raw_ptr_buffer_load_lds(rs, (LAS unsigned*)(lds + (bufoff) + ldsw + _i * 8192), 16, (voff)[_i], (soff), 0, 0); } while (0)
; #define PG8_WAIT_V(n) asm volatile("s_waitcnt vmcnt(" #n ")" ::: "memory")
; #define PG8_WAIT_L(n) asm volatile("s_waitcnt lgkmcnt(" #n ")" ::: "memory")
; #define PG8_BAR __builtin_amdgcn_s_barrier()
;     ...
;             PG8_LDB(B0, 1, 0); PG8_LDB(B1, 1, 1); PG8_SCHED; PG8_LDA(At, 1, 0); PG8_STAGEX(rsA, PG8_SA(0, 1), a2 + hstepA, voffA);
;             PG8_WAIT_V(8); PG8_WAIT_L(0); PG8_BAR; PG8_MMA(0, 0, At, B0); PG8_MMA(0, 1, At, B1); PG8_BAR; PG8_SCHED;
;             PG8_LDA(At, 1, 1); PG8_STAGEX(rsB, PG8_SB(1, 0), b3, voffB); PG8_STAGEX(rsB, PG8_SB(1, 1), b3 + hstepB, voffB); PG8_STAGEX(rsA, PG8_SA(1, 0), a3, voffA);
;             PG8_WAIT_V(8); PG8_WAIT_L(0); PG8_BAR; PG8_MMA(1, 0, At, B0); PG8_MMA(1, 1, At, B1); PG8_BAR; PG8_SCHED;
;         }
;         } else {
;             const bool w0 = (QV == 2) || (wr == 0);
; #pragma nounroll
;             for (int t = 0; t < nt; t += 2) {
;                 const bool last = (t == nt - 2);
;                 const unsigned a1 = cA + (unsigned)(t + 1) * kstep;
;                 const unsigned a2 = last ? nA : cA + (unsigned)(t + 2) * kstep, b2 = last ? nB : cB + (unsigned)(t + 2) * kstep;
;                 const unsigned a3 = a2 + kstep, b3 = b2 + kstep;
;                 if (w0) { PG8_LDB(B0, 0, 0); PG8_LDB(B1, 0, 1); PG8_SCHED; PG8_LDA(At, 0, 0); }
;                 PG8_WAIT_L(0); PG8_BAR; if (w0) { PG8_MMA(0, 0, At, B0); PG8_MMA(0, 1, At, B1); } PG8_BAR; PG8_SCHED;
;                 PG8_STAGEX(rsB, PG8_SB(0, 0), b2, voffB); PG8_STAGEX(rsB, PG8_SB(0, 1), b2 + hstepB, voffB); PG8_STAGEX(rsA, PG8_SA(0, 0), a2, voffA);
;                 PG8_WAIT_V(6); PG8_BAR; PG8_BAR; PG8_SCHED;
;                 if (w0) { PG8_LDB(B0, 1, 0); PG8_LDB(B1, 1, 1); PG8_SCHED; PG8_LDA(At, 1, 0); }
;                 PG8_WAIT_L(0); PG8_BAR; if (w0) { PG8_MMA(0, 0, At, B0); PG8_MMA(0, 1, At, B1); } PG8_BAR; PG8_SCHED;
;                 PG8_STAGEX(rsB, PG8_SB(1, 0), b3, voffB); PG8_STAGEX(rsB, PG8_SB(1, 1), b3 + hstepB, voffB); PG8_STAGEX(rsA, PG8_SA(1, 0), a3, voffA);
;                 PG8_WAIT_V(6); PG8_BAR; PG8_BAR; PG8_SCHED;
;             }
;         }
;         if (wr == 0) PG8_BAR;
	s_setprio 0
	v_add_u32_e32 v74, 0x18000, v241
	ds_read_b128 v[134:137], v74
	ds_read_b128 v[138:141], v74 offset:1024
	ds_read_b128 v[142:145], v74 offset:2048
	ds_read_b128 v[146:149], v74 offset:3072
	v_add_u32_e32 v74, 0x1c000, v241
	ds_read_b128 v[150:153], v74
	ds_read_b128 v[154:157], v74 offset:1024
	ds_read_b128 v[158:161], v74 offset:2048
	ds_read_b128 v[162:165], v74 offset:3072
	s_add_i32 s63, s63, 0x158000
	s_mov_b32 m0, s22
	ds_read_b128 v[166:169], v242 offset:32768
	ds_read_b128 v[170:173], v242 offset:33792
	ds_read_b128 v[184:187], v242 offset:34816
	ds_read_b128 v[188:191], v242 offset:35840
	ds_read_b128 v[192:195], v242 offset:36864
	ds_read_b128 v[196:199], v242 offset:37888
	ds_read_b128 v[200:203], v242 offset:38912
	ds_read_b128 v[204:207], v242 offset:39936
	buffer_load_dwordx4 v178, s[76:79], s63 offen lds
	s_mov_b32 m0, s23
	s_nop 0
	buffer_load_dwordx4 v237, s[76:79], s63 offen lds
	s_waitcnt vmcnt(8)
	s_waitcnt lgkmcnt(0)
	s_setprio 1
	s_barrier
	v_mfma_f32_16x16x32_bf16 v[130:133], v[134:137], v[166:169], v[130:133]
	v_mfma_f32_16x16x32_bf16 v[130:133], v[138:141], v[170:173], v[130:133]
	v_mfma_f32_16x16x32_bf16 v[126:129], v[146:149], v[170:173], v[126:129]
	v_mfma_f32_16x16x32_bf16 v[126:129], v[142:145], v[166:169], v[126:129]
	v_mfma_f32_16x16x32_bf16 v[118:121], v[142:145], v[184:187], v[118:121]
	v_mfma_f32_16x16x32_bf16 v[118:121], v[146:149], v[188:191], v[118:121]
	v_mfma_f32_16x16x32_bf16 v[122:125], v[138:141], v[188:191], v[122:125]
	v_mfma_f32_16x16x32_bf16 v[122:125], v[134:137], v[184:187], v[122:125]
	v_mfma_f32_16x16x32_bf16 v[114:117], v[134:137], v[192:195], v[114:117]
	v_mfma_f32_16x16x32_bf16 v[114:117], v[138:141], v[196:199], v[114:117]
	v_mfma_f32_16x16x32_bf16 v[110:113], v[146:149], v[196:199], v[110:113]
	v_mfma_f32_16x16x32_bf16 v[110:113], v[142:145], v[192:195], v[110:113]
	v_mfma_f32_16x16x32_bf16 v[102:105], v[142:145], v[200:203], v[102:105]
	v_mfma_f32_16x16x32_bf16 v[102:105], v[146:149], v[204:207], v[102:105]
	v_mfma_f32_16x16x32_bf16 v[106:109], v[138:141], v[204:207], v[106:109]
	v_mfma_f32_16x16x32_bf16 v[106:109], v[134:137], v[200:203], v[106:109]
	v_mfma_f32_16x16x32_bf16 v[62:65], v[150:153], v[166:169], v[62:65]
	v_mfma_f32_16x16x32_bf16 v[62:65], v[154:157], v[170:173], v[62:65]
	v_mfma_f32_16x16x32_bf16 v[58:61], v[162:165], v[170:173], v[58:61]
	v_mfma_f32_16x16x32_bf16 v[58:61], v[158:161], v[166:169], v[58:61]
	v_mfma_f32_16x16x32_bf16 v[50:53], v[158:161], v[184:187], v[50:53]
	v_mfma_f32_16x16x32_bf16 v[50:53], v[162:165], v[188:191], v[50:53]
	v_mfma_f32_16x16x32_bf16 v[54:57], v[154:157], v[188:191], v[54:57]
	v_mfma_f32_16x16x32_bf16 v[54:57], v[150:153], v[184:187], v[54:57]
	v_mfma_f32_16x16x32_bf16 v[46:49], v[150:153], v[192:195], v[46:49]
	v_mfma_f32_16x16x32_bf16 v[46:49], v[154:157], v[196:199], v[46:49]
	v_mfma_f32_16x16x32_bf16 v[42:45], v[162:165], v[196:199], v[42:45]
	v_mfma_f32_16x16x32_bf16 v[42:45], v[158:161], v[192:195], v[42:45]
	v_mfma_f32_16x16x32_bf16 v[34:37], v[158:161], v[200:203], v[34:37]
	v_mfma_f32_16x16x32_bf16 v[34:37], v[162:165], v[204:207], v[34:37]
	v_mfma_f32_16x16x32_bf16 v[38:41], v[154:157], v[204:207], v[38:41]
	v_mfma_f32_16x16x32_bf16 v[38:41], v[150:153], v[200:203], v[38:41]
	s_barrier
	s_setprio 0
	s_mov_b32 m0, s54
	s_or_b32 s63, s62, 0x80
	ds_read_b128 v[166:169], v242 offset:49152
	ds_read_b128 v[170:173], v242 offset:50176
	ds_read_b128 v[184:187], v242 offset:51200
	ds_read_b128 v[188:191], v242 offset:52224
	ds_read_b128 v[192:195], v242 offset:53248
	ds_read_b128 v[196:199], v242 offset:54272
	ds_read_b128 v[200:203], v242 offset:55296
	ds_read_b128 v[204:207], v242 offset:56320
	buffer_load_dwordx4 v179, s[44:47], s63 offen lds
	s_mov_b32 m0, s55
	s_add_i32 s62, s62, 0x158080
	buffer_load_dwordx4 v238, s[44:47], s63 offen lds
	s_mov_b32 m0, s70
	s_nop 0
	buffer_load_dwordx4 v179, s[44:47], s62 offen lds
	s_mov_b32 m0, s71
	s_nop 0
	buffer_load_dwordx4 v238, s[44:47], s62 offen lds
	s_mov_b32 m0, s68
	s_nop 0
	buffer_load_dwordx4 v178, s[76:79], s61 offen lds
	s_mov_b32 m0, s69
	s_nop 0
	buffer_load_dwordx4 v237, s[76:79], s61 offen lds
	s_waitcnt vmcnt(8)
	s_waitcnt lgkmcnt(0)
	s_setprio 1
	s_barrier
	v_mfma_f32_16x16x32_bf16 v[98:101], v[134:137], v[166:169], v[98:101]
	v_mfma_f32_16x16x32_bf16 v[94:97], v[142:145], v[166:169], v[94:97]
	v_mfma_f32_16x16x32_bf16 v[90:93], v[134:137], v[184:187], v[90:93]
	v_mfma_f32_16x16x32_bf16 v[86:89], v[142:145], v[184:187], v[86:89]
	v_mfma_f32_16x16x32_bf16 v[80:83], v[134:137], v[192:195], v[82:85]
	v_mfma_f32_16x16x32_bf16 v[74:77], v[142:145], v[192:195], v[76:79]
	v_mfma_f32_16x16x32_bf16 v[70:73], v[134:137], v[200:203], v[70:73]
	v_mfma_f32_16x16x32_bf16 v[66:69], v[142:145], v[200:203], v[66:69]
	v_mfma_f32_16x16x32_bf16 v[98:101], v[138:141], v[170:173], v[98:101]
	v_mfma_f32_16x16x32_bf16 v[94:97], v[146:149], v[170:173], v[94:97]
	v_mfma_f32_16x16x32_bf16 v[90:93], v[138:141], v[188:191], v[90:93]
	v_mfma_f32_16x16x32_bf16 v[86:89], v[146:149], v[188:191], v[86:89]
	v_mfma_f32_16x16x32_bf16 v[82:85], v[138:141], v[196:199], v[80:83]
	v_mfma_f32_16x16x32_bf16 v[78:81], v[146:149], v[196:199], v[74:77]
	v_mfma_f32_16x16x32_bf16 v[72:75], v[138:141], v[204:207], v[70:73]
	v_mfma_f32_16x16x32_bf16 v[66:69], v[146:149], v[204:207], v[66:69]
	v_mfma_f32_16x16x32_bf16 v[30:33], v[150:153], v[166:169], v[30:33]
	v_mfma_f32_16x16x32_bf16 v[26:29], v[158:161], v[166:169], v[26:29]
	v_mfma_f32_16x16x32_bf16 v[22:25], v[150:153], v[184:187], v[22:25]
	v_mfma_f32_16x16x32_bf16 v[18:21], v[158:161], v[184:187], v[18:21]
	v_mfma_f32_16x16x32_bf16 v[14:17], v[150:153], v[192:195], v[14:17]
	v_mfma_f32_16x16x32_bf16 v[10:13], v[158:161], v[192:195], v[10:13]
	v_mfma_f32_16x16x32_bf16 v[6:9], v[150:153], v[200:203], v[6:9]
	v_mfma_f32_16x16x32_bf16 v[2:5], v[158:161], v[200:203], v[2:5]
	v_mfma_f32_16x16x32_bf16 v[30:33], v[154:157], v[170:173], v[30:33]
	v_mfma_f32_16x16x32_bf16 v[26:29], v[162:165], v[170:173], v[26:29]
	v_mfma_f32_16x16x32_bf16 v[22:25], v[154:157], v[188:191], v[22:25]
	v_mfma_f32_16x16x32_bf16 v[18:21], v[162:165], v[188:191], v[18:21]
	v_mfma_f32_16x16x32_bf16 v[14:17], v[154:157], v[196:199], v[14:17]
	v_mfma_f32_16x16x32_bf16 v[10:13], v[162:165], v[196:199], v[10:13]
	v_mfma_f32_16x16x32_bf16 v[6:9], v[154:157], v[204:207], v[6:9]
	v_mfma_f32_16x16x32_bf16 v[2:5], v[162:165], v[204:207], v[2:5]
	s_barrier
	s_setprio 0
	s_add_i32 s60, s60, 2
	s_addk_i32 s40, 0x100
	s_addk_i32 s41, 0x100
	s_cmpk_gt_u32 s60, 0x53
	s_cbranch_scc0 .LBB0_1750
	s_and_b64 vcc, exec, s[50:51]
	s_cbranch_vccz .LBB0_1753
	s_barrier
	s_setprio 1

; #define PG8_WAIT_V(n) asm volatile("s_waitcnt vmcnt(" #n ")" ::: "memory")
; #define PG8_BAR __builtin_amdgcn_s_barrier()
;     ...
;     PG8_WAIT_V(0);
;     PG8_BAR;
; __device__ __forceinline__ void xcd_barrier(const XcdBarrier& b) {
;     asm volatile("s_waitcnt vmcnt(0)" ::: "memory");
;     __syncthreads();
;     if (threadIdx.x == 0) {
.LBB0_1807:
	s_waitcnt vmcnt(0)
	s_waitcnt vmcnt(0) lgkmcnt(0)
	s_setprio 0
	s_barrier
	s_and_saveexec_b64 s[30:31], s[94:95]
	s_cbranch_execnz .LBB0_1808
	s_getpc_b64 s[98:99]
